# k39: k36 with the per-phase s_setprio flips removed from every GEMM K-loop and one static s_setprio 1 for waves 0-3 at kernel entry
# speedup vs baseline: 1.0392x; 1.0054x over previous
; #define LAS __attribute__((address_space(3)))
; __device__ __forceinline__ unsigned xb_add(unsigned* p, unsigned v) { return __hip_atomic_fetch_add(p, v, __ATOMIC_RELAXED, __HIP_MEMORY_SCOPE_AGENT); }
; __device__ __forceinline__ unsigned xb_xcc_id() { return (unsigned)__builtin_amdgcn_s_getreg((3 << 11) | 20) & 0xFu; }
; #define REFRESH() do { int t_ = threadIdx.x; asm volatile("" : "+v"(t_)); F.tid = t_; F.lane = t_ & 63; F.wave = __builtin_amdgcn_readfirstlane(t_ >> 6); F.gw = blockIdx.x * NWAVES + F.wave; } while (0)
; __device__ __forceinline__ XcdBarrier xcd_barrier_post(unsigned* bar, volatile LAS unsigned* st, unsigned gsz) {
;     XcdBarrier b; b.gsz = gsz; b.bar = bar; b.x = xb_xcc_id(); b.st = st;
;     if (threadIdx.x == 0) (void)xb_add(&bar[XB_XCNT(b.x)], 1u);
;     return b;
; __global__ void __launch_bounds__(NWAVES * 64, 2) fwd_kernel(Args args) {
;     ...
;     F.lds = (LAS unsigned char*)lds_raw;
;     ...
;     F.G = gridDim.x; F.NGW = F.G * NWAVES; REFRESH();
;     F.in = args.in; F.out = args.out; F.ws = args.ws;
;     volatile LAS unsigned* MISC = (volatile LAS unsigned*)(F.lds + LDSCTL_OFF);
;     if (threadIdx.x < 16) MISC[threadIdx.x] = 0u;
;     __syncthreads();
;     const bool side_wg = blockIdx.x >= 64;
;     (void)xcd_barrier_post((unsigned*)(args.ws + WS_CTL), MISC + 8, F.G);
_Z10fwd_kernel4Args:
	s_mov_b32 s42, s2
	s_add_u32 s2, s0, 0xe8
	s_addc_u32 s3, s1, 0
	s_load_dwordx8 s[88:95], s[0:1], 0xc0
	v_writelane_b32 v251, s2, 0
	v_and_b32_e32 v206, 0x3ff, v0
	v_mov_b32_e32 v1, v206
	v_readfirstlane_b32 s100, v206
	s_nop 3
	s_lshr_b32 s100, s100, 8
	s_cmp_eq_u32 s100, 0
	s_cbranch_scc0 .Lprio_done
	s_setprio 1
.Lprio_done:
	v_writelane_b32 v251, s3, 1
	s_load_dword s2, s[0:1], 0xe8
	v_cmp_gt_u32_e32 vcc, 16, v206
	s_waitcnt lgkmcnt(0)
	v_writelane_b32 v251, s2, 2
	s_and_saveexec_b64 s[6:7], vcc
	v_lshl_add_u32 v1, v206, 2, 0
	v_add_u32_e32 v1, 0x22000, v1
	v_mov_b32_e32 v2, 0
	ds_write_b32 v1, v2
	s_or_b64 exec, exec, s[6:7]
	v_cmp_eq_u32_e64 s[2:3], 0, v206
	s_waitcnt lgkmcnt(0)
	s_barrier
	v_writelane_b32 v251, s2, 3
	s_getreg_b32 s6, hwreg(HW_REG_XCC_ID, 0, 4)
	s_nop 0
	v_writelane_b32 v251, s3, 4
	s_and_saveexec_b64 s[10:11], s[2:3]
	s_cbranch_execz .LBB0_5
	s_mov_b64 s[4:5], exec
	v_mbcnt_lo_u32_b32 v1, s4, 0
	v_mbcnt_hi_u32_b32 v1, s5, v1
	v_cmp_eq_u32_e32 vcc, 0, v1
	s_and_b64 s[8:9], exec, vcc
	s_mov_b64 exec, s[8:9]
	s_cbranch_execz .LBB0_5
	s_lshl_b32 s6, s6, 8
	s_and_b32 s6, s6, 0xf00
	s_bcnt1_i32_b64 s4, s[4:5]
	v_mov_b32_e32 v1, s6
	v_mov_b32_e32 v2, s4
	global_atomic_add v1, v2, s[94:95] offset:1024

; #define PG8_STAGE(bufoff, gbase, voff) do { _Pragma("unroll") for (int _i = 0; _i < 2; ++_i) \
;         __builtin_amdgcn_global_load_lds((const unsigned*)((const char*)(gbase) + (voff)[_i]), (PG8_LAS unsigned*)(lds + (bufoff) + ldsw + _i * 8192), 16, 0, 0); } while (0)
; #define PG8_LDA(dst, b, h) do { _Pragma("unroll") for (int m = 0; m < 4; ++m) _Pragma("unroll") for (int k = 0; k < 2; ++k) dst[m][k] = *(const PG8_LAS bf16x8*)(lds + PG8_SA(b, h) + aoff + m * 2048 + k * 1024); } while (0)
; #define PG8_LDB(dst, b, h) do { _Pragma("unroll") for (int n = 0; n < 2; ++n) _Pragma("unroll") for (int k = 0; k < 2; ++k) dst[n][k] = *(const PG8_LAS bf16x8*)(lds + PG8_SB(b, h) + boff + n * 2048 + k * 1024); } while (0)
; #define PG8_MMA(ai, bj, At, Bt) do { __builtin_amdgcn_s_setprio(1); _Pragma("unroll") for (int m = 0; m < 4; ++m) _Pragma("unroll") for (int n = 0; n < 2; ++n) _Pragma("unroll") for (int k = 0; k < 2; ++k) \
;         acc[ai][bj][m][n] = __builtin_amdgcn_mfma_f32_16x16x32_bf16(Bt[n][k], At[m][k], acc[ai][bj][m][n], 0, 0, 0); __builtin_amdgcn_s_setprio(0); } while (0)
; #define PG8_WAIT_V(n) asm volatile("s_waitcnt vmcnt(" #n ")" ::: "memory")
; template <class Epi, class Sched, bool APERM>
; __device__ __forceinline__ void gemm_phase(PG8_LAS unsigned char* lds, const Gemm g, const Sched& S, const Epi& E) {
;     ...
;             PG8_LDB(B0, 0, 0); PG8_LDB(B1, 0, 1); PG8_SCHED; PG8_LDA(At, 0, 0); PG8_STAGE(PG8_SA(1, 1), a1 + hstepA, voffA);
;             PG8_WAIT_V(8); PG8_WAIT_L(0); PG8_BAR; PG8_MMA(0, 0, At, B0); PG8_MMA(0, 1, At, B1); PG8_BAR; PG8_SCHED;
;             PG8_LDA(At, 0, 1); PG8_STAGE(PG8_SB(0, 0), b2, voffB); PG8_STAGE(PG8_SB(0, 1), b2 + hstep, voffB); PG8_STAGE(PG8_SA(0, 0), a2, voffA);
;             PG8_WAIT_V(8); PG8_WAIT_L(0); PG8_BAR; PG8_MMA(1, 0, At, B0); PG8_MMA(1, 1, At, B1); PG8_BAR; PG8_SCHED;
;             PG8_LDB(B0, 1, 0); PG8_LDB(B1, 1, 1); PG8_SCHED; PG8_LDA(At, 1, 0); PG8_STAGE(PG8_SA(0, 1), a2 + hstepA, voffA);
;             PG8_WAIT_V(8); PG8_WAIT_L(0); PG8_BAR; PG8_MMA(0, 0, At, B0); PG8_MMA(0, 1, At, B1); PG8_BAR; PG8_SCHED;
;             PG8_LDA(At, 1, 1); PG8_STAGE(PG8_SB(1, 0), b3, voffB); PG8_STAGE(PG8_SB(1, 1), b3 + hstep, voffB); PG8_STAGE(PG8_SA(1, 0), a3, voffA);
;             PG8_WAIT_V(8); PG8_WAIT_L(0); PG8_BAR; PG8_MMA(1, 0, At, B0); PG8_MMA(1, 1, At, B1); PG8_BAR; PG8_SCHED;
.LBB0_217:
	s_add_i32 s20, s22, 2
	s_mov_b32 s21, s77
	s_or_b32 s76, s22, 1
	s_lshl_b64 s[24:25], s[20:21], 7
	s_cmp_lg_u32 s22, s60
	s_cselect_b32 s22, s24, 0
	s_cselect_b32 s21, s25, 0
	s_add_u32 s24, s8, s22
	s_addc_u32 s25, s9, s21
	s_add_i32 s61, 0, 0x10000
	s_add_u32 s22, s6, s22
	v_add_u32_e32 v141, s61, v139
	s_addc_u32 s23, s7, s21
	s_add_i32 s21, 0, 0x14000
	ds_read_b128 v[142:145], v141
	ds_read_b128 v[146:149], v141 offset:1024
	ds_read_b128 v[150:153], v141 offset:2048
	ds_read_b128 v[154:157], v141 offset:3072
	v_add_u32_e32 v141, s21, v139
	ds_read_b128 v[158:161], v141
	ds_read_b128 v[162:165], v141 offset:1024
	ds_read_b128 v[166:169], v141 offset:2048
	ds_read_b128 v[170:173], v141 offset:3072
	s_lshl_b64 s[62:63], s[76:77], 7
	s_add_u32 s62, s10, s62
	s_addc_u32 s63, s11, s63
	v_lshl_add_u64 v[222:223], s[62:63], 0, v[134:135]
	s_add_i32 m0, s47, 0xc000
	ds_read_b128 v[174:177], v140
	ds_read_b128 v[178:181], v140 offset:1024
	ds_read_b128 v[182:185], v140 offset:2048
	ds_read_b128 v[186:189], v140 offset:3072
	ds_read_b128 v[190:193], v140 offset:4096
	ds_read_b128 v[194:197], v140 offset:5120
	ds_read_b128 v[198:201], v140 offset:6144
	ds_read_b128 v[202:205], v140 offset:7168
	global_load_lds_dwordx4 v[222:223], off
	v_lshl_add_u64 v[222:223], s[62:63], 0, v[132:133]
	s_add_i32 m0, s47, 0xe000
	s_nop 0
	global_load_lds_dwordx4 v[222:223], off
	s_waitcnt vmcnt(8)
	s_waitcnt lgkmcnt(0)
	s_barrier
	s_waitcnt lgkmcnt(0)
	v_mfma_f32_16x16x32_bf16 v[128:131], v[142:145], v[174:177], v[128:131]
	v_mfma_f32_16x16x32_bf16 v[124:127], v[150:153], v[174:177], v[124:127]
	v_mfma_f32_16x16x32_bf16 v[120:123], v[142:145], v[182:185], v[120:123]
	v_mfma_f32_16x16x32_bf16 v[116:119], v[150:153], v[182:185], v[116:119]
	v_mfma_f32_16x16x32_bf16 v[112:115], v[142:145], v[190:193], v[112:115]
	v_mfma_f32_16x16x32_bf16 v[108:111], v[150:153], v[190:193], v[108:111]
	v_mfma_f32_16x16x32_bf16 v[104:107], v[142:145], v[198:201], v[104:107]
	v_mfma_f32_16x16x32_bf16 v[100:103], v[150:153], v[198:201], v[100:103]
	v_mfma_f32_16x16x32_bf16 v[128:131], v[146:149], v[178:181], v[128:131]
	v_mfma_f32_16x16x32_bf16 v[124:127], v[154:157], v[178:181], v[124:127]
	v_mfma_f32_16x16x32_bf16 v[120:123], v[146:149], v[186:189], v[120:123]
	v_mfma_f32_16x16x32_bf16 v[116:119], v[154:157], v[186:189], v[116:119]
	v_mfma_f32_16x16x32_bf16 v[112:115], v[146:149], v[194:197], v[112:115]
	v_mfma_f32_16x16x32_bf16 v[108:111], v[154:157], v[194:197], v[108:111]
	v_mfma_f32_16x16x32_bf16 v[104:107], v[146:149], v[202:205], v[104:107]
	v_mfma_f32_16x16x32_bf16 v[100:103], v[154:157], v[202:205], v[100:103]
	v_mfma_f32_16x16x32_bf16 v[96:99], v[158:161], v[174:177], v[96:99]
	v_mfma_f32_16x16x32_bf16 v[92:95], v[166:169], v[174:177], v[92:95]
	v_mfma_f32_16x16x32_bf16 v[88:91], v[158:161], v[182:185], v[88:91]
	v_mfma_f32_16x16x32_bf16 v[84:87], v[166:169], v[182:185], v[84:87]
	v_mfma_f32_16x16x32_bf16 v[80:83], v[158:161], v[190:193], v[80:83]
	v_mfma_f32_16x16x32_bf16 v[76:79], v[166:169], v[190:193], v[76:79]
	v_mfma_f32_16x16x32_bf16 v[72:75], v[158:161], v[198:201], v[72:75]
	v_mfma_f32_16x16x32_bf16 v[68:71], v[166:169], v[198:201], v[68:71]
	v_mfma_f32_16x16x32_bf16 v[96:99], v[162:165], v[178:181], v[96:99]
	v_mfma_f32_16x16x32_bf16 v[92:95], v[170:173], v[178:181], v[92:95]
	v_mfma_f32_16x16x32_bf16 v[88:91], v[162:165], v[186:189], v[88:91]
	v_mfma_f32_16x16x32_bf16 v[84:87], v[170:173], v[186:189], v[84:87]
	v_mfma_f32_16x16x32_bf16 v[80:83], v[162:165], v[194:197], v[80:83]
	v_mfma_f32_16x16x32_bf16 v[76:79], v[170:173], v[194:197], v[76:79]
	v_mfma_f32_16x16x32_bf16 v[72:75], v[162:165], v[202:205], v[72:75]
	v_mfma_f32_16x16x32_bf16 v[68:71], v[170:173], v[202:205], v[68:71]
	s_barrier
	s_add_i32 s61, s61, s46
	v_lshl_add_u64 v[222:223], s[22:23], 0, v[2:3]
	s_mov_b32 m0, s61
	ds_read_b128 v[174:177], v140 offset:16384
	ds_read_b128 v[178:181], v140 offset:17408
	ds_read_b128 v[182:185], v140 offset:18432
	ds_read_b128 v[186:189], v140 offset:19456
	ds_read_b128 v[190:193], v140 offset:20480
	ds_read_b128 v[194:197], v140 offset:21504
	ds_read_b128 v[198:201], v140 offset:22528
	ds_read_b128 v[202:205], v140 offset:23552
	global_load_lds_dwordx4 v[222:223], off
	s_add_i32 m0, s61, 0x2000
	s_add_u32 s62, s22, 0xb0000
	v_lshl_add_u64 v[230:231], s[22:23], 0, v[0:1]
	s_addc_u32 s63, s23, 0
	s_add_i32 s21, s21, s46
	global_load_lds_dwordx4 v[230:231], off
	v_lshl_add_u64 v[232:233], s[62:63], 0, v[2:3]
	s_mov_b32 m0, s21
	v_lshl_add_u64 v[234:235], s[24:25], 0, v[132:133]
	global_load_lds_dwordx4 v[232:233], off
	v_lshl_add_u64 v[232:233], s[62:63], 0, v[0:1]
	s_add_i32 m0, s21, 0x2000
	s_nop 0
	global_load_lds_dwordx4 v[232:233], off
	v_lshl_add_u64 v[232:233], s[24:25], 0, v[134:135]
	s_mov_b32 m0, s47
	s_nop 0
	global_load_lds_dwordx4 v[232:233], off
	s_mov_b32 m0, s49
	s_nop 0
	global_load_lds_dwordx4 v[234:235], off
	s_waitcnt vmcnt(8)
	s_waitcnt lgkmcnt(0)
	s_barrier
; #define PG8_STAGE(bufoff, gbase, voff) do { _Pragma("unroll") for (int _i = 0; _i < 2; ++_i) \
;         __builtin_amdgcn_global_load_lds((const unsigned*)((const char*)(gbase) + (voff)[_i]), (PG8_LAS unsigned*)(lds + (bufoff) + ldsw + _i * 8192), 16, 0, 0); } while (0)
; #define PG8_LDA(dst, b, h) do { _Pragma("unroll") for (int m = 0; m < 4; ++m) _Pragma("unroll") for (int k = 0; k < 2; ++k) dst[m][k] = *(const PG8_LAS bf16x8*)(lds + PG8_SA(b, h) + aoff + m * 2048 + k * 1024); } while (0)
; #define PG8_LDB(dst, b, h) do { _Pragma("unroll") for (int n = 0; n < 2; ++n) _Pragma("unroll") for (int k = 0; k < 2; ++k) dst[n][k] = *(const PG8_LAS bf16x8*)(lds + PG8_SB(b, h) + boff + n * 2048 + k * 1024); } while (0)
; #define PG8_MMA(ai, bj, At, Bt) do { __builtin_amdgcn_s_setprio(1); _Pragma("unroll") for (int m = 0; m < 4; ++m) _Pragma("unroll") for (int n = 0; n < 2; ++n) _Pragma("unroll") for (int k = 0; k < 2; ++k) \
;         acc[ai][bj][m][n] = __builtin_amdgcn_mfma_f32_16x16x32_bf16(Bt[n][k], At[m][k], acc[ai][bj][m][n], 0, 0, 0); __builtin_amdgcn_s_setprio(0); } while (0)
; #define PG8_WAIT_V(n) asm volatile("s_waitcnt vmcnt(" #n ")" ::: "memory")
; template <class Epi, class Sched, bool APERM>
; __device__ __forceinline__ void gemm_phase(PG8_LAS unsigned char* lds, const Gemm g, const Sched& S, const Epi& E) {
;     ...
;             PG8_LDB(B0, 0, 0); PG8_LDB(B1, 0, 1); PG8_SCHED; PG8_LDA(At, 0, 0); PG8_STAGE(PG8_SA(1, 1), a1 + hstepA, voffA);
;             PG8_WAIT_V(8); PG8_WAIT_L(0); PG8_BAR; PG8_MMA(0, 0, At, B0); PG8_MMA(0, 1, At, B1); PG8_BAR; PG8_SCHED;
;             PG8_LDA(At, 0, 1); PG8_STAGE(PG8_SB(0, 0), b2, voffB); PG8_STAGE(PG8_SB(0, 1), b2 + hstep, voffB); PG8_STAGE(PG8_SA(0, 0), a2, voffA);
;             PG8_WAIT_V(8); PG8_WAIT_L(0); PG8_BAR; PG8_MMA(1, 0, At, B0); PG8_MMA(1, 1, At, B1); PG8_BAR; PG8_SCHED;
;             PG8_LDB(B0, 1, 0); PG8_LDB(B1, 1, 1); PG8_SCHED; PG8_LDA(At, 1, 0); PG8_STAGE(PG8_SA(0, 1), a2 + hstepA, voffA);
;             PG8_WAIT_V(8); PG8_WAIT_L(0); PG8_BAR; PG8_MMA(0, 0, At, B0); PG8_MMA(0, 1, At, B1); PG8_BAR; PG8_SCHED;
;             PG8_LDA(At, 1, 1); PG8_STAGE(PG8_SB(1, 0), b3, voffB); PG8_STAGE(PG8_SB(1, 1), b3 + hstep, voffB); PG8_STAGE(PG8_SA(1, 0), a3, voffA);
;             PG8_WAIT_V(8); PG8_WAIT_L(0); PG8_BAR; PG8_MMA(1, 0, At, B0); PG8_MMA(1, 1, At, B1); PG8_BAR; PG8_SCHED;
	s_waitcnt lgkmcnt(0)
	v_mfma_f32_16x16x32_bf16 v[64:67], v[142:145], v[174:177], v[64:67]
	v_mfma_f32_16x16x32_bf16 v[60:63], v[150:153], v[174:177], v[60:63]
	v_mfma_f32_16x16x32_bf16 v[56:59], v[142:145], v[182:185], v[56:59]
	v_mfma_f32_16x16x32_bf16 v[52:55], v[150:153], v[182:185], v[52:55]
	v_mfma_f32_16x16x32_bf16 v[48:51], v[142:145], v[190:193], v[48:51]
	v_mfma_f32_16x16x32_bf16 v[44:47], v[150:153], v[190:193], v[44:47]
	v_mfma_f32_16x16x32_bf16 v[40:43], v[142:145], v[198:201], v[40:43]
	v_mfma_f32_16x16x32_bf16 v[36:39], v[150:153], v[198:201], v[36:39]
	v_mfma_f32_16x16x32_bf16 v[64:67], v[146:149], v[178:181], v[64:67]
	v_mfma_f32_16x16x32_bf16 v[60:63], v[154:157], v[178:181], v[60:63]
	v_mfma_f32_16x16x32_bf16 v[56:59], v[146:149], v[186:189], v[56:59]
	v_mfma_f32_16x16x32_bf16 v[52:55], v[154:157], v[186:189], v[52:55]
	v_mfma_f32_16x16x32_bf16 v[48:51], v[146:149], v[194:197], v[48:51]
	v_mfma_f32_16x16x32_bf16 v[44:47], v[154:157], v[194:197], v[44:47]
	v_mfma_f32_16x16x32_bf16 v[40:43], v[146:149], v[202:205], v[40:43]
	v_mfma_f32_16x16x32_bf16 v[36:39], v[154:157], v[202:205], v[36:39]
	v_mfma_f32_16x16x32_bf16 v[32:35], v[158:161], v[174:177], v[32:35]
	v_mfma_f32_16x16x32_bf16 v[28:31], v[166:169], v[174:177], v[28:31]
	v_mfma_f32_16x16x32_bf16 v[24:27], v[158:161], v[182:185], v[24:27]
	v_mfma_f32_16x16x32_bf16 v[20:23], v[166:169], v[182:185], v[20:23]
	v_mfma_f32_16x16x32_bf16 v[16:19], v[158:161], v[190:193], v[16:19]
	v_mfma_f32_16x16x32_bf16 v[12:15], v[166:169], v[190:193], v[12:15]
	v_mfma_f32_16x16x32_bf16 v[8:11], v[158:161], v[198:201], v[8:11]
	v_mfma_f32_16x16x32_bf16 v[4:7], v[166:169], v[198:201], v[4:7]
	v_mfma_f32_16x16x32_bf16 v[32:35], v[162:165], v[178:181], v[32:35]
	v_mfma_f32_16x16x32_bf16 v[28:31], v[170:173], v[178:181], v[28:31]
	v_mfma_f32_16x16x32_bf16 v[24:27], v[162:165], v[186:189], v[24:27]
	v_mfma_f32_16x16x32_bf16 v[20:23], v[170:173], v[186:189], v[20:23]
	v_mfma_f32_16x16x32_bf16 v[16:19], v[162:165], v[194:197], v[16:19]
	v_mfma_f32_16x16x32_bf16 v[12:15], v[170:173], v[194:197], v[12:15]
	v_mfma_f32_16x16x32_bf16 v[8:11], v[162:165], v[202:205], v[8:11]
	v_mfma_f32_16x16x32_bf16 v[4:7], v[170:173], v[202:205], v[4:7]
	s_barrier
	s_add_i32 s21, 0, 0x18000
	v_add_u32_e32 v141, s21, v139
	s_add_i32 s61, 0, 0x1c000
	ds_read_b128 v[142:145], v141
	ds_read_b128 v[146:149], v141 offset:1024
	ds_read_b128 v[150:153], v141 offset:2048
	ds_read_b128 v[154:157], v141 offset:3072
	v_add_u32_e32 v141, s61, v139
	ds_read_b128 v[158:161], v141
	ds_read_b128 v[162:165], v141 offset:1024
	ds_read_b128 v[166:169], v141 offset:2048
	ds_read_b128 v[170:173], v141 offset:3072
	s_add_u32 s24, s24, 0xb0000
	s_addc_u32 s25, s25, 0
	s_mov_b32 m0, s50
	v_lshl_add_u64 v[236:237], s[24:25], 0, v[134:135]
	ds_read_b128 v[174:177], v140 offset:32768
	ds_read_b128 v[178:181], v140 offset:33792
	ds_read_b128 v[182:185], v140 offset:34816
	ds_read_b128 v[186:189], v140 offset:35840
	ds_read_b128 v[190:193], v140 offset:36864
	ds_read_b128 v[194:197], v140 offset:37888
	ds_read_b128 v[198:201], v140 offset:38912
	ds_read_b128 v[202:205], v140 offset:39936
	global_load_lds_dwordx4 v[236:237], off
	v_lshl_add_u64 v[236:237], s[24:25], 0, v[132:133]
	s_mov_b32 m0, s56
	s_nop 0
	global_load_lds_dwordx4 v[236:237], off
	s_waitcnt vmcnt(8)
	s_waitcnt lgkmcnt(0)
	s_barrier
	s_waitcnt lgkmcnt(0)
	v_mfma_f32_16x16x32_bf16 v[128:131], v[142:145], v[174:177], v[128:131]
	v_mfma_f32_16x16x32_bf16 v[124:127], v[150:153], v[174:177], v[124:127]
	v_mfma_f32_16x16x32_bf16 v[120:123], v[142:145], v[182:185], v[120:123]
	v_mfma_f32_16x16x32_bf16 v[116:119], v[150:153], v[182:185], v[116:119]
	v_mfma_f32_16x16x32_bf16 v[112:115], v[142:145], v[190:193], v[112:115]
	v_mfma_f32_16x16x32_bf16 v[108:111], v[150:153], v[190:193], v[108:111]
	v_mfma_f32_16x16x32_bf16 v[104:107], v[142:145], v[198:201], v[104:107]
	v_mfma_f32_16x16x32_bf16 v[100:103], v[150:153], v[198:201], v[100:103]
	v_mfma_f32_16x16x32_bf16 v[128:131], v[146:149], v[178:181], v[128:131]
	v_mfma_f32_16x16x32_bf16 v[124:127], v[154:157], v[178:181], v[124:127]
	v_mfma_f32_16x16x32_bf16 v[120:123], v[146:149], v[186:189], v[120:123]
	v_mfma_f32_16x16x32_bf16 v[116:119], v[154:157], v[186:189], v[116:119]
	v_mfma_f32_16x16x32_bf16 v[112:115], v[146:149], v[194:197], v[112:115]
	v_mfma_f32_16x16x32_bf16 v[108:111], v[154:157], v[194:197], v[108:111]
	v_mfma_f32_16x16x32_bf16 v[104:107], v[146:149], v[202:205], v[104:107]
	v_mfma_f32_16x16x32_bf16 v[100:103], v[154:157], v[202:205], v[100:103]
	v_mfma_f32_16x16x32_bf16 v[96:99], v[158:161], v[174:177], v[96:99]
	v_mfma_f32_16x16x32_bf16 v[92:95], v[166:169], v[174:177], v[92:95]
	v_mfma_f32_16x16x32_bf16 v[88:91], v[158:161], v[182:185], v[88:91]
	v_mfma_f32_16x16x32_bf16 v[84:87], v[166:169], v[182:185], v[84:87]
	v_mfma_f32_16x16x32_bf16 v[80:83], v[158:161], v[190:193], v[80:83]
	v_mfma_f32_16x16x32_bf16 v[76:79], v[166:169], v[190:193], v[76:79]
	v_mfma_f32_16x16x32_bf16 v[72:75], v[158:161], v[198:201], v[72:75]
	v_mfma_f32_16x16x32_bf16 v[68:71], v[166:169], v[198:201], v[68:71]
	v_mfma_f32_16x16x32_bf16 v[96:99], v[162:165], v[178:181], v[96:99]
	v_mfma_f32_16x16x32_bf16 v[92:95], v[170:173], v[178:181], v[92:95]
	v_mfma_f32_16x16x32_bf16 v[88:91], v[162:165], v[186:189], v[88:91]
	v_mfma_f32_16x16x32_bf16 v[84:87], v[170:173], v[186:189], v[84:87]
	v_mfma_f32_16x16x32_bf16 v[80:83], v[162:165], v[194:197], v[80:83]
	v_mfma_f32_16x16x32_bf16 v[76:79], v[170:173], v[194:197], v[76:79]
	v_mfma_f32_16x16x32_bf16 v[72:75], v[162:165], v[202:205], v[72:75]
	v_mfma_f32_16x16x32_bf16 v[68:71], v[170:173], v[202:205], v[68:71]
	s_barrier
; #define PG8_STAGE(bufoff, gbase, voff) do { _Pragma("unroll") for (int _i = 0; _i < 2; ++_i) \
;         __builtin_amdgcn_global_load_lds((const unsigned*)((const char*)(gbase) + (voff)[_i]), (PG8_LAS unsigned*)(lds + (bufoff) + ldsw + _i * 8192), 16, 0, 0); } while (0)
; #define PG8_LDA(dst, b, h) do { _Pragma("unroll") for (int m = 0; m < 4; ++m) _Pragma("unroll") for (int k = 0; k < 2; ++k) dst[m][k] = *(const PG8_LAS bf16x8*)(lds + PG8_SA(b, h) + aoff + m * 2048 + k * 1024); } while (0)
; #define PG8_LDB(dst, b, h) do { _Pragma("unroll") for (int n = 0; n < 2; ++n) _Pragma("unroll") for (int k = 0; k < 2; ++k) dst[n][k] = *(const PG8_LAS bf16x8*)(lds + PG8_SB(b, h) + boff + n * 2048 + k * 1024); } while (0)
; #define PG8_MMA(ai, bj, At, Bt) do { __builtin_amdgcn_s_setprio(1); _Pragma("unroll") for (int m = 0; m < 4; ++m) _Pragma("unroll") for (int n = 0; n < 2; ++n) _Pragma("unroll") for (int k = 0; k < 2; ++k) \
;         acc[ai][bj][m][n] = __builtin_amdgcn_mfma_f32_16x16x32_bf16(Bt[n][k], At[m][k], acc[ai][bj][m][n], 0, 0, 0); __builtin_amdgcn_s_setprio(0); } while (0)
; #define PG8_BAR __builtin_amdgcn_s_barrier()
; template <class Epi, class Sched, bool APERM>
; __device__ __forceinline__ void gemm_phase(PG8_LAS unsigned char* lds, const Gemm g, const Sched& S, const Epi& E) {
;     ...
;             PG8_LDB(B0, 0, 0); PG8_LDB(B1, 0, 1); PG8_SCHED; PG8_LDA(At, 0, 0); PG8_STAGE(PG8_SA(1, 1), a1 + hstepA, voffA);
;             PG8_WAIT_V(8); PG8_WAIT_L(0); PG8_BAR; PG8_MMA(0, 0, At, B0); PG8_MMA(0, 1, At, B1); PG8_BAR; PG8_SCHED;
;             PG8_LDA(At, 0, 1); PG8_STAGE(PG8_SB(0, 0), b2, voffB); PG8_STAGE(PG8_SB(0, 1), b2 + hstep, voffB); PG8_STAGE(PG8_SA(0, 0), a2, voffA);
;             PG8_WAIT_V(8); PG8_WAIT_L(0); PG8_BAR; PG8_MMA(1, 0, At, B0); PG8_MMA(1, 1, At, B1); PG8_BAR; PG8_SCHED;
;             PG8_LDB(B0, 1, 0); PG8_LDB(B1, 1, 1); PG8_SCHED; PG8_LDA(At, 1, 0); PG8_STAGE(PG8_SA(0, 1), a2 + hstepA, voffA);
;             PG8_WAIT_V(8); PG8_WAIT_L(0); PG8_BAR; PG8_MMA(0, 0, At, B0); PG8_MMA(0, 1, At, B1); PG8_BAR; PG8_SCHED;
;             PG8_LDA(At, 1, 1); PG8_STAGE(PG8_SB(1, 0), b3, voffB); PG8_STAGE(PG8_SB(1, 1), b3 + hstep, voffB); PG8_STAGE(PG8_SA(1, 0), a3, voffA);
;             PG8_WAIT_V(8); PG8_WAIT_L(0); PG8_BAR; PG8_MMA(1, 0, At, B0); PG8_MMA(1, 1, At, B1); PG8_BAR; PG8_SCHED;
;         }
;         if (wr == 0) PG8_BAR;
	s_add_i32 s21, s21, s46
	v_lshl_add_u64 v[222:223], v[222:223], 0, s[52:53]
	s_mov_b32 m0, s21
	ds_read_b128 v[174:177], v140 offset:49152
	ds_read_b128 v[178:181], v140 offset:50176
	ds_read_b128 v[182:185], v140 offset:51200
	ds_read_b128 v[186:189], v140 offset:52224
	ds_read_b128 v[190:193], v140 offset:53248
	ds_read_b128 v[194:197], v140 offset:54272
	ds_read_b128 v[198:201], v140 offset:55296
	ds_read_b128 v[202:205], v140 offset:56320
	global_load_lds_dwordx4 v[222:223], off
	s_add_i32 m0, s21, 0x2000
	s_add_u32 s22, s22, 0xb0080
	v_lshl_add_u64 v[222:223], v[230:231], 0, s[52:53]
	s_addc_u32 s23, s23, 0
	s_add_i32 s21, s61, s46
	global_load_lds_dwordx4 v[222:223], off
	v_lshl_add_u64 v[222:223], s[22:23], 0, v[2:3]
	s_mov_b32 m0, s21
	s_nop 0
	global_load_lds_dwordx4 v[222:223], off
	v_lshl_add_u64 v[222:223], s[22:23], 0, v[0:1]
	s_add_i32 m0, s21, 0x2000
	s_nop 0
	global_load_lds_dwordx4 v[222:223], off
	v_lshl_add_u64 v[222:223], v[232:233], 0, s[52:53]
	s_mov_b32 m0, s58
	s_nop 0
	global_load_lds_dwordx4 v[222:223], off
	v_lshl_add_u64 v[222:223], v[234:235], 0, s[52:53]
	s_mov_b32 m0, s59
	s_nop 0
	global_load_lds_dwordx4 v[222:223], off
	s_waitcnt vmcnt(8)
	s_waitcnt lgkmcnt(0)
	s_barrier
	s_waitcnt lgkmcnt(0)
	v_mfma_f32_16x16x32_bf16 v[64:67], v[142:145], v[174:177], v[64:67]
	v_mfma_f32_16x16x32_bf16 v[60:63], v[150:153], v[174:177], v[60:63]
	v_mfma_f32_16x16x32_bf16 v[56:59], v[142:145], v[182:185], v[56:59]
	v_mfma_f32_16x16x32_bf16 v[52:55], v[150:153], v[182:185], v[52:55]
	v_mfma_f32_16x16x32_bf16 v[48:51], v[142:145], v[190:193], v[48:51]
	v_mfma_f32_16x16x32_bf16 v[44:47], v[150:153], v[190:193], v[44:47]
	v_mfma_f32_16x16x32_bf16 v[40:43], v[142:145], v[198:201], v[40:43]
	v_mfma_f32_16x16x32_bf16 v[36:39], v[150:153], v[198:201], v[36:39]
	v_mfma_f32_16x16x32_bf16 v[64:67], v[146:149], v[178:181], v[64:67]
	v_mfma_f32_16x16x32_bf16 v[60:63], v[154:157], v[178:181], v[60:63]
	v_mfma_f32_16x16x32_bf16 v[56:59], v[146:149], v[186:189], v[56:59]
	v_mfma_f32_16x16x32_bf16 v[52:55], v[154:157], v[186:189], v[52:55]
	v_mfma_f32_16x16x32_bf16 v[48:51], v[146:149], v[194:197], v[48:51]
	v_mfma_f32_16x16x32_bf16 v[44:47], v[154:157], v[194:197], v[44:47]
	v_mfma_f32_16x16x32_bf16 v[40:43], v[146:149], v[202:205], v[40:43]
	v_mfma_f32_16x16x32_bf16 v[36:39], v[154:157], v[202:205], v[36:39]
	v_mfma_f32_16x16x32_bf16 v[32:35], v[158:161], v[174:177], v[32:35]
	v_mfma_f32_16x16x32_bf16 v[28:31], v[166:169], v[174:177], v[28:31]
	v_mfma_f32_16x16x32_bf16 v[24:27], v[158:161], v[182:185], v[24:27]
	v_mfma_f32_16x16x32_bf16 v[20:23], v[166:169], v[182:185], v[20:23]
	v_mfma_f32_16x16x32_bf16 v[16:19], v[158:161], v[190:193], v[16:19]
	v_mfma_f32_16x16x32_bf16 v[12:15], v[166:169], v[190:193], v[12:15]
	v_mfma_f32_16x16x32_bf16 v[8:11], v[158:161], v[198:201], v[8:11]
	v_mfma_f32_16x16x32_bf16 v[4:7], v[166:169], v[198:201], v[4:7]
	v_mfma_f32_16x16x32_bf16 v[32:35], v[162:165], v[178:181], v[32:35]
	v_mfma_f32_16x16x32_bf16 v[28:31], v[170:173], v[178:181], v[28:31]
	v_mfma_f32_16x16x32_bf16 v[24:27], v[162:165], v[186:189], v[24:27]
	v_mfma_f32_16x16x32_bf16 v[20:23], v[170:173], v[186:189], v[20:23]
	v_mfma_f32_16x16x32_bf16 v[16:19], v[162:165], v[194:197], v[16:19]
	v_mfma_f32_16x16x32_bf16 v[12:15], v[170:173], v[194:197], v[12:15]
	v_mfma_f32_16x16x32_bf16 v[8:11], v[162:165], v[202:205], v[8:11]
	v_mfma_f32_16x16x32_bf16 v[4:7], v[170:173], v[202:205], v[4:7]
	s_barrier
	s_cmp_ge_u32 s20, s57
	s_mov_b32 s22, s20
	s_cbranch_scc0 .LBB0_217
	s_cmpk_lt_u32 s45, 0x100
	s_cbranch_scc0 .LBB0_220
	s_barrier

; #define PG8_STAGE(bufoff, gbase, voff) do { _Pragma("unroll") for (int _i = 0; _i < 2; ++_i) \
;         __builtin_amdgcn_global_load_lds((const unsigned*)((const char*)(gbase) + (voff)[_i]), (PG8_LAS unsigned*)(lds + (bufoff) + ldsw + _i * 8192), 16, 0, 0); } while (0)
; #define PG8_LDA(dst, b, h) do { _Pragma("unroll") for (int m = 0; m < 4; ++m) _Pragma("unroll") for (int k = 0; k < 2; ++k) dst[m][k] = *(const PG8_LAS bf16x8*)(lds + PG8_SA(b, h) + aoff + m * 2048 + k * 1024); } while (0)
; #define PG8_LDB(dst, b, h) do { _Pragma("unroll") for (int n = 0; n < 2; ++n) _Pragma("unroll") for (int k = 0; k < 2; ++k) dst[n][k] = *(const PG8_LAS bf16x8*)(lds + PG8_SB(b, h) + boff + n * 2048 + k * 1024); } while (0)
; #define PG8_BAR __builtin_amdgcn_s_barrier()
; template <class Epi, class Sched, bool APERM>
; __device__ __forceinline__ void gemm_phase(PG8_LAS unsigned char* lds, const Gemm g, const Sched& S, const Epi& E) {
;     ...
;         for (int t = 0; t < nt; t += 2) {
;             const bool last = (t == nt - 2);
;             const char* a1 = cA + (size_t)(t + 1) * kstep;
;             const char* a2 = last ? nA : cA + (size_t)(t + 2) * kstep; const char* b2 = last ? nB : cB + (size_t)(t + 2) * kstep;
;             const char* a3 = a2 + kstep; const char* b3 = b2 + kstep;
;             if (last && has_next) S.a_ready(nxt);
;             PG8_LDB(B0, 0, 0); PG8_LDB(B1, 0, 1); PG8_SCHED; PG8_LDA(At, 0, 0); PG8_STAGE(PG8_SA(1, 1), a1 + hstepA, voffA);
;             PG8_WAIT_V(8); PG8_WAIT_L(0); PG8_BAR; PG8_MMA(0, 0, At, B0); PG8_MMA(0, 1, At, B1); PG8_BAR; PG8_SCHED;
;             PG8_LDA(At, 0, 1); PG8_STAGE(PG8_SB(0, 0), b2, voffB); PG8_STAGE(PG8_SB(0, 1), b2 + hstep, voffB); PG8_STAGE(PG8_SA(0, 0), a2, voffA);
;             PG8_WAIT_V(8); PG8_WAIT_L(0); PG8_BAR; PG8_MMA(1, 0, At, B0); PG8_MMA(1, 1, At, B1); PG8_BAR; PG8_SCHED;
;             PG8_LDB(B0, 1, 0); PG8_LDB(B1, 1, 1); PG8_SCHED; PG8_LDA(At, 1, 0); PG8_STAGE(PG8_SA(0, 1), a2 + hstepA, voffA);
;             PG8_WAIT_V(8); PG8_WAIT_L(0); PG8_BAR; PG8_MMA(0, 0, At, B0); PG8_MMA(0, 1, At, B1); PG8_BAR; PG8_SCHED;
;             PG8_LDA(At, 1, 1); PG8_STAGE(PG8_SB(1, 0), b3, voffB); PG8_STAGE(PG8_SB(1, 1), b3 + hstep, voffB); PG8_STAGE(PG8_SA(1, 0), a3, voffA);
;             PG8_WAIT_V(8); PG8_WAIT_L(0); PG8_BAR; PG8_MMA(1, 0, At, B0); PG8_MMA(1, 1, At, B1); PG8_BAR; PG8_SCHED;
.LBB0_230:
	s_add_u32 s10, s8, 0x100
	s_addc_u32 s11, s9, 0
	s_cmp_lg_u32 s35, 6
	s_cselect_b32 s20, s10, 0
	s_cselect_b32 s21, s11, 0
	s_add_u32 s22, s6, s20
	s_addc_u32 s23, s7, s21
	s_add_i32 s47, 0, 0x10000
	s_add_u32 s20, s4, s20
	v_add_u32_e32 v145, s47, v143
	s_addc_u32 s21, s5, s21
	s_add_i32 s49, 0, 0x14000
	ds_read_b128 v[146:149], v145
	ds_read_b128 v[152:155], v145 offset:1024
	ds_read_b128 v[156:159], v145 offset:2048
	ds_read_b128 v[160:163], v145 offset:3072
	v_add_u32_e32 v145, s49, v143
	ds_read_b128 v[164:167], v145
	ds_read_b128 v[168:171], v145 offset:1024
	ds_read_b128 v[172:175], v145 offset:2048
	ds_read_b128 v[176:179], v145 offset:3072
	v_lshl_add_u64 v[204:205], v[136:137], 0, s[8:9]
	s_add_i32 m0, s40, 0xc000
	ds_read_b128 v[180:183], v144
	ds_read_b128 v[184:187], v144 offset:1024
	ds_read_b128 v[188:191], v144 offset:2048
	ds_read_b128 v[192:195], v144 offset:3072
	ds_read_b128 v[196:199], v144 offset:4096
	ds_read_b128 v[200:203], v144 offset:5120
	ds_read_b128 v[230:233], v144 offset:6144
	ds_read_b128 v[234:237], v144 offset:7168
	global_load_lds_dwordx4 v[204:205], off
	v_lshl_add_u64 v[204:205], v[138:139], 0, s[8:9]
	s_add_i32 m0, s40, 0xe000
	s_nop 0
	global_load_lds_dwordx4 v[204:205], off
	s_waitcnt vmcnt(8)
	s_waitcnt lgkmcnt(0)
	s_barrier
	s_waitcnt lgkmcnt(0)
	v_mfma_f32_16x16x32_bf16 v[128:131], v[146:149], v[180:183], v[128:131]
	v_mfma_f32_16x16x32_bf16 v[124:127], v[156:159], v[180:183], v[124:127]
	v_mfma_f32_16x16x32_bf16 v[112:115], v[146:149], v[188:191], v[112:115]
	v_mfma_f32_16x16x32_bf16 v[108:111], v[156:159], v[188:191], v[108:111]
	v_mfma_f32_16x16x32_bf16 v[96:99], v[146:149], v[196:199], v[96:99]
	v_mfma_f32_16x16x32_bf16 v[92:95], v[156:159], v[196:199], v[92:95]
	v_mfma_f32_16x16x32_bf16 v[80:83], v[146:149], v[230:233], v[80:83]
	v_mfma_f32_16x16x32_bf16 v[76:79], v[156:159], v[230:233], v[76:79]
	v_mfma_f32_16x16x32_bf16 v[128:131], v[152:155], v[184:187], v[128:131]
	v_mfma_f32_16x16x32_bf16 v[124:127], v[160:163], v[184:187], v[124:127]
	v_mfma_f32_16x16x32_bf16 v[112:115], v[152:155], v[192:195], v[112:115]
	v_mfma_f32_16x16x32_bf16 v[108:111], v[160:163], v[192:195], v[108:111]
	v_mfma_f32_16x16x32_bf16 v[96:99], v[152:155], v[200:203], v[96:99]
	v_mfma_f32_16x16x32_bf16 v[92:95], v[160:163], v[200:203], v[92:95]
	v_mfma_f32_16x16x32_bf16 v[80:83], v[152:155], v[234:237], v[80:83]
	v_mfma_f32_16x16x32_bf16 v[76:79], v[160:163], v[234:237], v[76:79]
	v_mfma_f32_16x16x32_bf16 v[120:123], v[164:167], v[180:183], v[120:123]
	v_mfma_f32_16x16x32_bf16 v[116:119], v[172:175], v[180:183], v[116:119]
	v_mfma_f32_16x16x32_bf16 v[104:107], v[164:167], v[188:191], v[104:107]
	v_mfma_f32_16x16x32_bf16 v[100:103], v[172:175], v[188:191], v[100:103]
	v_mfma_f32_16x16x32_bf16 v[88:91], v[164:167], v[196:199], v[88:91]
	v_mfma_f32_16x16x32_bf16 v[84:87], v[172:175], v[196:199], v[84:87]
	v_mfma_f32_16x16x32_bf16 v[72:75], v[164:167], v[230:233], v[72:75]
	v_mfma_f32_16x16x32_bf16 v[68:71], v[172:175], v[230:233], v[68:71]
	v_mfma_f32_16x16x32_bf16 v[120:123], v[168:171], v[184:187], v[120:123]
	v_mfma_f32_16x16x32_bf16 v[116:119], v[176:179], v[184:187], v[116:119]
	v_mfma_f32_16x16x32_bf16 v[104:107], v[168:171], v[192:195], v[104:107]
	v_mfma_f32_16x16x32_bf16 v[100:103], v[176:179], v[192:195], v[100:103]
	v_mfma_f32_16x16x32_bf16 v[88:91], v[168:171], v[200:203], v[88:91]
	v_mfma_f32_16x16x32_bf16 v[84:87], v[176:179], v[200:203], v[84:87]
	v_mfma_f32_16x16x32_bf16 v[72:75], v[168:171], v[234:237], v[72:75]
	v_mfma_f32_16x16x32_bf16 v[68:71], v[176:179], v[234:237], v[68:71]
	s_barrier
	s_add_i32 s8, s47, s44
	v_lshl_add_u64 v[204:205], s[20:21], 0, v[2:3]
	s_mov_b32 m0, s8
	ds_read_b128 v[180:183], v144 offset:16384
	ds_read_b128 v[184:187], v144 offset:17408
	ds_read_b128 v[188:191], v144 offset:18432
	ds_read_b128 v[192:195], v144 offset:19456
	ds_read_b128 v[196:199], v144 offset:20480
	ds_read_b128 v[200:203], v144 offset:21504
	ds_read_b128 v[230:233], v144 offset:22528
	ds_read_b128 v[234:237], v144 offset:23552
	global_load_lds_dwordx4 v[204:205], off
	s_add_i32 m0, s8, 0x2000
	s_add_u32 s8, s20, 0xb0000
	v_lshl_add_u64 v[222:223], s[20:21], 0, v[0:1]
	s_addc_u32 s9, s21, 0
	s_add_i32 s47, s49, s44
	global_load_lds_dwordx4 v[222:223], off
	v_lshl_add_u64 v[238:239], s[8:9], 0, v[2:3]
	s_mov_b32 m0, s47
	v_lshl_add_u64 v[240:241], s[22:23], 0, v[132:133]
	global_load_lds_dwordx4 v[238:239], off
	v_lshl_add_u64 v[238:239], s[8:9], 0, v[0:1]
	s_add_i32 m0, s47, 0x2000
	s_nop 0
	global_load_lds_dwordx4 v[238:239], off
	v_lshl_add_u64 v[238:239], s[22:23], 0, v[134:135]
	s_mov_b32 m0, s40
	s_nop 0
	global_load_lds_dwordx4 v[238:239], off
	s_mov_b32 m0, s36
	s_nop 0
	global_load_lds_dwordx4 v[240:241], off
	s_waitcnt vmcnt(8)
	s_waitcnt lgkmcnt(0)
	s_barrier
; #define PG8_STAGE(bufoff, gbase, voff) do { _Pragma("unroll") for (int _i = 0; _i < 2; ++_i) \
;         __builtin_amdgcn_global_load_lds((const unsigned*)((const char*)(gbase) + (voff)[_i]), (PG8_LAS unsigned*)(lds + (bufoff) + ldsw + _i * 8192), 16, 0, 0); } while (0)
; #define PG8_LDA(dst, b, h) do { _Pragma("unroll") for (int m = 0; m < 4; ++m) _Pragma("unroll") for (int k = 0; k < 2; ++k) dst[m][k] = *(const PG8_LAS bf16x8*)(lds + PG8_SA(b, h) + aoff + m * 2048 + k * 1024); } while (0)
; #define PG8_LDB(dst, b, h) do { _Pragma("unroll") for (int n = 0; n < 2; ++n) _Pragma("unroll") for (int k = 0; k < 2; ++k) dst[n][k] = *(const PG8_LAS bf16x8*)(lds + PG8_SB(b, h) + boff + n * 2048 + k * 1024); } while (0)
; #define PG8_MMA(ai, bj, At, Bt) do { __builtin_amdgcn_s_setprio(1); _Pragma("unroll") for (int m = 0; m < 4; ++m) _Pragma("unroll") for (int n = 0; n < 2; ++n) _Pragma("unroll") for (int k = 0; k < 2; ++k) \
;         acc[ai][bj][m][n] = __builtin_amdgcn_mfma_f32_16x16x32_bf16(Bt[n][k], At[m][k], acc[ai][bj][m][n], 0, 0, 0); __builtin_amdgcn_s_setprio(0); } while (0)
; #define PG8_WAIT_V(n) asm volatile("s_waitcnt vmcnt(" #n ")" ::: "memory")
; template <class Epi, class Sched, bool APERM>
; __device__ __forceinline__ void gemm_phase(PG8_LAS unsigned char* lds, const Gemm g, const Sched& S, const Epi& E) {
;     ...
;             PG8_LDB(B0, 0, 0); PG8_LDB(B1, 0, 1); PG8_SCHED; PG8_LDA(At, 0, 0); PG8_STAGE(PG8_SA(1, 1), a1 + hstepA, voffA);
;             PG8_WAIT_V(8); PG8_WAIT_L(0); PG8_BAR; PG8_MMA(0, 0, At, B0); PG8_MMA(0, 1, At, B1); PG8_BAR; PG8_SCHED;
;             PG8_LDA(At, 0, 1); PG8_STAGE(PG8_SB(0, 0), b2, voffB); PG8_STAGE(PG8_SB(0, 1), b2 + hstep, voffB); PG8_STAGE(PG8_SA(0, 0), a2, voffA);
;             PG8_WAIT_V(8); PG8_WAIT_L(0); PG8_BAR; PG8_MMA(1, 0, At, B0); PG8_MMA(1, 1, At, B1); PG8_BAR; PG8_SCHED;
;             PG8_LDB(B0, 1, 0); PG8_LDB(B1, 1, 1); PG8_SCHED; PG8_LDA(At, 1, 0); PG8_STAGE(PG8_SA(0, 1), a2 + hstepA, voffA);
;             PG8_WAIT_V(8); PG8_WAIT_L(0); PG8_BAR; PG8_MMA(0, 0, At, B0); PG8_MMA(0, 1, At, B1); PG8_BAR; PG8_SCHED;
;             PG8_LDA(At, 1, 1); PG8_STAGE(PG8_SB(1, 0), b3, voffB); PG8_STAGE(PG8_SB(1, 1), b3 + hstep, voffB); PG8_STAGE(PG8_SA(1, 0), a3, voffA);
;             PG8_WAIT_V(8); PG8_WAIT_L(0); PG8_BAR; PG8_MMA(1, 0, At, B0); PG8_MMA(1, 1, At, B1); PG8_BAR; PG8_SCHED;
	s_waitcnt lgkmcnt(0)
	v_mfma_f32_16x16x32_bf16 v[64:67], v[146:149], v[180:183], v[64:67]
	v_mfma_f32_16x16x32_bf16 v[60:63], v[156:159], v[180:183], v[60:63]
	v_mfma_f32_16x16x32_bf16 v[48:51], v[146:149], v[188:191], v[48:51]
	v_mfma_f32_16x16x32_bf16 v[44:47], v[156:159], v[188:191], v[44:47]
	v_mfma_f32_16x16x32_bf16 v[32:35], v[146:149], v[196:199], v[32:35]
	v_mfma_f32_16x16x32_bf16 v[28:31], v[156:159], v[196:199], v[28:31]
	v_mfma_f32_16x16x32_bf16 v[16:19], v[146:149], v[230:233], v[16:19]
	v_mfma_f32_16x16x32_bf16 v[12:15], v[156:159], v[230:233], v[12:15]
	v_mfma_f32_16x16x32_bf16 v[64:67], v[152:155], v[184:187], v[64:67]
	v_mfma_f32_16x16x32_bf16 v[60:63], v[160:163], v[184:187], v[60:63]
	v_mfma_f32_16x16x32_bf16 v[48:51], v[152:155], v[192:195], v[48:51]
	v_mfma_f32_16x16x32_bf16 v[44:47], v[160:163], v[192:195], v[44:47]
	v_mfma_f32_16x16x32_bf16 v[32:35], v[152:155], v[200:203], v[32:35]
	v_mfma_f32_16x16x32_bf16 v[28:31], v[160:163], v[200:203], v[28:31]
	v_mfma_f32_16x16x32_bf16 v[16:19], v[152:155], v[234:237], v[16:19]
	v_mfma_f32_16x16x32_bf16 v[12:15], v[160:163], v[234:237], v[12:15]
	v_mfma_f32_16x16x32_bf16 v[56:59], v[164:167], v[180:183], v[56:59]
	v_mfma_f32_16x16x32_bf16 v[52:55], v[172:175], v[180:183], v[52:55]
	v_mfma_f32_16x16x32_bf16 v[40:43], v[164:167], v[188:191], v[40:43]
	v_mfma_f32_16x16x32_bf16 v[36:39], v[172:175], v[188:191], v[36:39]
	v_mfma_f32_16x16x32_bf16 v[24:27], v[164:167], v[196:199], v[24:27]
	v_mfma_f32_16x16x32_bf16 v[20:23], v[172:175], v[196:199], v[20:23]
	v_mfma_f32_16x16x32_bf16 v[8:11], v[164:167], v[230:233], v[8:11]
	v_mfma_f32_16x16x32_bf16 v[4:7], v[172:175], v[230:233], v[4:7]
	v_mfma_f32_16x16x32_bf16 v[56:59], v[168:171], v[184:187], v[56:59]
	v_mfma_f32_16x16x32_bf16 v[52:55], v[176:179], v[184:187], v[52:55]
	v_mfma_f32_16x16x32_bf16 v[40:43], v[168:171], v[192:195], v[40:43]
	v_mfma_f32_16x16x32_bf16 v[36:39], v[176:179], v[192:195], v[36:39]
	v_mfma_f32_16x16x32_bf16 v[24:27], v[168:171], v[200:203], v[24:27]
	v_mfma_f32_16x16x32_bf16 v[20:23], v[176:179], v[200:203], v[20:23]
	v_mfma_f32_16x16x32_bf16 v[8:11], v[168:171], v[234:237], v[8:11]
	v_mfma_f32_16x16x32_bf16 v[4:7], v[176:179], v[234:237], v[4:7]
	s_barrier
	s_add_i32 s47, 0, 0x18000
	v_add_u32_e32 v145, s47, v143
	s_add_i32 s49, 0, 0x1c000
	ds_read_b128 v[146:149], v145
	ds_read_b128 v[152:155], v145 offset:1024
	ds_read_b128 v[156:159], v145 offset:2048
	ds_read_b128 v[160:163], v145 offset:3072
	v_add_u32_e32 v145, s49, v143
	ds_read_b128 v[164:167], v145
	ds_read_b128 v[168:171], v145 offset:1024
	ds_read_b128 v[172:175], v145 offset:2048
	ds_read_b128 v[176:179], v145 offset:3072
	s_add_u32 s8, s22, 0xb0000
	s_addc_u32 s9, s23, 0
	s_mov_b32 m0, s37
	v_lshl_add_u64 v[242:243], s[8:9], 0, v[134:135]
	ds_read_b128 v[180:183], v144 offset:32768
	ds_read_b128 v[184:187], v144 offset:33792
	ds_read_b128 v[188:191], v144 offset:34816
	ds_read_b128 v[192:195], v144 offset:35840
	ds_read_b128 v[196:199], v144 offset:36864
	ds_read_b128 v[200:203], v144 offset:37888
	ds_read_b128 v[230:233], v144 offset:38912
	ds_read_b128 v[234:237], v144 offset:39936
	global_load_lds_dwordx4 v[242:243], off
	v_lshl_add_u64 v[242:243], s[8:9], 0, v[132:133]
	s_mov_b32 m0, s41
	s_nop 0
	global_load_lds_dwordx4 v[242:243], off
	s_waitcnt vmcnt(8)
	s_waitcnt lgkmcnt(0)
	s_barrier
	s_waitcnt lgkmcnt(0)
	v_mfma_f32_16x16x32_bf16 v[128:131], v[146:149], v[180:183], v[128:131]
	v_mfma_f32_16x16x32_bf16 v[124:127], v[156:159], v[180:183], v[124:127]
	v_mfma_f32_16x16x32_bf16 v[112:115], v[146:149], v[188:191], v[112:115]
	v_mfma_f32_16x16x32_bf16 v[108:111], v[156:159], v[188:191], v[108:111]
	v_mfma_f32_16x16x32_bf16 v[96:99], v[146:149], v[196:199], v[96:99]
	v_mfma_f32_16x16x32_bf16 v[92:95], v[156:159], v[196:199], v[92:95]
	v_mfma_f32_16x16x32_bf16 v[80:83], v[146:149], v[230:233], v[80:83]
	v_mfma_f32_16x16x32_bf16 v[76:79], v[156:159], v[230:233], v[76:79]
	v_mfma_f32_16x16x32_bf16 v[128:131], v[152:155], v[184:187], v[128:131]
	v_mfma_f32_16x16x32_bf16 v[124:127], v[160:163], v[184:187], v[124:127]
	v_mfma_f32_16x16x32_bf16 v[112:115], v[152:155], v[192:195], v[112:115]
	v_mfma_f32_16x16x32_bf16 v[108:111], v[160:163], v[192:195], v[108:111]
	v_mfma_f32_16x16x32_bf16 v[96:99], v[152:155], v[200:203], v[96:99]
	v_mfma_f32_16x16x32_bf16 v[92:95], v[160:163], v[200:203], v[92:95]
	v_mfma_f32_16x16x32_bf16 v[80:83], v[152:155], v[234:237], v[80:83]
	v_mfma_f32_16x16x32_bf16 v[76:79], v[160:163], v[234:237], v[76:79]
	v_mfma_f32_16x16x32_bf16 v[120:123], v[164:167], v[180:183], v[120:123]
	v_mfma_f32_16x16x32_bf16 v[116:119], v[172:175], v[180:183], v[116:119]
	v_mfma_f32_16x16x32_bf16 v[104:107], v[164:167], v[188:191], v[104:107]
	v_mfma_f32_16x16x32_bf16 v[100:103], v[172:175], v[188:191], v[100:103]
	v_mfma_f32_16x16x32_bf16 v[88:91], v[164:167], v[196:199], v[88:91]
	v_mfma_f32_16x16x32_bf16 v[84:87], v[172:175], v[196:199], v[84:87]
	v_mfma_f32_16x16x32_bf16 v[72:75], v[164:167], v[230:233], v[72:75]
	v_mfma_f32_16x16x32_bf16 v[68:71], v[172:175], v[230:233], v[68:71]
	v_mfma_f32_16x16x32_bf16 v[120:123], v[168:171], v[184:187], v[120:123]
	v_mfma_f32_16x16x32_bf16 v[116:119], v[176:179], v[184:187], v[116:119]
	v_mfma_f32_16x16x32_bf16 v[104:107], v[168:171], v[192:195], v[104:107]
	v_mfma_f32_16x16x32_bf16 v[100:103], v[176:179], v[192:195], v[100:103]
	v_mfma_f32_16x16x32_bf16 v[88:91], v[168:171], v[200:203], v[88:91]
	v_mfma_f32_16x16x32_bf16 v[84:87], v[176:179], v[200:203], v[84:87]
	v_mfma_f32_16x16x32_bf16 v[72:75], v[168:171], v[234:237], v[72:75]
	v_mfma_f32_16x16x32_bf16 v[68:71], v[176:179], v[234:237], v[68:71]
	s_barrier
; #define PG8_STAGE(bufoff, gbase, voff) do { _Pragma("unroll") for (int _i = 0; _i < 2; ++_i) \
;         __builtin_amdgcn_global_load_lds((const unsigned*)((const char*)(gbase) + (voff)[_i]), (PG8_LAS unsigned*)(lds + (bufoff) + ldsw + _i * 8192), 16, 0, 0); } while (0)
; #define PG8_LDA(dst, b, h) do { _Pragma("unroll") for (int m = 0; m < 4; ++m) _Pragma("unroll") for (int k = 0; k < 2; ++k) dst[m][k] = *(const PG8_LAS bf16x8*)(lds + PG8_SA(b, h) + aoff + m * 2048 + k * 1024); } while (0)
; #define PG8_LDB(dst, b, h) do { _Pragma("unroll") for (int n = 0; n < 2; ++n) _Pragma("unroll") for (int k = 0; k < 2; ++k) dst[n][k] = *(const PG8_LAS bf16x8*)(lds + PG8_SB(b, h) + boff + n * 2048 + k * 1024); } while (0)
; #define PG8_MMA(ai, bj, At, Bt) do { __builtin_amdgcn_s_setprio(1); _Pragma("unroll") for (int m = 0; m < 4; ++m) _Pragma("unroll") for (int n = 0; n < 2; ++n) _Pragma("unroll") for (int k = 0; k < 2; ++k) \
;         acc[ai][bj][m][n] = __builtin_amdgcn_mfma_f32_16x16x32_bf16(Bt[n][k], At[m][k], acc[ai][bj][m][n], 0, 0, 0); __builtin_amdgcn_s_setprio(0); } while (0)
; #define PG8_BAR __builtin_amdgcn_s_barrier()
; template <class Epi, class Sched, bool APERM>
; __device__ __forceinline__ void gemm_phase(PG8_LAS unsigned char* lds, const Gemm g, const Sched& S, const Epi& E) {
;     ...
;             PG8_LDB(B0, 0, 0); PG8_LDB(B1, 0, 1); PG8_SCHED; PG8_LDA(At, 0, 0); PG8_STAGE(PG8_SA(1, 1), a1 + hstepA, voffA);
;             PG8_WAIT_V(8); PG8_WAIT_L(0); PG8_BAR; PG8_MMA(0, 0, At, B0); PG8_MMA(0, 1, At, B1); PG8_BAR; PG8_SCHED;
;             PG8_LDA(At, 0, 1); PG8_STAGE(PG8_SB(0, 0), b2, voffB); PG8_STAGE(PG8_SB(0, 1), b2 + hstep, voffB); PG8_STAGE(PG8_SA(0, 0), a2, voffA);
;             PG8_WAIT_V(8); PG8_WAIT_L(0); PG8_BAR; PG8_MMA(1, 0, At, B0); PG8_MMA(1, 1, At, B1); PG8_BAR; PG8_SCHED;
;             PG8_LDB(B0, 1, 0); PG8_LDB(B1, 1, 1); PG8_SCHED; PG8_LDA(At, 1, 0); PG8_STAGE(PG8_SA(0, 1), a2 + hstepA, voffA);
;             PG8_WAIT_V(8); PG8_WAIT_L(0); PG8_BAR; PG8_MMA(0, 0, At, B0); PG8_MMA(0, 1, At, B1); PG8_BAR; PG8_SCHED;
;             PG8_LDA(At, 1, 1); PG8_STAGE(PG8_SB(1, 0), b3, voffB); PG8_STAGE(PG8_SB(1, 1), b3 + hstep, voffB); PG8_STAGE(PG8_SA(1, 0), a3, voffA);
;             PG8_WAIT_V(8); PG8_WAIT_L(0); PG8_BAR; PG8_MMA(1, 0, At, B0); PG8_MMA(1, 1, At, B1); PG8_BAR; PG8_SCHED;
;         }
;         if (wr == 0) PG8_BAR;
	s_add_i32 s8, s47, s44
	v_lshl_add_u64 v[204:205], v[204:205], 0, s[52:53]
	s_mov_b32 m0, s8
	ds_read_b128 v[180:183], v144 offset:49152
	ds_read_b128 v[184:187], v144 offset:50176
	ds_read_b128 v[188:191], v144 offset:51200
	ds_read_b128 v[192:195], v144 offset:52224
	ds_read_b128 v[196:199], v144 offset:53248
	ds_read_b128 v[200:203], v144 offset:54272
	ds_read_b128 v[230:233], v144 offset:55296
	ds_read_b128 v[234:237], v144 offset:56320
	global_load_lds_dwordx4 v[204:205], off
	s_add_i32 m0, s8, 0x2000
	s_add_u32 s8, s20, 0xb0080
	v_lshl_add_u64 v[204:205], v[222:223], 0, s[52:53]
	s_addc_u32 s9, s21, 0
	s_add_i32 s20, s49, s44
	global_load_lds_dwordx4 v[204:205], off
	v_lshl_add_u64 v[204:205], s[8:9], 0, v[2:3]
	s_mov_b32 m0, s20
	s_nop 0
	global_load_lds_dwordx4 v[204:205], off
	v_lshl_add_u64 v[204:205], s[8:9], 0, v[0:1]
	s_add_i32 m0, s20, 0x2000
	s_nop 0
	global_load_lds_dwordx4 v[204:205], off
	v_lshl_add_u64 v[204:205], v[238:239], 0, s[52:53]
	s_mov_b32 m0, s45
	s_nop 0
	global_load_lds_dwordx4 v[204:205], off
	v_lshl_add_u64 v[204:205], v[240:241], 0, s[52:53]
	s_mov_b32 m0, s46
	s_nop 0
	global_load_lds_dwordx4 v[204:205], off
	s_waitcnt vmcnt(8)
	s_waitcnt lgkmcnt(0)
	s_barrier
	s_waitcnt lgkmcnt(0)
	v_mfma_f32_16x16x32_bf16 v[64:67], v[146:149], v[180:183], v[64:67]
	v_mfma_f32_16x16x32_bf16 v[60:63], v[156:159], v[180:183], v[60:63]
	v_mfma_f32_16x16x32_bf16 v[48:51], v[146:149], v[188:191], v[48:51]
	v_mfma_f32_16x16x32_bf16 v[44:47], v[156:159], v[188:191], v[44:47]
	v_mfma_f32_16x16x32_bf16 v[32:35], v[146:149], v[196:199], v[32:35]
	v_mfma_f32_16x16x32_bf16 v[28:31], v[156:159], v[196:199], v[28:31]
	v_mfma_f32_16x16x32_bf16 v[16:19], v[146:149], v[230:233], v[16:19]
	v_mfma_f32_16x16x32_bf16 v[12:15], v[156:159], v[230:233], v[12:15]
	v_mfma_f32_16x16x32_bf16 v[64:67], v[152:155], v[184:187], v[64:67]
	v_mfma_f32_16x16x32_bf16 v[60:63], v[160:163], v[184:187], v[60:63]
	v_mfma_f32_16x16x32_bf16 v[48:51], v[152:155], v[192:195], v[48:51]
	v_mfma_f32_16x16x32_bf16 v[44:47], v[160:163], v[192:195], v[44:47]
	v_mfma_f32_16x16x32_bf16 v[32:35], v[152:155], v[200:203], v[32:35]
	v_mfma_f32_16x16x32_bf16 v[28:31], v[160:163], v[200:203], v[28:31]
	v_mfma_f32_16x16x32_bf16 v[16:19], v[152:155], v[234:237], v[16:19]
	v_mfma_f32_16x16x32_bf16 v[12:15], v[160:163], v[234:237], v[12:15]
	v_mfma_f32_16x16x32_bf16 v[56:59], v[164:167], v[180:183], v[56:59]
	v_mfma_f32_16x16x32_bf16 v[52:55], v[172:175], v[180:183], v[52:55]
	v_mfma_f32_16x16x32_bf16 v[40:43], v[164:167], v[188:191], v[40:43]
	v_mfma_f32_16x16x32_bf16 v[36:39], v[172:175], v[188:191], v[36:39]
	v_mfma_f32_16x16x32_bf16 v[24:27], v[164:167], v[196:199], v[24:27]
	v_mfma_f32_16x16x32_bf16 v[20:23], v[172:175], v[196:199], v[20:23]
	v_mfma_f32_16x16x32_bf16 v[8:11], v[164:167], v[230:233], v[8:11]
	v_mfma_f32_16x16x32_bf16 v[4:7], v[172:175], v[230:233], v[4:7]
	v_mfma_f32_16x16x32_bf16 v[56:59], v[168:171], v[184:187], v[56:59]
	v_mfma_f32_16x16x32_bf16 v[52:55], v[176:179], v[184:187], v[52:55]
	v_mfma_f32_16x16x32_bf16 v[40:43], v[168:171], v[192:195], v[40:43]
	v_mfma_f32_16x16x32_bf16 v[36:39], v[176:179], v[192:195], v[36:39]
	v_mfma_f32_16x16x32_bf16 v[24:27], v[168:171], v[200:203], v[24:27]
	v_mfma_f32_16x16x32_bf16 v[20:23], v[176:179], v[200:203], v[20:23]
	v_mfma_f32_16x16x32_bf16 v[8:11], v[168:171], v[234:237], v[8:11]
	v_mfma_f32_16x16x32_bf16 v[4:7], v[176:179], v[234:237], v[4:7]
	s_barrier
	s_add_i32 s35, s35, 2
	s_cmp_gt_u32 s35, 7
	s_mov_b64 s[8:9], s[10:11]
	s_cbranch_scc0 .LBB0_230
	s_cmpk_lt_u32 s25, 0x100
	s_cbranch_scc0 .LBB0_233
	s_barrier

; #define PG8_STAGE(bufoff, gbase, voff) do { _Pragma("unroll") for (int _i = 0; _i < 2; ++_i) \
;         __builtin_amdgcn_global_load_lds((const unsigned*)((const char*)(gbase) + (voff)[_i]), (PG8_LAS unsigned*)(lds + (bufoff) + ldsw + _i * 8192), 16, 0, 0); } while (0)
; #define PG8_LDA(dst, b, h) do { _Pragma("unroll") for (int m = 0; m < 4; ++m) _Pragma("unroll") for (int k = 0; k < 2; ++k) dst[m][k] = *(const PG8_LAS bf16x8*)(lds + PG8_SA(b, h) + aoff + m * 2048 + k * 1024); } while (0)
; #define PG8_LDB(dst, b, h) do { _Pragma("unroll") for (int n = 0; n < 2; ++n) _Pragma("unroll") for (int k = 0; k < 2; ++k) dst[n][k] = *(const PG8_LAS bf16x8*)(lds + PG8_SB(b, h) + boff + n * 2048 + k * 1024); } while (0)
; #define PG8_BAR __builtin_amdgcn_s_barrier()
; template <class Epi, class Sched, bool APERM>
; __device__ __forceinline__ void gemm_phase(PG8_LAS unsigned char* lds, const Gemm g, const Sched& S, const Epi& E) {
;     ...
;         for (int t = 0; t < nt; t += 2) {
;             const bool last = (t == nt - 2);
;             const char* a1 = cA + (size_t)(t + 1) * kstep;
;             const char* a2 = last ? nA : cA + (size_t)(t + 2) * kstep; const char* b2 = last ? nB : cB + (size_t)(t + 2) * kstep;
;             const char* a3 = a2 + kstep; const char* b3 = b2 + kstep;
;             if (last && has_next) S.a_ready(nxt);
;             PG8_LDB(B0, 0, 0); PG8_LDB(B1, 0, 1); PG8_SCHED; PG8_LDA(At, 0, 0); PG8_STAGE(PG8_SA(1, 1), a1 + hstepA, voffA);
;             PG8_WAIT_V(8); PG8_WAIT_L(0); PG8_BAR; PG8_MMA(0, 0, At, B0); PG8_MMA(0, 1, At, B1); PG8_BAR; PG8_SCHED;
;             PG8_LDA(At, 0, 1); PG8_STAGE(PG8_SB(0, 0), b2, voffB); PG8_STAGE(PG8_SB(0, 1), b2 + hstep, voffB); PG8_STAGE(PG8_SA(0, 0), a2, voffA);
;             PG8_WAIT_V(8); PG8_WAIT_L(0); PG8_BAR; PG8_MMA(1, 0, At, B0); PG8_MMA(1, 1, At, B1); PG8_BAR; PG8_SCHED;
;             PG8_LDB(B0, 1, 0); PG8_LDB(B1, 1, 1); PG8_SCHED; PG8_LDA(At, 1, 0); PG8_STAGE(PG8_SA(0, 1), a2 + hstepA, voffA);
;             PG8_WAIT_V(8); PG8_WAIT_L(0); PG8_BAR; PG8_MMA(0, 0, At, B0); PG8_MMA(0, 1, At, B1); PG8_BAR; PG8_SCHED;
;             PG8_LDA(At, 1, 1); PG8_STAGE(PG8_SB(1, 0), b3, voffB); PG8_STAGE(PG8_SB(1, 1), b3 + hstep, voffB); PG8_STAGE(PG8_SA(1, 0), a3, voffA);
;             PG8_WAIT_V(8); PG8_WAIT_L(0); PG8_BAR; PG8_MMA(1, 0, At, B0); PG8_MMA(1, 1, At, B1); PG8_BAR; PG8_SCHED;
.LBB0_362:
	s_add_u32 s10, s40, 0x100
	s_addc_u32 s11, s41, 0
	s_add_i32 s68, 0, 0x10000
	s_cmp_eq_u32 s67, 40
	s_cselect_b32 s51, s35, s11
	s_cselect_b32 s50, s34, s10
	s_cselect_b32 s45, s37, s66
	s_cselect_b32 s44, s36, s65
	s_add_i32 s69, 0, 0x14000
	v_add_u32_e32 v152, s68, v179
	v_add_u32_e32 v168, s69, v179
	ds_read_b128 v[132:135], v152
	ds_read_b128 v[136:139], v152 offset:1024
	ds_read_b128 v[140:143], v152 offset:2048
	ds_read_b128 v[152:155], v152 offset:3072
	ds_read_b128 v[156:159], v168
	ds_read_b128 v[160:163], v168 offset:1024
	ds_read_b128 v[164:167], v168 offset:2048
	ds_read_b128 v[168:171], v168 offset:3072
	v_lshl_add_u64 v[176:177], s[40:41], 0, v[148:149]
	s_add_i32 m0, s56, 0xc000
	ds_read_b128 v[172:175], v181
	ds_read_b128 v[182:185], v181 offset:1024
	ds_read_b128 v[186:189], v181 offset:2048
	ds_read_b128 v[190:193], v181 offset:3072
	ds_read_b128 v[194:197], v181 offset:4096
	ds_read_b128 v[198:201], v181 offset:5120
	ds_read_b128 v[202:205], v181 offset:6144
	ds_read_b128 v[230:233], v181 offset:7168
	global_load_lds_dwordx4 v[176:177], off
	v_lshl_add_u64 v[176:177], s[40:41], 0, v[150:151]
	s_add_i32 m0, s56, 0xe000
	s_nop 0
	global_load_lds_dwordx4 v[176:177], off
	s_waitcnt vmcnt(8)
	s_waitcnt lgkmcnt(0)
	s_barrier
	s_waitcnt lgkmcnt(0)
	v_mfma_f32_16x16x32_bf16 v[128:131], v[132:135], v[172:175], v[128:131]
	v_mfma_f32_16x16x32_bf16 v[124:127], v[140:143], v[172:175], v[124:127]
	v_mfma_f32_16x16x32_bf16 v[112:115], v[132:135], v[186:189], v[112:115]
	v_mfma_f32_16x16x32_bf16 v[108:111], v[140:143], v[186:189], v[108:111]
	v_mfma_f32_16x16x32_bf16 v[96:99], v[132:135], v[194:197], v[96:99]
	v_mfma_f32_16x16x32_bf16 v[92:95], v[140:143], v[194:197], v[92:95]
	v_mfma_f32_16x16x32_bf16 v[80:83], v[132:135], v[202:205], v[80:83]
	v_mfma_f32_16x16x32_bf16 v[76:79], v[140:143], v[202:205], v[76:79]
	v_mfma_f32_16x16x32_bf16 v[128:131], v[136:139], v[182:185], v[128:131]
	v_mfma_f32_16x16x32_bf16 v[124:127], v[152:155], v[182:185], v[124:127]
	v_mfma_f32_16x16x32_bf16 v[112:115], v[136:139], v[190:193], v[112:115]
	v_mfma_f32_16x16x32_bf16 v[108:111], v[152:155], v[190:193], v[108:111]
	v_mfma_f32_16x16x32_bf16 v[96:99], v[136:139], v[198:201], v[96:99]
	v_mfma_f32_16x16x32_bf16 v[92:95], v[152:155], v[198:201], v[92:95]
	v_mfma_f32_16x16x32_bf16 v[80:83], v[136:139], v[230:233], v[80:83]
	v_mfma_f32_16x16x32_bf16 v[76:79], v[152:155], v[230:233], v[76:79]
	v_mfma_f32_16x16x32_bf16 v[120:123], v[156:159], v[172:175], v[120:123]
	v_mfma_f32_16x16x32_bf16 v[116:119], v[164:167], v[172:175], v[116:119]
	v_mfma_f32_16x16x32_bf16 v[104:107], v[156:159], v[186:189], v[104:107]
	v_mfma_f32_16x16x32_bf16 v[100:103], v[164:167], v[186:189], v[100:103]
	v_mfma_f32_16x16x32_bf16 v[88:91], v[156:159], v[194:197], v[88:91]
	v_mfma_f32_16x16x32_bf16 v[84:87], v[164:167], v[194:197], v[84:87]
	v_mfma_f32_16x16x32_bf16 v[72:75], v[156:159], v[202:205], v[72:75]
	v_mfma_f32_16x16x32_bf16 v[68:71], v[164:167], v[202:205], v[68:71]
	v_mfma_f32_16x16x32_bf16 v[120:123], v[160:163], v[182:185], v[120:123]
	v_mfma_f32_16x16x32_bf16 v[116:119], v[168:171], v[182:185], v[116:119]
	v_mfma_f32_16x16x32_bf16 v[104:107], v[160:163], v[190:193], v[104:107]
	v_mfma_f32_16x16x32_bf16 v[100:103], v[168:171], v[190:193], v[100:103]
	v_mfma_f32_16x16x32_bf16 v[88:91], v[160:163], v[198:201], v[88:91]
	v_mfma_f32_16x16x32_bf16 v[84:87], v[168:171], v[198:201], v[84:87]
	v_mfma_f32_16x16x32_bf16 v[72:75], v[160:163], v[230:233], v[72:75]
	v_mfma_f32_16x16x32_bf16 v[68:71], v[168:171], v[230:233], v[68:71]
	s_barrier
	s_add_i32 s40, s68, s49
	v_lshl_add_u64 v[176:177], s[44:45], 0, v[2:3]
	s_mov_b32 m0, s40
	ds_read_b128 v[172:175], v181 offset:16384
	ds_read_b128 v[182:185], v181 offset:17408
	ds_read_b128 v[186:189], v181 offset:18432
	ds_read_b128 v[190:193], v181 offset:19456
	ds_read_b128 v[194:197], v181 offset:20480
	ds_read_b128 v[198:201], v181 offset:21504
	ds_read_b128 v[202:205], v181 offset:22528
	ds_read_b128 v[230:233], v181 offset:23552
	global_load_lds_dwordx4 v[176:177], off
	s_add_i32 m0, s40, 0x2000
	s_add_u32 s40, s44, 0xb0000
	v_lshl_add_u64 v[222:223], s[44:45], 0, v[146:147]
	s_addc_u32 s41, s45, 0
	s_add_i32 s68, s69, s49
	global_load_lds_dwordx4 v[222:223], off
	v_lshl_add_u64 v[234:235], s[40:41], 0, v[2:3]
	s_mov_b32 m0, s68
	v_lshl_add_u64 v[236:237], s[50:51], 0, v[144:145]
	global_load_lds_dwordx4 v[234:235], off
	v_lshl_add_u64 v[234:235], s[40:41], 0, v[146:147]
	s_add_i32 m0, s68, 0x2000
	s_nop 0
	global_load_lds_dwordx4 v[234:235], off
	v_lshl_add_u64 v[234:235], s[50:51], 0, v[0:1]
	s_mov_b32 m0, s56
	s_nop 0
	global_load_lds_dwordx4 v[234:235], off
	s_mov_b32 m0, s57
	s_nop 0
	global_load_lds_dwordx4 v[236:237], off
	s_waitcnt vmcnt(8)
	s_waitcnt lgkmcnt(0)
	s_barrier
; #define PG8_STAGE(bufoff, gbase, voff) do { _Pragma("unroll") for (int _i = 0; _i < 2; ++_i) \
;         __builtin_amdgcn_global_load_lds((const unsigned*)((const char*)(gbase) + (voff)[_i]), (PG8_LAS unsigned*)(lds + (bufoff) + ldsw + _i * 8192), 16, 0, 0); } while (0)
; #define PG8_LDA(dst, b, h) do { _Pragma("unroll") for (int m = 0; m < 4; ++m) _Pragma("unroll") for (int k = 0; k < 2; ++k) dst[m][k] = *(const PG8_LAS bf16x8*)(lds + PG8_SA(b, h) + aoff + m * 2048 + k * 1024); } while (0)
; #define PG8_LDB(dst, b, h) do { _Pragma("unroll") for (int n = 0; n < 2; ++n) _Pragma("unroll") for (int k = 0; k < 2; ++k) dst[n][k] = *(const PG8_LAS bf16x8*)(lds + PG8_SB(b, h) + boff + n * 2048 + k * 1024); } while (0)
; #define PG8_MMA(ai, bj, At, Bt) do { __builtin_amdgcn_s_setprio(1); _Pragma("unroll") for (int m = 0; m < 4; ++m) _Pragma("unroll") for (int n = 0; n < 2; ++n) _Pragma("unroll") for (int k = 0; k < 2; ++k) \
;         acc[ai][bj][m][n] = __builtin_amdgcn_mfma_f32_16x16x32_bf16(Bt[n][k], At[m][k], acc[ai][bj][m][n], 0, 0, 0); __builtin_amdgcn_s_setprio(0); } while (0)
; #define PG8_WAIT_V(n) asm volatile("s_waitcnt vmcnt(" #n ")" ::: "memory")
; template <class Epi, class Sched, bool APERM>
; __device__ __forceinline__ void gemm_phase(PG8_LAS unsigned char* lds, const Gemm g, const Sched& S, const Epi& E) {
;     ...
;             PG8_LDB(B0, 0, 0); PG8_LDB(B1, 0, 1); PG8_SCHED; PG8_LDA(At, 0, 0); PG8_STAGE(PG8_SA(1, 1), a1 + hstepA, voffA);
;             PG8_WAIT_V(8); PG8_WAIT_L(0); PG8_BAR; PG8_MMA(0, 0, At, B0); PG8_MMA(0, 1, At, B1); PG8_BAR; PG8_SCHED;
;             PG8_LDA(At, 0, 1); PG8_STAGE(PG8_SB(0, 0), b2, voffB); PG8_STAGE(PG8_SB(0, 1), b2 + hstep, voffB); PG8_STAGE(PG8_SA(0, 0), a2, voffA);
;             PG8_WAIT_V(8); PG8_WAIT_L(0); PG8_BAR; PG8_MMA(1, 0, At, B0); PG8_MMA(1, 1, At, B1); PG8_BAR; PG8_SCHED;
;             PG8_LDB(B0, 1, 0); PG8_LDB(B1, 1, 1); PG8_SCHED; PG8_LDA(At, 1, 0); PG8_STAGE(PG8_SA(0, 1), a2 + hstepA, voffA);
;             PG8_WAIT_V(8); PG8_WAIT_L(0); PG8_BAR; PG8_MMA(0, 0, At, B0); PG8_MMA(0, 1, At, B1); PG8_BAR; PG8_SCHED;
;             PG8_LDA(At, 1, 1); PG8_STAGE(PG8_SB(1, 0), b3, voffB); PG8_STAGE(PG8_SB(1, 1), b3 + hstep, voffB); PG8_STAGE(PG8_SA(1, 0), a3, voffA);
;             PG8_WAIT_V(8); PG8_WAIT_L(0); PG8_BAR; PG8_MMA(1, 0, At, B0); PG8_MMA(1, 1, At, B1); PG8_BAR; PG8_SCHED;
	s_waitcnt lgkmcnt(0)
	v_mfma_f32_16x16x32_bf16 v[64:67], v[132:135], v[172:175], v[64:67]
	v_mfma_f32_16x16x32_bf16 v[60:63], v[140:143], v[172:175], v[60:63]
	v_mfma_f32_16x16x32_bf16 v[48:51], v[132:135], v[186:189], v[48:51]
	v_mfma_f32_16x16x32_bf16 v[44:47], v[140:143], v[186:189], v[44:47]
	v_mfma_f32_16x16x32_bf16 v[32:35], v[132:135], v[194:197], v[32:35]
	v_mfma_f32_16x16x32_bf16 v[28:31], v[140:143], v[194:197], v[28:31]
	v_mfma_f32_16x16x32_bf16 v[16:19], v[132:135], v[202:205], v[16:19]
	v_mfma_f32_16x16x32_bf16 v[12:15], v[140:143], v[202:205], v[12:15]
	v_mfma_f32_16x16x32_bf16 v[64:67], v[136:139], v[182:185], v[64:67]
	v_mfma_f32_16x16x32_bf16 v[60:63], v[152:155], v[182:185], v[60:63]
	v_mfma_f32_16x16x32_bf16 v[48:51], v[136:139], v[190:193], v[48:51]
	v_mfma_f32_16x16x32_bf16 v[44:47], v[152:155], v[190:193], v[44:47]
	v_mfma_f32_16x16x32_bf16 v[32:35], v[136:139], v[198:201], v[32:35]
	v_mfma_f32_16x16x32_bf16 v[28:31], v[152:155], v[198:201], v[28:31]
	v_mfma_f32_16x16x32_bf16 v[16:19], v[136:139], v[230:233], v[16:19]
	v_mfma_f32_16x16x32_bf16 v[12:15], v[152:155], v[230:233], v[12:15]
	v_mfma_f32_16x16x32_bf16 v[56:59], v[156:159], v[172:175], v[56:59]
	v_mfma_f32_16x16x32_bf16 v[52:55], v[164:167], v[172:175], v[52:55]
	v_mfma_f32_16x16x32_bf16 v[40:43], v[156:159], v[186:189], v[40:43]
	v_mfma_f32_16x16x32_bf16 v[36:39], v[164:167], v[186:189], v[36:39]
	v_mfma_f32_16x16x32_bf16 v[24:27], v[156:159], v[194:197], v[24:27]
	v_mfma_f32_16x16x32_bf16 v[20:23], v[164:167], v[194:197], v[20:23]
	v_mfma_f32_16x16x32_bf16 v[8:11], v[156:159], v[202:205], v[8:11]
	v_mfma_f32_16x16x32_bf16 v[4:7], v[164:167], v[202:205], v[4:7]
	v_mfma_f32_16x16x32_bf16 v[56:59], v[160:163], v[182:185], v[56:59]
	v_mfma_f32_16x16x32_bf16 v[52:55], v[168:171], v[182:185], v[52:55]
	v_mfma_f32_16x16x32_bf16 v[40:43], v[160:163], v[190:193], v[40:43]
	v_mfma_f32_16x16x32_bf16 v[36:39], v[168:171], v[190:193], v[36:39]
	v_mfma_f32_16x16x32_bf16 v[24:27], v[160:163], v[198:201], v[24:27]
	v_mfma_f32_16x16x32_bf16 v[20:23], v[168:171], v[198:201], v[20:23]
	v_mfma_f32_16x16x32_bf16 v[8:11], v[160:163], v[230:233], v[8:11]
	v_mfma_f32_16x16x32_bf16 v[4:7], v[168:171], v[230:233], v[4:7]
	s_barrier
	s_add_i32 s68, 0, 0x18000
	s_add_i32 s69, 0, 0x1c000
	v_add_u32_e32 v152, s68, v179
	v_add_u32_e32 v168, s69, v179
	ds_read_b128 v[132:135], v152
	ds_read_b128 v[136:139], v152 offset:1024
	ds_read_b128 v[140:143], v152 offset:2048
	ds_read_b128 v[152:155], v152 offset:3072
	ds_read_b128 v[156:159], v168
	ds_read_b128 v[160:163], v168 offset:1024
	ds_read_b128 v[164:167], v168 offset:2048
	ds_read_b128 v[168:171], v168 offset:3072
	s_add_u32 s40, s50, 0xb0000
	s_addc_u32 s41, s51, 0
	s_mov_b32 m0, s58
	v_lshl_add_u64 v[238:239], s[40:41], 0, v[0:1]
	ds_read_b128 v[172:175], v181 offset:32768
	ds_read_b128 v[182:185], v181 offset:33792
	ds_read_b128 v[186:189], v181 offset:34816
	ds_read_b128 v[190:193], v181 offset:35840
	ds_read_b128 v[194:197], v181 offset:36864
	ds_read_b128 v[198:201], v181 offset:37888
	ds_read_b128 v[202:205], v181 offset:38912
	ds_read_b128 v[230:233], v181 offset:39936
	global_load_lds_dwordx4 v[238:239], off
	v_lshl_add_u64 v[238:239], s[40:41], 0, v[144:145]
	s_mov_b32 m0, s59
	s_nop 0
	global_load_lds_dwordx4 v[238:239], off
	s_waitcnt vmcnt(8)
	s_waitcnt lgkmcnt(0)
	s_barrier
	s_waitcnt lgkmcnt(0)
	v_mfma_f32_16x16x32_bf16 v[128:131], v[132:135], v[172:175], v[128:131]
	v_mfma_f32_16x16x32_bf16 v[124:127], v[140:143], v[172:175], v[124:127]
	v_mfma_f32_16x16x32_bf16 v[112:115], v[132:135], v[186:189], v[112:115]
	v_mfma_f32_16x16x32_bf16 v[108:111], v[140:143], v[186:189], v[108:111]
	v_mfma_f32_16x16x32_bf16 v[96:99], v[132:135], v[194:197], v[96:99]
	v_mfma_f32_16x16x32_bf16 v[92:95], v[140:143], v[194:197], v[92:95]
	v_mfma_f32_16x16x32_bf16 v[80:83], v[132:135], v[202:205], v[80:83]
	v_mfma_f32_16x16x32_bf16 v[76:79], v[140:143], v[202:205], v[76:79]
	v_mfma_f32_16x16x32_bf16 v[128:131], v[136:139], v[182:185], v[128:131]
	v_mfma_f32_16x16x32_bf16 v[124:127], v[152:155], v[182:185], v[124:127]
	v_mfma_f32_16x16x32_bf16 v[112:115], v[136:139], v[190:193], v[112:115]
	v_mfma_f32_16x16x32_bf16 v[108:111], v[152:155], v[190:193], v[108:111]
	v_mfma_f32_16x16x32_bf16 v[96:99], v[136:139], v[198:201], v[96:99]
	v_mfma_f32_16x16x32_bf16 v[92:95], v[152:155], v[198:201], v[92:95]
	v_mfma_f32_16x16x32_bf16 v[80:83], v[136:139], v[230:233], v[80:83]
	v_mfma_f32_16x16x32_bf16 v[76:79], v[152:155], v[230:233], v[76:79]
	v_mfma_f32_16x16x32_bf16 v[120:123], v[156:159], v[172:175], v[120:123]
	v_mfma_f32_16x16x32_bf16 v[116:119], v[164:167], v[172:175], v[116:119]
	v_mfma_f32_16x16x32_bf16 v[104:107], v[156:159], v[186:189], v[104:107]
	v_mfma_f32_16x16x32_bf16 v[100:103], v[164:167], v[186:189], v[100:103]
	v_mfma_f32_16x16x32_bf16 v[88:91], v[156:159], v[194:197], v[88:91]
	v_mfma_f32_16x16x32_bf16 v[84:87], v[164:167], v[194:197], v[84:87]
	v_mfma_f32_16x16x32_bf16 v[72:75], v[156:159], v[202:205], v[72:75]
	v_mfma_f32_16x16x32_bf16 v[68:71], v[164:167], v[202:205], v[68:71]
	v_mfma_f32_16x16x32_bf16 v[120:123], v[160:163], v[182:185], v[120:123]
	v_mfma_f32_16x16x32_bf16 v[116:119], v[168:171], v[182:185], v[116:119]
	v_mfma_f32_16x16x32_bf16 v[104:107], v[160:163], v[190:193], v[104:107]
	v_mfma_f32_16x16x32_bf16 v[100:103], v[168:171], v[190:193], v[100:103]
	v_mfma_f32_16x16x32_bf16 v[88:91], v[160:163], v[198:201], v[88:91]
	v_mfma_f32_16x16x32_bf16 v[84:87], v[168:171], v[198:201], v[84:87]
	v_mfma_f32_16x16x32_bf16 v[72:75], v[160:163], v[230:233], v[72:75]
	v_mfma_f32_16x16x32_bf16 v[68:71], v[168:171], v[230:233], v[68:71]
	s_barrier
; #define PG8_STAGE(bufoff, gbase, voff) do { _Pragma("unroll") for (int _i = 0; _i < 2; ++_i) \
;         __builtin_amdgcn_global_load_lds((const unsigned*)((const char*)(gbase) + (voff)[_i]), (PG8_LAS unsigned*)(lds + (bufoff) + ldsw + _i * 8192), 16, 0, 0); } while (0)
; #define PG8_LDA(dst, b, h) do { _Pragma("unroll") for (int m = 0; m < 4; ++m) _Pragma("unroll") for (int k = 0; k < 2; ++k) dst[m][k] = *(const PG8_LAS bf16x8*)(lds + PG8_SA(b, h) + aoff + m * 2048 + k * 1024); } while (0)
; #define PG8_LDB(dst, b, h) do { _Pragma("unroll") for (int n = 0; n < 2; ++n) _Pragma("unroll") for (int k = 0; k < 2; ++k) dst[n][k] = *(const PG8_LAS bf16x8*)(lds + PG8_SB(b, h) + boff + n * 2048 + k * 1024); } while (0)
; #define PG8_MMA(ai, bj, At, Bt) do { __builtin_amdgcn_s_setprio(1); _Pragma("unroll") for (int m = 0; m < 4; ++m) _Pragma("unroll") for (int n = 0; n < 2; ++n) _Pragma("unroll") for (int k = 0; k < 2; ++k) \
;         acc[ai][bj][m][n] = __builtin_amdgcn_mfma_f32_16x16x32_bf16(Bt[n][k], At[m][k], acc[ai][bj][m][n], 0, 0, 0); __builtin_amdgcn_s_setprio(0); } while (0)
; #define PG8_WAIT_V(n) asm volatile("s_waitcnt vmcnt(" #n ")" ::: "memory")
; template <class Epi, class Sched, bool APERM>
; __device__ __forceinline__ void gemm_phase(PG8_LAS unsigned char* lds, const Gemm g, const Sched& S, const Epi& E) {
;     ...
;             PG8_LDB(B0, 0, 0); PG8_LDB(B1, 0, 1); PG8_SCHED; PG8_LDA(At, 0, 0); PG8_STAGE(PG8_SA(1, 1), a1 + hstepA, voffA);
;             PG8_WAIT_V(8); PG8_WAIT_L(0); PG8_BAR; PG8_MMA(0, 0, At, B0); PG8_MMA(0, 1, At, B1); PG8_BAR; PG8_SCHED;
;             PG8_LDA(At, 0, 1); PG8_STAGE(PG8_SB(0, 0), b2, voffB); PG8_STAGE(PG8_SB(0, 1), b2 + hstep, voffB); PG8_STAGE(PG8_SA(0, 0), a2, voffA);
;             PG8_WAIT_V(8); PG8_WAIT_L(0); PG8_BAR; PG8_MMA(1, 0, At, B0); PG8_MMA(1, 1, At, B1); PG8_BAR; PG8_SCHED;
;             PG8_LDB(B0, 1, 0); PG8_LDB(B1, 1, 1); PG8_SCHED; PG8_LDA(At, 1, 0); PG8_STAGE(PG8_SA(0, 1), a2 + hstepA, voffA);
;             PG8_WAIT_V(8); PG8_WAIT_L(0); PG8_BAR; PG8_MMA(0, 0, At, B0); PG8_MMA(0, 1, At, B1); PG8_BAR; PG8_SCHED;
;             PG8_LDA(At, 1, 1); PG8_STAGE(PG8_SB(1, 0), b3, voffB); PG8_STAGE(PG8_SB(1, 1), b3 + hstep, voffB); PG8_STAGE(PG8_SA(1, 0), a3, voffA);
;             PG8_WAIT_V(8); PG8_WAIT_L(0); PG8_BAR; PG8_MMA(1, 0, At, B0); PG8_MMA(1, 1, At, B1); PG8_BAR; PG8_SCHED;
	s_add_i32 s40, s68, s49
	v_lshl_add_u64 v[176:177], v[176:177], 0, s[52:53]
	s_mov_b32 m0, s40
	ds_read_b128 v[172:175], v181 offset:49152
	ds_read_b128 v[182:185], v181 offset:50176
	ds_read_b128 v[186:189], v181 offset:51200
	ds_read_b128 v[190:193], v181 offset:52224
	ds_read_b128 v[194:197], v181 offset:53248
	ds_read_b128 v[198:201], v181 offset:54272
	ds_read_b128 v[202:205], v181 offset:55296
	ds_read_b128 v[230:233], v181 offset:56320
	global_load_lds_dwordx4 v[176:177], off
	s_add_i32 m0, s40, 0x2000
	s_add_u32 s40, s44, 0xb0080
	v_lshl_add_u64 v[176:177], v[222:223], 0, s[52:53]
	s_addc_u32 s41, s45, 0
	s_add_i32 s44, s69, s49
	global_load_lds_dwordx4 v[176:177], off
	v_lshl_add_u64 v[176:177], s[40:41], 0, v[2:3]
	s_mov_b32 m0, s44
	s_nop 0
	global_load_lds_dwordx4 v[176:177], off
	v_lshl_add_u64 v[176:177], s[40:41], 0, v[146:147]
	s_add_i32 m0, s44, 0x2000
	s_nop 0
	global_load_lds_dwordx4 v[176:177], off
	v_lshl_add_u64 v[176:177], v[234:235], 0, s[52:53]
	s_mov_b32 m0, s60
	s_nop 0
	global_load_lds_dwordx4 v[176:177], off
	v_lshl_add_u64 v[176:177], v[236:237], 0, s[52:53]
	s_mov_b32 m0, s61
	s_nop 0
	global_load_lds_dwordx4 v[176:177], off
	s_waitcnt vmcnt(8)
	s_waitcnt lgkmcnt(0)
	s_barrier
	s_waitcnt lgkmcnt(0)
	v_mfma_f32_16x16x32_bf16 v[64:67], v[132:135], v[172:175], v[64:67]
	v_mfma_f32_16x16x32_bf16 v[60:63], v[140:143], v[172:175], v[60:63]
	v_mfma_f32_16x16x32_bf16 v[48:51], v[132:135], v[186:189], v[48:51]
	v_mfma_f32_16x16x32_bf16 v[44:47], v[140:143], v[186:189], v[44:47]
	v_mfma_f32_16x16x32_bf16 v[32:35], v[132:135], v[194:197], v[32:35]
	v_mfma_f32_16x16x32_bf16 v[28:31], v[140:143], v[194:197], v[28:31]
	v_mfma_f32_16x16x32_bf16 v[16:19], v[132:135], v[202:205], v[16:19]
	v_mfma_f32_16x16x32_bf16 v[12:15], v[140:143], v[202:205], v[12:15]
	v_mfma_f32_16x16x32_bf16 v[64:67], v[136:139], v[182:185], v[64:67]
	v_mfma_f32_16x16x32_bf16 v[60:63], v[152:155], v[182:185], v[60:63]
	v_mfma_f32_16x16x32_bf16 v[48:51], v[136:139], v[190:193], v[48:51]
	v_mfma_f32_16x16x32_bf16 v[44:47], v[152:155], v[190:193], v[44:47]
	v_mfma_f32_16x16x32_bf16 v[32:35], v[136:139], v[198:201], v[32:35]
	v_mfma_f32_16x16x32_bf16 v[28:31], v[152:155], v[198:201], v[28:31]
	v_mfma_f32_16x16x32_bf16 v[16:19], v[136:139], v[230:233], v[16:19]
	v_mfma_f32_16x16x32_bf16 v[12:15], v[152:155], v[230:233], v[12:15]
	v_mfma_f32_16x16x32_bf16 v[56:59], v[156:159], v[172:175], v[56:59]
	v_mfma_f32_16x16x32_bf16 v[52:55], v[164:167], v[172:175], v[52:55]
	v_mfma_f32_16x16x32_bf16 v[40:43], v[156:159], v[186:189], v[40:43]
	v_mfma_f32_16x16x32_bf16 v[36:39], v[164:167], v[186:189], v[36:39]
	v_mfma_f32_16x16x32_bf16 v[24:27], v[156:159], v[194:197], v[24:27]
	v_mfma_f32_16x16x32_bf16 v[20:23], v[164:167], v[194:197], v[20:23]
	v_mfma_f32_16x16x32_bf16 v[8:11], v[156:159], v[202:205], v[8:11]
	v_mfma_f32_16x16x32_bf16 v[4:7], v[164:167], v[202:205], v[4:7]
	v_mfma_f32_16x16x32_bf16 v[56:59], v[160:163], v[182:185], v[56:59]
	v_mfma_f32_16x16x32_bf16 v[52:55], v[168:171], v[182:185], v[52:55]
	v_mfma_f32_16x16x32_bf16 v[40:43], v[160:163], v[190:193], v[40:43]
	v_mfma_f32_16x16x32_bf16 v[36:39], v[168:171], v[190:193], v[36:39]
	v_mfma_f32_16x16x32_bf16 v[24:27], v[160:163], v[198:201], v[24:27]
	v_mfma_f32_16x16x32_bf16 v[20:23], v[168:171], v[198:201], v[20:23]
	v_mfma_f32_16x16x32_bf16 v[8:11], v[160:163], v[230:233], v[8:11]
	v_mfma_f32_16x16x32_bf16 v[4:7], v[168:171], v[230:233], v[4:7]
	s_barrier
	s_add_i32 s67, s67, 2
	s_add_u32 s65, s65, 0x100
	s_addc_u32 s66, s66, 0
	s_cmp_gt_u32 s67, 41
	s_mov_b64 s[40:41], s[10:11]
	s_cbranch_scc0 .LBB0_362
	s_and_b64 vcc, exec, s[24:25]
	s_cbranch_vccz .LBB0_365
	s_barrier

; #define PG8_STAGE(bufoff, gbase, voff) do { _Pragma("unroll") for (int _i = 0; _i < 2; ++_i) \
;         __builtin_amdgcn_global_load_lds((const unsigned*)((const char*)(gbase) + (voff)[_i]), (PG8_LAS unsigned*)(lds + (bufoff) + ldsw + _i * 8192), 16, 0, 0); } while (0)
; #define PG8_LDA(dst, b, h) do { _Pragma("unroll") for (int m = 0; m < 4; ++m) _Pragma("unroll") for (int k = 0; k < 2; ++k) dst[m][k] = *(const PG8_LAS bf16x8*)(lds + PG8_SA(b, h) + aoff + m * 2048 + k * 1024); } while (0)
; #define PG8_LDB(dst, b, h) do { _Pragma("unroll") for (int n = 0; n < 2; ++n) _Pragma("unroll") for (int k = 0; k < 2; ++k) dst[n][k] = *(const PG8_LAS bf16x8*)(lds + PG8_SB(b, h) + boff + n * 2048 + k * 1024); } while (0)
; #define PG8_BAR __builtin_amdgcn_s_barrier()
; template <class Epi, class Sched, bool APERM>
; __device__ __forceinline__ void gemm_phase(PG8_LAS unsigned char* lds, const Gemm g, const Sched& S, const Epi& E) {
;     ...
;         for (int t = 0; t < nt; t += 2) {
;             const bool last = (t == nt - 2);
;             const char* a1 = cA + (size_t)(t + 1) * kstep;
;             const char* a2 = last ? nA : cA + (size_t)(t + 2) * kstep; const char* b2 = last ? nB : cB + (size_t)(t + 2) * kstep;
;             const char* a3 = a2 + kstep; const char* b3 = b2 + kstep;
;             if (last && has_next) S.a_ready(nxt);
;             PG8_LDB(B0, 0, 0); PG8_LDB(B1, 0, 1); PG8_SCHED; PG8_LDA(At, 0, 0); PG8_STAGE(PG8_SA(1, 1), a1 + hstepA, voffA);
;             PG8_WAIT_V(8); PG8_WAIT_L(0); PG8_BAR; PG8_MMA(0, 0, At, B0); PG8_MMA(0, 1, At, B1); PG8_BAR; PG8_SCHED;
;             PG8_LDA(At, 0, 1); PG8_STAGE(PG8_SB(0, 0), b2, voffB); PG8_STAGE(PG8_SB(0, 1), b2 + hstep, voffB); PG8_STAGE(PG8_SA(0, 0), a2, voffA);
;             PG8_WAIT_V(8); PG8_WAIT_L(0); PG8_BAR; PG8_MMA(1, 0, At, B0); PG8_MMA(1, 1, At, B1); PG8_BAR; PG8_SCHED;
;             PG8_LDB(B0, 1, 0); PG8_LDB(B1, 1, 1); PG8_SCHED; PG8_LDA(At, 1, 0); PG8_STAGE(PG8_SA(0, 1), a2 + hstepA, voffA);
;             PG8_WAIT_V(8); PG8_WAIT_L(0); PG8_BAR; PG8_MMA(0, 0, At, B0); PG8_MMA(0, 1, At, B1); PG8_BAR; PG8_SCHED;
;             PG8_LDA(At, 1, 1); PG8_STAGE(PG8_SB(1, 0), b3, voffB); PG8_STAGE(PG8_SB(1, 1), b3 + hstep, voffB); PG8_STAGE(PG8_SA(1, 0), a3, voffA);
;             PG8_WAIT_V(8); PG8_WAIT_L(0); PG8_BAR; PG8_MMA(1, 0, At, B0); PG8_MMA(1, 1, At, B1); PG8_BAR; PG8_SCHED;
.LBB0_470:
	s_add_u32 s12, s10, 0x100
	s_addc_u32 s13, s11, 0
	s_add_i32 s71, 0, 0x10000
	s_cmp_eq_u32 s70, 12
	s_cselect_b32 s47, s1, s13
	s_cselect_b32 s46, s45, s12
	s_cselect_b32 vcc_hi, s21, s69
	s_cselect_b32 vcc_lo, s67, s68
	s_add_i32 s76, 0, 0x14000
	v_add_u32_e32 v24, s71, v230
	v_add_u32_e32 v160, s76, v230
	ds_read_b128 v[4:7], v24
	ds_read_b128 v[8:11], v24 offset:1024
	ds_read_b128 v[12:15], v24 offset:2048
	ds_read_b128 v[24:27], v24 offset:3072
	ds_read_b128 v[28:31], v160
	ds_read_b128 v[36:39], v160 offset:1024
	ds_read_b128 v[140:143], v160 offset:2048
	ds_read_b128 v[160:163], v160 offset:3072
	v_lshl_add_u64 v[204:205], s[10:11], 0, v[184:185]
	s_add_i32 m0, s97, 0xc000
	ds_read_b128 v[164:167], v234
	ds_read_b128 v[168:171], v234 offset:1024
	ds_read_b128 v[172:175], v234 offset:2048
	ds_read_b128 v[176:179], v234 offset:3072
	ds_read_b128 v[188:191], v234 offset:4096
	ds_read_b128 v[192:195], v234 offset:5120
	ds_read_b128 v[196:199], v234 offset:6144
	ds_read_b128 v[200:203], v234 offset:7168
	global_load_lds_dwordx4 v[204:205], off
	v_lshl_add_u64 v[204:205], s[10:11], 0, v[186:187]
	s_add_i32 m0, s97, 0xe000
	s_nop 0
	global_load_lds_dwordx4 v[204:205], off
	s_waitcnt vmcnt(8)
	s_waitcnt lgkmcnt(0)
	s_barrier
	s_waitcnt lgkmcnt(0)
	v_mfma_f32_16x16x32_bf16 v[152:155], v[4:7], v[164:167], v[152:155]
	v_mfma_f32_16x16x32_bf16 v[148:151], v[12:15], v[164:167], v[148:151]
	v_mfma_f32_16x16x32_bf16 v[136:139], v[4:7], v[172:175], v[136:139]
	v_mfma_f32_16x16x32_bf16 v[128:131], v[12:15], v[172:175], v[128:131]
	v_mfma_f32_16x16x32_bf16 v[120:123], v[4:7], v[188:191], v[120:123]
	v_mfma_f32_16x16x32_bf16 v[116:119], v[12:15], v[188:191], v[116:119]
	v_mfma_f32_16x16x32_bf16 v[104:107], v[4:7], v[196:199], v[104:107]
	v_mfma_f32_16x16x32_bf16 v[100:103], v[12:15], v[196:199], v[100:103]
	v_mfma_f32_16x16x32_bf16 v[152:155], v[8:11], v[168:171], v[152:155]
	v_mfma_f32_16x16x32_bf16 v[148:151], v[24:27], v[168:171], v[148:151]
	v_mfma_f32_16x16x32_bf16 v[136:139], v[8:11], v[176:179], v[136:139]
	v_mfma_f32_16x16x32_bf16 v[128:131], v[24:27], v[176:179], v[128:131]
	v_mfma_f32_16x16x32_bf16 v[120:123], v[8:11], v[192:195], v[120:123]
	v_mfma_f32_16x16x32_bf16 v[116:119], v[24:27], v[192:195], v[116:119]
	v_mfma_f32_16x16x32_bf16 v[104:107], v[8:11], v[200:203], v[104:107]
	v_mfma_f32_16x16x32_bf16 v[100:103], v[24:27], v[200:203], v[100:103]
	v_mfma_f32_16x16x32_bf16 v[156:159], v[28:31], v[164:167], v[156:159]
	v_mfma_f32_16x16x32_bf16 v[144:147], v[140:143], v[164:167], v[144:147]
	v_mfma_f32_16x16x32_bf16 v[132:135], v[28:31], v[172:175], v[132:135]
	v_mfma_f32_16x16x32_bf16 v[124:127], v[140:143], v[172:175], v[124:127]
	v_mfma_f32_16x16x32_bf16 v[112:115], v[28:31], v[188:191], v[112:115]
	v_mfma_f32_16x16x32_bf16 v[108:111], v[140:143], v[188:191], v[108:111]
	v_mfma_f32_16x16x32_bf16 v[96:99], v[28:31], v[196:199], v[96:99]
	v_mfma_f32_16x16x32_bf16 v[92:95], v[140:143], v[196:199], v[92:95]
	v_mfma_f32_16x16x32_bf16 v[156:159], v[36:39], v[168:171], v[156:159]
	v_mfma_f32_16x16x32_bf16 v[144:147], v[160:163], v[168:171], v[144:147]
	v_mfma_f32_16x16x32_bf16 v[132:135], v[36:39], v[176:179], v[132:135]
	v_mfma_f32_16x16x32_bf16 v[124:127], v[160:163], v[176:179], v[124:127]
	v_mfma_f32_16x16x32_bf16 v[112:115], v[36:39], v[192:195], v[112:115]
	v_mfma_f32_16x16x32_bf16 v[108:111], v[160:163], v[192:195], v[108:111]
	v_mfma_f32_16x16x32_bf16 v[96:99], v[36:39], v[200:203], v[96:99]
	v_mfma_f32_16x16x32_bf16 v[92:95], v[160:163], v[200:203], v[92:95]
	s_barrier
	s_add_i32 s10, s71, s72
	v_lshl_add_u64 v[204:205], vcc, 0, v[2:3]
	s_mov_b32 m0, s10
	ds_read_b128 v[164:167], v234 offset:16384
	ds_read_b128 v[168:171], v234 offset:17408
	ds_read_b128 v[172:175], v234 offset:18432
	ds_read_b128 v[176:179], v234 offset:19456
	ds_read_b128 v[188:191], v234 offset:20480
	ds_read_b128 v[192:195], v234 offset:21504
	ds_read_b128 v[196:199], v234 offset:22528
	ds_read_b128 v[200:203], v234 offset:23552
	global_load_lds_dwordx4 v[204:205], off
	s_add_i32 m0, s10, 0x2000
	s_add_u32 s10, vcc_lo, 0x40000
	v_lshl_add_u64 v[222:223], vcc, 0, v[182:183]
	s_addc_u32 s11, vcc_hi, 0
	s_add_i32 s71, s76, s72
	global_load_lds_dwordx4 v[222:223], off
	v_lshl_add_u64 v[236:237], s[10:11], 0, v[2:3]
	s_mov_b32 m0, s71
	v_lshl_add_u64 v[240:241], s[46:47], 0, v[0:1]
	global_load_lds_dwordx4 v[236:237], off
	v_lshl_add_u64 v[236:237], s[10:11], 0, v[182:183]
	s_add_i32 m0, s71, 0x2000
	v_lshl_add_u64 v[242:243], s[46:47], 0, v[180:181]
	global_load_lds_dwordx4 v[236:237], off
	s_mov_b32 m0, s97
	s_nop 0
	global_load_lds_dwordx4 v[240:241], off
	s_mov_b32 m0, s56
	s_nop 0
	global_load_lds_dwordx4 v[242:243], off
	s_waitcnt vmcnt(8)
	s_waitcnt lgkmcnt(0)
	s_barrier
; #define PG8_STAGE(bufoff, gbase, voff) do { _Pragma("unroll") for (int _i = 0; _i < 2; ++_i) \
;         __builtin_amdgcn_global_load_lds((const unsigned*)((const char*)(gbase) + (voff)[_i]), (PG8_LAS unsigned*)(lds + (bufoff) + ldsw + _i * 8192), 16, 0, 0); } while (0)
; #define PG8_LDA(dst, b, h) do { _Pragma("unroll") for (int m = 0; m < 4; ++m) _Pragma("unroll") for (int k = 0; k < 2; ++k) dst[m][k] = *(const PG8_LAS bf16x8*)(lds + PG8_SA(b, h) + aoff + m * 2048 + k * 1024); } while (0)
; #define PG8_LDB(dst, b, h) do { _Pragma("unroll") for (int n = 0; n < 2; ++n) _Pragma("unroll") for (int k = 0; k < 2; ++k) dst[n][k] = *(const PG8_LAS bf16x8*)(lds + PG8_SB(b, h) + boff + n * 2048 + k * 1024); } while (0)
; #define PG8_MMA(ai, bj, At, Bt) do { __builtin_amdgcn_s_setprio(1); _Pragma("unroll") for (int m = 0; m < 4; ++m) _Pragma("unroll") for (int n = 0; n < 2; ++n) _Pragma("unroll") for (int k = 0; k < 2; ++k) \
;         acc[ai][bj][m][n] = __builtin_amdgcn_mfma_f32_16x16x32_bf16(Bt[n][k], At[m][k], acc[ai][bj][m][n], 0, 0, 0); __builtin_amdgcn_s_setprio(0); } while (0)
; #define PG8_WAIT_V(n) asm volatile("s_waitcnt vmcnt(" #n ")" ::: "memory")
; template <class Epi, class Sched, bool APERM>
; __device__ __forceinline__ void gemm_phase(PG8_LAS unsigned char* lds, const Gemm g, const Sched& S, const Epi& E) {
;     ...
;             PG8_LDB(B0, 0, 0); PG8_LDB(B1, 0, 1); PG8_SCHED; PG8_LDA(At, 0, 0); PG8_STAGE(PG8_SA(1, 1), a1 + hstepA, voffA);
;             PG8_WAIT_V(8); PG8_WAIT_L(0); PG8_BAR; PG8_MMA(0, 0, At, B0); PG8_MMA(0, 1, At, B1); PG8_BAR; PG8_SCHED;
;             PG8_LDA(At, 0, 1); PG8_STAGE(PG8_SB(0, 0), b2, voffB); PG8_STAGE(PG8_SB(0, 1), b2 + hstep, voffB); PG8_STAGE(PG8_SA(0, 0), a2, voffA);
;             PG8_WAIT_V(8); PG8_WAIT_L(0); PG8_BAR; PG8_MMA(1, 0, At, B0); PG8_MMA(1, 1, At, B1); PG8_BAR; PG8_SCHED;
;             PG8_LDB(B0, 1, 0); PG8_LDB(B1, 1, 1); PG8_SCHED; PG8_LDA(At, 1, 0); PG8_STAGE(PG8_SA(0, 1), a2 + hstepA, voffA);
;             PG8_WAIT_V(8); PG8_WAIT_L(0); PG8_BAR; PG8_MMA(0, 0, At, B0); PG8_MMA(0, 1, At, B1); PG8_BAR; PG8_SCHED;
;             PG8_LDA(At, 1, 1); PG8_STAGE(PG8_SB(1, 0), b3, voffB); PG8_STAGE(PG8_SB(1, 1), b3 + hstep, voffB); PG8_STAGE(PG8_SA(1, 0), a3, voffA);
;             PG8_WAIT_V(8); PG8_WAIT_L(0); PG8_BAR; PG8_MMA(1, 0, At, B0); PG8_MMA(1, 1, At, B1); PG8_BAR; PG8_SCHED;
	s_waitcnt lgkmcnt(0)
	v_mfma_f32_16x16x32_bf16 v[88:91], v[4:7], v[164:167], v[88:91]
	v_mfma_f32_16x16x32_bf16 v[84:87], v[12:15], v[164:167], v[84:87]
	v_mfma_f32_16x16x32_bf16 v[72:75], v[4:7], v[172:175], v[72:75]
	v_mfma_f32_16x16x32_bf16 v[68:71], v[12:15], v[172:175], v[68:71]
	v_mfma_f32_16x16x32_bf16 v[20:23], v[4:7], v[188:191], v[20:23]
	v_mfma_f32_16x16x32_bf16 v[32:35], v[12:15], v[188:191], v[32:35]
	v_mfma_f32_16x16x32_bf16 v[4:7], v[4:7], v[196:199], v[16:19]
	v_mfma_f32_16x16x32_bf16 v[88:91], v[8:11], v[168:171], v[88:91]
	v_mfma_f32_16x16x32_bf16 v[84:87], v[24:27], v[168:171], v[84:87]
	v_mfma_f32_16x16x32_bf16 v[72:75], v[8:11], v[176:179], v[72:75]
	v_mfma_f32_16x16x32_bf16 v[68:71], v[24:27], v[176:179], v[68:71]
	v_mfma_f32_16x16x32_bf16 v[20:23], v[8:11], v[192:195], v[20:23]
	v_mfma_f32_16x16x32_bf16 v[32:35], v[24:27], v[192:195], v[32:35]
	v_mfma_f32_16x16x32_bf16 v[4:7], v[8:11], v[200:203], v[4:7]
	v_mfma_f32_16x16x32_bf16 v[8:11], v[12:15], v[196:199], v[40:43]
	v_mfma_f32_16x16x32_bf16 v[8:11], v[24:27], v[200:203], v[8:11]
	v_mfma_f32_16x16x32_bf16 v[16:19], v[140:143], v[164:167], v[76:79]
	v_mfma_f32_16x16x32_bf16 v[24:27], v[160:163], v[168:171], v[16:19]
	v_mfma_f32_16x16x32_bf16 v[16:19], v[28:31], v[172:175], v[64:67]
	v_mfma_f32_16x16x32_bf16 v[64:67], v[36:39], v[176:179], v[16:19]
	v_mfma_f32_16x16x32_bf16 v[16:19], v[140:143], v[172:175], v[60:63]
	v_mfma_f32_16x16x32_bf16 v[60:63], v[160:163], v[176:179], v[16:19]
	v_mfma_f32_16x16x32_bf16 v[16:19], v[28:31], v[188:191], v[56:59]
	v_mfma_f32_16x16x32_bf16 v[56:59], v[36:39], v[192:195], v[16:19]
	v_mfma_f32_16x16x32_bf16 v[16:19], v[140:143], v[188:191], v[52:55]
	v_mfma_f32_16x16x32_bf16 v[52:55], v[160:163], v[192:195], v[16:19]
	v_mfma_f32_16x16x32_bf16 v[16:19], v[28:31], v[196:199], v[48:51]
	v_mfma_f32_16x16x32_bf16 v[12:15], v[28:31], v[164:167], v[80:83]
	v_mfma_f32_16x16x32_bf16 v[28:31], v[36:39], v[200:203], v[16:19]
	v_mfma_f32_16x16x32_bf16 v[16:19], v[140:143], v[196:199], v[44:47]
	v_mfma_f32_16x16x32_bf16 v[12:15], v[36:39], v[168:171], v[12:15]
	v_mfma_f32_16x16x32_bf16 v[36:39], v[160:163], v[200:203], v[16:19]
	s_barrier
	s_add_i32 s71, 0, 0x18000
	s_add_i32 s76, 0, 0x1c000
	v_add_u32_e32 v48, s71, v230
	v_add_u32_e32 v76, s76, v230
	ds_read_b128 v[16:19], v48
	ds_read_b128 v[40:43], v48 offset:1024
	ds_read_b128 v[44:47], v48 offset:2048
	ds_read_b128 v[48:51], v48 offset:3072
	ds_read_b128 v[140:143], v76
	ds_read_b128 v[160:163], v76 offset:1024
	ds_read_b128 v[164:167], v76 offset:2048
	ds_read_b128 v[168:171], v76 offset:3072
	s_add_u32 s10, s46, 0x2000
	s_addc_u32 s11, s47, 0
	s_mov_b32 m0, s57
	v_lshl_add_u64 v[236:237], s[10:11], 0, v[0:1]
	ds_read_b128 v[76:79], v234 offset:32768
	ds_read_b128 v[80:83], v234 offset:33792
	ds_read_b128 v[172:175], v234 offset:34816
	ds_read_b128 v[176:179], v234 offset:35840
	ds_read_b128 v[188:191], v234 offset:36864
	ds_read_b128 v[192:195], v234 offset:37888
	ds_read_b128 v[196:199], v234 offset:38912
	ds_read_b128 v[200:203], v234 offset:39936
	global_load_lds_dwordx4 v[236:237], off
	v_lshl_add_u64 v[236:237], s[10:11], 0, v[180:181]
	s_mov_b32 m0, s58
	s_nop 0
	global_load_lds_dwordx4 v[236:237], off
	s_waitcnt vmcnt(8)
	s_waitcnt lgkmcnt(0)
	s_barrier
	s_waitcnt lgkmcnt(0)
	v_mfma_f32_16x16x32_bf16 v[152:155], v[16:19], v[76:79], v[152:155]
	v_mfma_f32_16x16x32_bf16 v[148:151], v[44:47], v[76:79], v[148:151]
	v_mfma_f32_16x16x32_bf16 v[136:139], v[16:19], v[172:175], v[136:139]
	v_mfma_f32_16x16x32_bf16 v[128:131], v[44:47], v[172:175], v[128:131]
	v_mfma_f32_16x16x32_bf16 v[120:123], v[16:19], v[188:191], v[120:123]
	v_mfma_f32_16x16x32_bf16 v[116:119], v[44:47], v[188:191], v[116:119]
	v_mfma_f32_16x16x32_bf16 v[104:107], v[16:19], v[196:199], v[104:107]
	v_mfma_f32_16x16x32_bf16 v[100:103], v[44:47], v[196:199], v[100:103]
	v_mfma_f32_16x16x32_bf16 v[152:155], v[40:43], v[80:83], v[152:155]
	v_mfma_f32_16x16x32_bf16 v[148:151], v[48:51], v[80:83], v[148:151]
	v_mfma_f32_16x16x32_bf16 v[136:139], v[40:43], v[176:179], v[136:139]
	v_mfma_f32_16x16x32_bf16 v[128:131], v[48:51], v[176:179], v[128:131]
	v_mfma_f32_16x16x32_bf16 v[120:123], v[40:43], v[192:195], v[120:123]
	v_mfma_f32_16x16x32_bf16 v[116:119], v[48:51], v[192:195], v[116:119]
	v_mfma_f32_16x16x32_bf16 v[104:107], v[40:43], v[200:203], v[104:107]
	v_mfma_f32_16x16x32_bf16 v[100:103], v[48:51], v[200:203], v[100:103]
	v_mfma_f32_16x16x32_bf16 v[156:159], v[140:143], v[76:79], v[156:159]
	v_mfma_f32_16x16x32_bf16 v[76:79], v[164:167], v[76:79], v[144:147]
	v_mfma_f32_16x16x32_bf16 v[144:147], v[168:171], v[80:83], v[76:79]
	v_mfma_f32_16x16x32_bf16 v[76:79], v[140:143], v[172:175], v[132:135]
	v_mfma_f32_16x16x32_bf16 v[132:135], v[160:163], v[176:179], v[76:79]
	v_mfma_f32_16x16x32_bf16 v[76:79], v[164:167], v[172:175], v[124:127]
	v_mfma_f32_16x16x32_bf16 v[124:127], v[168:171], v[176:179], v[76:79]
	v_mfma_f32_16x16x32_bf16 v[76:79], v[140:143], v[188:191], v[112:115]
	v_mfma_f32_16x16x32_bf16 v[112:115], v[160:163], v[192:195], v[76:79]
	v_mfma_f32_16x16x32_bf16 v[76:79], v[164:167], v[188:191], v[108:111]
	v_mfma_f32_16x16x32_bf16 v[108:111], v[168:171], v[192:195], v[76:79]
	v_mfma_f32_16x16x32_bf16 v[76:79], v[140:143], v[196:199], v[96:99]
	v_mfma_f32_16x16x32_bf16 v[96:99], v[160:163], v[200:203], v[76:79]
	v_mfma_f32_16x16x32_bf16 v[76:79], v[164:167], v[196:199], v[92:95]
	v_mfma_f32_16x16x32_bf16 v[156:159], v[160:163], v[80:83], v[156:159]
	v_mfma_f32_16x16x32_bf16 v[92:95], v[168:171], v[200:203], v[76:79]
	s_barrier
; #define PG8_STAGE(bufoff, gbase, voff) do { _Pragma("unroll") for (int _i = 0; _i < 2; ++_i) \
;         __builtin_amdgcn_global_load_lds((const unsigned*)((const char*)(gbase) + (voff)[_i]), (PG8_LAS unsigned*)(lds + (bufoff) + ldsw + _i * 8192), 16, 0, 0); } while (0)
; #define PG8_LDA(dst, b, h) do { _Pragma("unroll") for (int m = 0; m < 4; ++m) _Pragma("unroll") for (int k = 0; k < 2; ++k) dst[m][k] = *(const PG8_LAS bf16x8*)(lds + PG8_SA(b, h) + aoff + m * 2048 + k * 1024); } while (0)
; #define PG8_LDB(dst, b, h) do { _Pragma("unroll") for (int n = 0; n < 2; ++n) _Pragma("unroll") for (int k = 0; k < 2; ++k) dst[n][k] = *(const PG8_LAS bf16x8*)(lds + PG8_SB(b, h) + boff + n * 2048 + k * 1024); } while (0)
; #define PG8_MMA(ai, bj, At, Bt) do { __builtin_amdgcn_s_setprio(1); _Pragma("unroll") for (int m = 0; m < 4; ++m) _Pragma("unroll") for (int n = 0; n < 2; ++n) _Pragma("unroll") for (int k = 0; k < 2; ++k) \
;         acc[ai][bj][m][n] = __builtin_amdgcn_mfma_f32_16x16x32_bf16(Bt[n][k], At[m][k], acc[ai][bj][m][n], 0, 0, 0); __builtin_amdgcn_s_setprio(0); } while (0)
; #define PG8_WAIT_V(n) asm volatile("s_waitcnt vmcnt(" #n ")" ::: "memory")
; template <class Epi, class Sched, bool APERM>
; __device__ __forceinline__ void gemm_phase(PG8_LAS unsigned char* lds, const Gemm g, const Sched& S, const Epi& E) {
;     ...
;             PG8_LDB(B0, 0, 0); PG8_LDB(B1, 0, 1); PG8_SCHED; PG8_LDA(At, 0, 0); PG8_STAGE(PG8_SA(1, 1), a1 + hstepA, voffA);
;             PG8_WAIT_V(8); PG8_WAIT_L(0); PG8_BAR; PG8_MMA(0, 0, At, B0); PG8_MMA(0, 1, At, B1); PG8_BAR; PG8_SCHED;
;             PG8_LDA(At, 0, 1); PG8_STAGE(PG8_SB(0, 0), b2, voffB); PG8_STAGE(PG8_SB(0, 1), b2 + hstep, voffB); PG8_STAGE(PG8_SA(0, 0), a2, voffA);
;             PG8_WAIT_V(8); PG8_WAIT_L(0); PG8_BAR; PG8_MMA(1, 0, At, B0); PG8_MMA(1, 1, At, B1); PG8_BAR; PG8_SCHED;
;             PG8_LDB(B0, 1, 0); PG8_LDB(B1, 1, 1); PG8_SCHED; PG8_LDA(At, 1, 0); PG8_STAGE(PG8_SA(0, 1), a2 + hstepA, voffA);
;             PG8_WAIT_V(8); PG8_WAIT_L(0); PG8_BAR; PG8_MMA(0, 0, At, B0); PG8_MMA(0, 1, At, B1); PG8_BAR; PG8_SCHED;
;             PG8_LDA(At, 1, 1); PG8_STAGE(PG8_SB(1, 0), b3, voffB); PG8_STAGE(PG8_SB(1, 1), b3 + hstep, voffB); PG8_STAGE(PG8_SA(1, 0), a3, voffA);
;             PG8_WAIT_V(8); PG8_WAIT_L(0); PG8_BAR; PG8_MMA(1, 0, At, B0); PG8_MMA(1, 1, At, B1); PG8_BAR; PG8_SCHED;
	s_add_i32 s10, s71, s72
	v_lshl_add_u64 v[80:81], v[204:205], 0, s[52:53]
	s_mov_b32 m0, s10
	s_nop 0
	ds_read_b128 v[76:79], v234 offset:49152
	ds_read_b128 v[172:175], v234 offset:50176
	ds_read_b128 v[176:179], v234 offset:51200
	ds_read_b128 v[188:191], v234 offset:52224
	ds_read_b128 v[192:195], v234 offset:53248
	ds_read_b128 v[196:199], v234 offset:54272
	ds_read_b128 v[200:203], v234 offset:55296
	ds_read_b128 v[236:239], v234 offset:56320
	global_load_lds_dwordx4 v[80:81], off
	s_add_i32 m0, s10, 0x2000
	s_add_u32 s10, vcc_lo, 0x40080
	v_lshl_add_u64 v[80:81], v[222:223], 0, s[52:53]
	s_addc_u32 s11, vcc_hi, 0
	s_add_i32 s46, s76, s72
	global_load_lds_dwordx4 v[80:81], off
	v_lshl_add_u64 v[80:81], s[10:11], 0, v[2:3]
	s_mov_b32 m0, s46
	s_nop 0
	global_load_lds_dwordx4 v[80:81], off
	v_lshl_add_u64 v[80:81], s[10:11], 0, v[182:183]
	s_add_i32 m0, s46, 0x2000
	s_nop 0
	global_load_lds_dwordx4 v[80:81], off
	v_lshl_add_u64 v[80:81], v[240:241], 0, s[52:53]
	s_mov_b32 m0, s59
	s_nop 0
	global_load_lds_dwordx4 v[80:81], off
	v_lshl_add_u64 v[80:81], v[242:243], 0, s[52:53]
	s_mov_b32 m0, s60
	s_nop 0
	global_load_lds_dwordx4 v[80:81], off
	s_waitcnt vmcnt(8)
	s_waitcnt lgkmcnt(0)
	s_barrier
	s_waitcnt lgkmcnt(0)
	v_mfma_f32_16x16x32_bf16 v[80:83], v[16:19], v[76:79], v[88:91]
	v_mfma_f32_16x16x32_bf16 v[4:7], v[16:19], v[200:203], v[4:7]
	v_mfma_f32_16x16x32_bf16 v[88:91], v[40:43], v[172:175], v[80:83]
	v_mfma_f32_16x16x32_bf16 v[80:83], v[44:47], v[76:79], v[84:87]
	v_mfma_f32_16x16x32_bf16 v[72:75], v[16:19], v[176:179], v[72:75]
	v_mfma_f32_16x16x32_bf16 v[68:71], v[44:47], v[176:179], v[68:71]
	v_mfma_f32_16x16x32_bf16 v[20:23], v[16:19], v[192:195], v[20:23]
	v_mfma_f32_16x16x32_bf16 v[32:35], v[44:47], v[192:195], v[32:35]
	v_mfma_f32_16x16x32_bf16 v[16:19], v[40:43], v[236:239], v[4:7]
	v_mfma_f32_16x16x32_bf16 v[4:7], v[44:47], v[200:203], v[8:11]
	v_mfma_f32_16x16x32_bf16 v[84:87], v[48:51], v[172:175], v[80:83]
	v_mfma_f32_16x16x32_bf16 v[72:75], v[40:43], v[188:191], v[72:75]
	v_mfma_f32_16x16x32_bf16 v[68:71], v[48:51], v[188:191], v[68:71]
	v_mfma_f32_16x16x32_bf16 v[20:23], v[40:43], v[196:199], v[20:23]
	v_mfma_f32_16x16x32_bf16 v[32:35], v[48:51], v[196:199], v[32:35]
	v_mfma_f32_16x16x32_bf16 v[40:43], v[48:51], v[236:239], v[4:7]
	v_mfma_f32_16x16x32_bf16 v[4:7], v[140:143], v[76:79], v[12:15]
	v_mfma_f32_16x16x32_bf16 v[80:83], v[160:163], v[172:175], v[4:7]
	v_mfma_f32_16x16x32_bf16 v[4:7], v[164:167], v[76:79], v[24:27]
	v_mfma_f32_16x16x32_bf16 v[76:79], v[168:171], v[172:175], v[4:7]
	v_mfma_f32_16x16x32_bf16 v[4:7], v[140:143], v[176:179], v[64:67]
	v_mfma_f32_16x16x32_bf16 v[64:67], v[160:163], v[188:191], v[4:7]
	v_mfma_f32_16x16x32_bf16 v[4:7], v[164:167], v[176:179], v[60:63]
	v_mfma_f32_16x16x32_bf16 v[60:63], v[168:171], v[188:191], v[4:7]
	v_mfma_f32_16x16x32_bf16 v[4:7], v[140:143], v[192:195], v[56:59]
	v_mfma_f32_16x16x32_bf16 v[56:59], v[160:163], v[196:199], v[4:7]
	v_mfma_f32_16x16x32_bf16 v[4:7], v[164:167], v[192:195], v[52:55]
	v_mfma_f32_16x16x32_bf16 v[52:55], v[168:171], v[196:199], v[4:7]
	v_mfma_f32_16x16x32_bf16 v[4:7], v[140:143], v[200:203], v[28:31]
	v_mfma_f32_16x16x32_bf16 v[48:51], v[160:163], v[236:239], v[4:7]
	v_mfma_f32_16x16x32_bf16 v[4:7], v[164:167], v[200:203], v[36:39]
	v_mfma_f32_16x16x32_bf16 v[44:47], v[168:171], v[236:239], v[4:7]
	s_barrier
	s_add_i32 s70, s70, 2
	s_add_u32 s68, s68, 0x100
	s_addc_u32 s69, s69, 0
	s_cmp_gt_u32 s70, 13
	s_mov_b64 s[10:11], s[12:13]
	s_cbranch_scc0 .LBB0_470
	s_and_b64 vcc, exec, s[40:41]
	s_cbranch_vccz .LBB0_473
	s_barrier

; #define PG8_STAGE(bufoff, gbase, voff) do { _Pragma("unroll") for (int _i = 0; _i < 2; ++_i) \
;         __builtin_amdgcn_global_load_lds((const unsigned*)((const char*)(gbase) + (voff)[_i]), (PG8_LAS unsigned*)(lds + (bufoff) + ldsw + _i * 8192), 16, 0, 0); } while (0)
; #define PG8_LDA(dst, b, h) do { _Pragma("unroll") for (int m = 0; m < 4; ++m) _Pragma("unroll") for (int k = 0; k < 2; ++k) dst[m][k] = *(const PG8_LAS bf16x8*)(lds + PG8_SA(b, h) + aoff + m * 2048 + k * 1024); } while (0)
; #define PG8_LDB(dst, b, h) do { _Pragma("unroll") for (int n = 0; n < 2; ++n) _Pragma("unroll") for (int k = 0; k < 2; ++k) dst[n][k] = *(const PG8_LAS bf16x8*)(lds + PG8_SB(b, h) + boff + n * 2048 + k * 1024); } while (0)
; #define PG8_BAR __builtin_amdgcn_s_barrier()
; template <class Epi, class Sched, bool APERM>
; __device__ __forceinline__ void gemm_phase(PG8_LAS unsigned char* lds, const Gemm g, const Sched& S, const Epi& E) {
;     ...
;         for (int t = 0; t < nt; t += 2) {
;             const bool last = (t == nt - 2);
;             const char* a1 = cA + (size_t)(t + 1) * kstep;
;             const char* a2 = last ? nA : cA + (size_t)(t + 2) * kstep; const char* b2 = last ? nB : cB + (size_t)(t + 2) * kstep;
;             const char* a3 = a2 + kstep; const char* b3 = b2 + kstep;
;             if (last && has_next) S.a_ready(nxt);
;             PG8_LDB(B0, 0, 0); PG8_LDB(B1, 0, 1); PG8_SCHED; PG8_LDA(At, 0, 0); PG8_STAGE(PG8_SA(1, 1), a1 + hstepA, voffA);
;             PG8_WAIT_V(8); PG8_WAIT_L(0); PG8_BAR; PG8_MMA(0, 0, At, B0); PG8_MMA(0, 1, At, B1); PG8_BAR; PG8_SCHED;
;             PG8_LDA(At, 0, 1); PG8_STAGE(PG8_SB(0, 0), b2, voffB); PG8_STAGE(PG8_SB(0, 1), b2 + hstep, voffB); PG8_STAGE(PG8_SA(0, 0), a2, voffA);
;             PG8_WAIT_V(8); PG8_WAIT_L(0); PG8_BAR; PG8_MMA(1, 0, At, B0); PG8_MMA(1, 1, At, B1); PG8_BAR; PG8_SCHED;
;             PG8_LDB(B0, 1, 0); PG8_LDB(B1, 1, 1); PG8_SCHED; PG8_LDA(At, 1, 0); PG8_STAGE(PG8_SA(0, 1), a2 + hstepA, voffA);
;             PG8_WAIT_V(8); PG8_WAIT_L(0); PG8_BAR; PG8_MMA(0, 0, At, B0); PG8_MMA(0, 1, At, B1); PG8_BAR; PG8_SCHED;
;             PG8_LDA(At, 1, 1); PG8_STAGE(PG8_SB(1, 0), b3, voffB); PG8_STAGE(PG8_SB(1, 1), b3 + hstep, voffB); PG8_STAGE(PG8_SA(1, 0), a3, voffA);
;             PG8_WAIT_V(8); PG8_WAIT_L(0); PG8_BAR; PG8_MMA(1, 0, At, B0); PG8_MMA(1, 1, At, B1); PG8_BAR; PG8_SCHED;
.LBB0_621:
	s_add_i32 s23, s22, 0x100
	s_and_b64 s[20:21], s[20:21], exec
	s_cselect_b32 s21, 0, s23
	s_cselect_b32 s20, 0, 0
	s_add_u32 s24, s14, s21
	s_addc_u32 s25, s15, s20
	s_add_i32 s66, 0, 0x10000
	s_add_u32 s26, s12, s21
	s_addc_u32 s27, s13, s20
	s_add_i32 s21, 0, 0x14000
	s_add_u32 s34, s16, s22
	s_addc_u32 s35, s17, 0
	s_add_i32 s65, s66, s50
	s_add_i32 m0, s1, 0xc000
	s_add_i32 s68, s1, 0xe000
	s_add_i32 s62, s65, 0x2000
	v_add_u32_e32 v141, s66, v139
	s_add_u32 s28, s26, 0x40000
	ds_read_b128 v[142:145], v141
	ds_read_b128 v[146:149], v141 offset:1024
	ds_read_b128 v[150:153], v141 offset:2048
	ds_read_b128 v[154:157], v141 offset:3072
	v_add_u32_e32 v141, s21, v139
	s_addc_u32 s29, s27, 0
	s_add_i32 s64, s21, s50
	ds_read_b128 v[158:161], v141
	ds_read_b128 v[162:165], v141 offset:1024
	ds_read_b128 v[166:169], v141 offset:2048
	ds_read_b128 v[170:173], v141 offset:3072
	s_add_i32 s63, s64, 0x2000
	s_add_i32 s61, 0, 0x18000
	s_add_i32 s60, 0, 0x1c000
	s_add_u32 s22, s24, 0x40000
	s_addc_u32 s23, s25, 0
	s_add_i32 s59, s61, s50
	s_add_i32 s58, s59, 0x2000
	s_add_u32 s20, s26, 0x40080
	s_addc_u32 s21, s27, 0
	s_add_i32 s67, s60, s50
	s_add_i32 s66, s67, 0x2000
	v_lshl_add_u64 v[222:223], s[34:35], 0, v[134:135]
	v_lshl_add_u64 v[222:223], v[222:223], 0, s[52:53]
	ds_read_b128 v[174:177], v140
	ds_read_b128 v[178:181], v140 offset:1024
	ds_read_b128 v[182:185], v140 offset:2048
	ds_read_b128 v[186:189], v140 offset:3072
	ds_read_b128 v[190:193], v140 offset:4096
	ds_read_b128 v[194:197], v140 offset:5120
	ds_read_b128 v[198:201], v140 offset:6144
	ds_read_b128 v[202:205], v140 offset:7168
	global_load_lds_dwordx4 v[222:223], off
	v_lshl_add_u64 v[222:223], s[34:35], 0, v[132:133]
	v_lshl_add_u64 v[222:223], v[222:223], 0, s[52:53]
	s_mov_b32 m0, s68
	s_nop 0
	global_load_lds_dwordx4 v[222:223], off
	s_waitcnt vmcnt(8)
	s_waitcnt lgkmcnt(0)
	s_barrier
	s_waitcnt lgkmcnt(0)
	v_mfma_f32_16x16x32_bf16 v[128:131], v[142:145], v[174:177], v[128:131]
	v_mfma_f32_16x16x32_bf16 v[124:127], v[150:153], v[174:177], v[124:127]
	v_mfma_f32_16x16x32_bf16 v[120:123], v[142:145], v[182:185], v[120:123]
	v_mfma_f32_16x16x32_bf16 v[116:119], v[150:153], v[182:185], v[116:119]
	v_mfma_f32_16x16x32_bf16 v[112:115], v[142:145], v[190:193], v[112:115]
	v_mfma_f32_16x16x32_bf16 v[108:111], v[150:153], v[190:193], v[108:111]
	v_mfma_f32_16x16x32_bf16 v[104:107], v[142:145], v[198:201], v[104:107]
	v_mfma_f32_16x16x32_bf16 v[100:103], v[150:153], v[198:201], v[100:103]
	v_mfma_f32_16x16x32_bf16 v[128:131], v[146:149], v[178:181], v[128:131]
	v_mfma_f32_16x16x32_bf16 v[124:127], v[154:157], v[178:181], v[124:127]
	v_mfma_f32_16x16x32_bf16 v[120:123], v[146:149], v[186:189], v[120:123]
	v_mfma_f32_16x16x32_bf16 v[116:119], v[154:157], v[186:189], v[116:119]
	v_mfma_f32_16x16x32_bf16 v[112:115], v[146:149], v[194:197], v[112:115]
	v_mfma_f32_16x16x32_bf16 v[108:111], v[154:157], v[194:197], v[108:111]
	v_mfma_f32_16x16x32_bf16 v[104:107], v[146:149], v[202:205], v[104:107]
	v_mfma_f32_16x16x32_bf16 v[100:103], v[154:157], v[202:205], v[100:103]
	v_mfma_f32_16x16x32_bf16 v[96:99], v[158:161], v[174:177], v[96:99]
	v_mfma_f32_16x16x32_bf16 v[92:95], v[166:169], v[174:177], v[92:95]
	v_mfma_f32_16x16x32_bf16 v[88:91], v[158:161], v[182:185], v[88:91]
	v_mfma_f32_16x16x32_bf16 v[84:87], v[166:169], v[182:185], v[84:87]
	v_mfma_f32_16x16x32_bf16 v[80:83], v[158:161], v[190:193], v[80:83]
	v_mfma_f32_16x16x32_bf16 v[76:79], v[166:169], v[190:193], v[76:79]
	v_mfma_f32_16x16x32_bf16 v[72:75], v[158:161], v[198:201], v[72:75]
	v_mfma_f32_16x16x32_bf16 v[68:71], v[166:169], v[198:201], v[68:71]
	v_mfma_f32_16x16x32_bf16 v[96:99], v[162:165], v[178:181], v[96:99]
	v_mfma_f32_16x16x32_bf16 v[92:95], v[170:173], v[178:181], v[92:95]
	v_mfma_f32_16x16x32_bf16 v[88:91], v[162:165], v[186:189], v[88:91]
	v_mfma_f32_16x16x32_bf16 v[84:87], v[170:173], v[186:189], v[84:87]
	v_mfma_f32_16x16x32_bf16 v[80:83], v[162:165], v[194:197], v[80:83]
	v_mfma_f32_16x16x32_bf16 v[76:79], v[170:173], v[194:197], v[76:79]
	v_mfma_f32_16x16x32_bf16 v[72:75], v[162:165], v[202:205], v[72:75]
	v_mfma_f32_16x16x32_bf16 v[68:71], v[170:173], v[202:205], v[68:71]
	s_barrier
	s_mov_b32 m0, s65
	v_lshl_add_u64 v[222:223], s[26:27], 0, v[2:3]
	ds_read_b128 v[174:177], v140 offset:16384
	ds_read_b128 v[178:181], v140 offset:17408
	ds_read_b128 v[182:185], v140 offset:18432
	ds_read_b128 v[186:189], v140 offset:19456
	ds_read_b128 v[190:193], v140 offset:20480
	ds_read_b128 v[194:197], v140 offset:21504
	ds_read_b128 v[198:201], v140 offset:22528
	ds_read_b128 v[202:205], v140 offset:23552
	global_load_lds_dwordx4 v[222:223], off
	v_lshl_add_u64 v[230:231], s[26:27], 0, v[0:1]
	s_mov_b32 m0, s62
	v_lshl_add_u64 v[232:233], s[28:29], 0, v[2:3]
	global_load_lds_dwordx4 v[230:231], off
	s_mov_b32 m0, s64
	v_lshl_add_u64 v[234:235], s[24:25], 0, v[132:133]
	global_load_lds_dwordx4 v[232:233], off
	v_lshl_add_u64 v[232:233], s[28:29], 0, v[0:1]
	s_mov_b32 m0, s63
	s_nop 0
	global_load_lds_dwordx4 v[232:233], off
	v_lshl_add_u64 v[232:233], s[24:25], 0, v[134:135]
	s_mov_b32 m0, s1
	s_nop 0
	global_load_lds_dwordx4 v[232:233], off
	s_mov_b32 m0, s7
	s_nop 0
	global_load_lds_dwordx4 v[234:235], off
	s_waitcnt vmcnt(8)
	s_waitcnt lgkmcnt(0)
	s_barrier
; #define PG8_STAGE(bufoff, gbase, voff) do { _Pragma("unroll") for (int _i = 0; _i < 2; ++_i) \
;         __builtin_amdgcn_global_load_lds((const unsigned*)((const char*)(gbase) + (voff)[_i]), (PG8_LAS unsigned*)(lds + (bufoff) + ldsw + _i * 8192), 16, 0, 0); } while (0)
; #define PG8_LDA(dst, b, h) do { _Pragma("unroll") for (int m = 0; m < 4; ++m) _Pragma("unroll") for (int k = 0; k < 2; ++k) dst[m][k] = *(const PG8_LAS bf16x8*)(lds + PG8_SA(b, h) + aoff + m * 2048 + k * 1024); } while (0)
; #define PG8_LDB(dst, b, h) do { _Pragma("unroll") for (int n = 0; n < 2; ++n) _Pragma("unroll") for (int k = 0; k < 2; ++k) dst[n][k] = *(const PG8_LAS bf16x8*)(lds + PG8_SB(b, h) + boff + n * 2048 + k * 1024); } while (0)
; #define PG8_MMA(ai, bj, At, Bt) do { __builtin_amdgcn_s_setprio(1); _Pragma("unroll") for (int m = 0; m < 4; ++m) _Pragma("unroll") for (int n = 0; n < 2; ++n) _Pragma("unroll") for (int k = 0; k < 2; ++k) \
;         acc[ai][bj][m][n] = __builtin_amdgcn_mfma_f32_16x16x32_bf16(Bt[n][k], At[m][k], acc[ai][bj][m][n], 0, 0, 0); __builtin_amdgcn_s_setprio(0); } while (0)
; #define PG8_WAIT_V(n) asm volatile("s_waitcnt vmcnt(" #n ")" ::: "memory")
; #define PG8_WAIT_L(n) asm volatile("s_waitcnt lgkmcnt(" #n ")" ::: "memory")
; #define PG8_BAR __builtin_amdgcn_s_barrier()
; #define PG8_SCHED __builtin_amdgcn_sched_barrier(0)
; template <class Epi, class Sched, bool APERM>
; __device__ __forceinline__ void gemm_phase(PG8_LAS unsigned char* lds, const Gemm g, const Sched& S, const Epi& E) {
;     ...
;             PG8_WAIT_V(8); PG8_WAIT_L(0); PG8_BAR; PG8_MMA(0, 0, At, B0); PG8_MMA(0, 1, At, B1); PG8_BAR; PG8_SCHED;
;             PG8_LDA(At, 0, 1); PG8_STAGE(PG8_SB(0, 0), b2, voffB); PG8_STAGE(PG8_SB(0, 1), b2 + hstep, voffB); PG8_STAGE(PG8_SA(0, 0), a2, voffA);
;             PG8_WAIT_V(8); PG8_WAIT_L(0); PG8_BAR; PG8_MMA(1, 0, At, B0); PG8_MMA(1, 1, At, B1); PG8_BAR; PG8_SCHED;
;             PG8_LDB(B0, 1, 0); PG8_LDB(B1, 1, 1); PG8_SCHED; PG8_LDA(At, 1, 0); PG8_STAGE(PG8_SA(0, 1), a2 + hstepA, voffA);
;             PG8_WAIT_V(8); PG8_WAIT_L(0); PG8_BAR; PG8_MMA(0, 0, At, B0); PG8_MMA(0, 1, At, B1); PG8_BAR; PG8_SCHED;
	s_waitcnt lgkmcnt(0)
	v_mfma_f32_16x16x32_bf16 v[64:67], v[142:145], v[174:177], v[64:67]
	v_mfma_f32_16x16x32_bf16 v[60:63], v[150:153], v[174:177], v[60:63]
	v_mfma_f32_16x16x32_bf16 v[56:59], v[142:145], v[182:185], v[56:59]
	v_mfma_f32_16x16x32_bf16 v[52:55], v[150:153], v[182:185], v[52:55]
	v_mfma_f32_16x16x32_bf16 v[48:51], v[142:145], v[190:193], v[48:51]
	v_mfma_f32_16x16x32_bf16 v[44:47], v[150:153], v[190:193], v[44:47]
	v_mfma_f32_16x16x32_bf16 v[40:43], v[142:145], v[198:201], v[40:43]
	v_mfma_f32_16x16x32_bf16 v[36:39], v[150:153], v[198:201], v[36:39]
	v_mfma_f32_16x16x32_bf16 v[64:67], v[146:149], v[178:181], v[64:67]
	v_mfma_f32_16x16x32_bf16 v[60:63], v[154:157], v[178:181], v[60:63]
	v_mfma_f32_16x16x32_bf16 v[56:59], v[146:149], v[186:189], v[56:59]
	v_mfma_f32_16x16x32_bf16 v[52:55], v[154:157], v[186:189], v[52:55]
	v_mfma_f32_16x16x32_bf16 v[48:51], v[146:149], v[194:197], v[48:51]
	v_mfma_f32_16x16x32_bf16 v[44:47], v[154:157], v[194:197], v[44:47]
	v_mfma_f32_16x16x32_bf16 v[40:43], v[146:149], v[202:205], v[40:43]
	v_mfma_f32_16x16x32_bf16 v[36:39], v[154:157], v[202:205], v[36:39]
	v_mfma_f32_16x16x32_bf16 v[32:35], v[158:161], v[174:177], v[32:35]
	v_mfma_f32_16x16x32_bf16 v[28:31], v[166:169], v[174:177], v[28:31]
	v_mfma_f32_16x16x32_bf16 v[24:27], v[158:161], v[182:185], v[24:27]
	v_mfma_f32_16x16x32_bf16 v[20:23], v[166:169], v[182:185], v[20:23]
	v_mfma_f32_16x16x32_bf16 v[16:19], v[158:161], v[190:193], v[16:19]
	v_mfma_f32_16x16x32_bf16 v[12:15], v[166:169], v[190:193], v[12:15]
	v_mfma_f32_16x16x32_bf16 v[8:11], v[158:161], v[198:201], v[8:11]
	v_mfma_f32_16x16x32_bf16 v[4:7], v[166:169], v[198:201], v[4:7]
	v_mfma_f32_16x16x32_bf16 v[32:35], v[162:165], v[178:181], v[32:35]
	v_mfma_f32_16x16x32_bf16 v[28:31], v[170:173], v[178:181], v[28:31]
	v_mfma_f32_16x16x32_bf16 v[24:27], v[162:165], v[186:189], v[24:27]
	v_mfma_f32_16x16x32_bf16 v[20:23], v[170:173], v[186:189], v[20:23]
	v_mfma_f32_16x16x32_bf16 v[16:19], v[162:165], v[194:197], v[16:19]
	v_mfma_f32_16x16x32_bf16 v[12:15], v[170:173], v[194:197], v[12:15]
	v_mfma_f32_16x16x32_bf16 v[8:11], v[162:165], v[202:205], v[8:11]
	v_mfma_f32_16x16x32_bf16 v[4:7], v[170:173], v[202:205], v[4:7]
	s_barrier
	v_add_u32_e32 v141, s61, v139
	ds_read_b128 v[142:145], v141
	ds_read_b128 v[146:149], v141 offset:1024
	ds_read_b128 v[150:153], v141 offset:2048
	ds_read_b128 v[154:157], v141 offset:3072
	v_add_u32_e32 v141, s60, v139
	ds_read_b128 v[158:161], v141
	ds_read_b128 v[162:165], v141 offset:1024
	ds_read_b128 v[166:169], v141 offset:2048
	ds_read_b128 v[170:173], v141 offset:3072
	s_mov_b32 m0, s51
	v_lshl_add_u64 v[236:237], s[22:23], 0, v[134:135]
	ds_read_b128 v[174:177], v140 offset:32768
	ds_read_b128 v[178:181], v140 offset:33792
	ds_read_b128 v[182:185], v140 offset:34816
	ds_read_b128 v[186:189], v140 offset:35840
	ds_read_b128 v[190:193], v140 offset:36864
	ds_read_b128 v[194:197], v140 offset:37888
	ds_read_b128 v[198:201], v140 offset:38912
	ds_read_b128 v[202:205], v140 offset:39936
	global_load_lds_dwordx4 v[236:237], off
	v_lshl_add_u64 v[236:237], s[22:23], 0, v[132:133]
	s_mov_b32 m0, s55
	s_nop 0
	global_load_lds_dwordx4 v[236:237], off
	s_waitcnt vmcnt(8)
	s_waitcnt lgkmcnt(0)
	s_barrier
	s_waitcnt lgkmcnt(0)
	v_mfma_f32_16x16x32_bf16 v[128:131], v[142:145], v[174:177], v[128:131]
	v_mfma_f32_16x16x32_bf16 v[124:127], v[150:153], v[174:177], v[124:127]
	v_mfma_f32_16x16x32_bf16 v[120:123], v[142:145], v[182:185], v[120:123]
	v_mfma_f32_16x16x32_bf16 v[116:119], v[150:153], v[182:185], v[116:119]
	v_mfma_f32_16x16x32_bf16 v[112:115], v[142:145], v[190:193], v[112:115]
	v_mfma_f32_16x16x32_bf16 v[108:111], v[150:153], v[190:193], v[108:111]
	v_mfma_f32_16x16x32_bf16 v[104:107], v[142:145], v[198:201], v[104:107]
	v_mfma_f32_16x16x32_bf16 v[100:103], v[150:153], v[198:201], v[100:103]
	v_mfma_f32_16x16x32_bf16 v[128:131], v[146:149], v[178:181], v[128:131]
	v_mfma_f32_16x16x32_bf16 v[124:127], v[154:157], v[178:181], v[124:127]
	v_mfma_f32_16x16x32_bf16 v[120:123], v[146:149], v[186:189], v[120:123]
	v_mfma_f32_16x16x32_bf16 v[116:119], v[154:157], v[186:189], v[116:119]
	v_mfma_f32_16x16x32_bf16 v[112:115], v[146:149], v[194:197], v[112:115]
	v_mfma_f32_16x16x32_bf16 v[108:111], v[154:157], v[194:197], v[108:111]
	v_mfma_f32_16x16x32_bf16 v[104:107], v[146:149], v[202:205], v[104:107]
	v_mfma_f32_16x16x32_bf16 v[100:103], v[154:157], v[202:205], v[100:103]
	v_mfma_f32_16x16x32_bf16 v[96:99], v[158:161], v[174:177], v[96:99]
	v_mfma_f32_16x16x32_bf16 v[92:95], v[166:169], v[174:177], v[92:95]
	v_mfma_f32_16x16x32_bf16 v[88:91], v[158:161], v[182:185], v[88:91]
	v_mfma_f32_16x16x32_bf16 v[84:87], v[166:169], v[182:185], v[84:87]
	v_mfma_f32_16x16x32_bf16 v[80:83], v[158:161], v[190:193], v[80:83]
	v_mfma_f32_16x16x32_bf16 v[76:79], v[166:169], v[190:193], v[76:79]
	v_mfma_f32_16x16x32_bf16 v[72:75], v[158:161], v[198:201], v[72:75]
	v_mfma_f32_16x16x32_bf16 v[68:71], v[166:169], v[198:201], v[68:71]
	v_mfma_f32_16x16x32_bf16 v[96:99], v[162:165], v[178:181], v[96:99]
	v_mfma_f32_16x16x32_bf16 v[92:95], v[170:173], v[178:181], v[92:95]
	v_mfma_f32_16x16x32_bf16 v[88:91], v[162:165], v[186:189], v[88:91]
	v_mfma_f32_16x16x32_bf16 v[84:87], v[170:173], v[186:189], v[84:87]
	v_mfma_f32_16x16x32_bf16 v[80:83], v[162:165], v[194:197], v[80:83]
	v_mfma_f32_16x16x32_bf16 v[76:79], v[170:173], v[194:197], v[76:79]
	v_mfma_f32_16x16x32_bf16 v[72:75], v[162:165], v[202:205], v[72:75]
	v_mfma_f32_16x16x32_bf16 v[68:71], v[170:173], v[202:205], v[68:71]
	s_barrier
; #define PG8_STAGE(bufoff, gbase, voff) do { _Pragma("unroll") for (int _i = 0; _i < 2; ++_i) \
;         __builtin_amdgcn_global_load_lds((const unsigned*)((const char*)(gbase) + (voff)[_i]), (PG8_LAS unsigned*)(lds + (bufoff) + ldsw + _i * 8192), 16, 0, 0); } while (0)
; #define PG8_LDA(dst, b, h) do { _Pragma("unroll") for (int m = 0; m < 4; ++m) _Pragma("unroll") for (int k = 0; k < 2; ++k) dst[m][k] = *(const PG8_LAS bf16x8*)(lds + PG8_SA(b, h) + aoff + m * 2048 + k * 1024); } while (0)
; #define PG8_MMA(ai, bj, At, Bt) do { __builtin_amdgcn_s_setprio(1); _Pragma("unroll") for (int m = 0; m < 4; ++m) _Pragma("unroll") for (int n = 0; n < 2; ++n) _Pragma("unroll") for (int k = 0; k < 2; ++k) \
;         acc[ai][bj][m][n] = __builtin_amdgcn_mfma_f32_16x16x32_bf16(Bt[n][k], At[m][k], acc[ai][bj][m][n], 0, 0, 0); __builtin_amdgcn_s_setprio(0); } while (0)
; #define PG8_WAIT_V(n) asm volatile("s_waitcnt vmcnt(" #n ")" ::: "memory")
; #define PG8_WAIT_L(n) asm volatile("s_waitcnt lgkmcnt(" #n ")" ::: "memory")
; #define PG8_BAR __builtin_amdgcn_s_barrier()
; #define PG8_SCHED __builtin_amdgcn_sched_barrier(0)
; template <class Epi, class Sched, bool APERM>
; __device__ __forceinline__ void gemm_phase(PG8_LAS unsigned char* lds, const Gemm g, const Sched& S, const Epi& E) {
;     ...
;             PG8_LDA(At, 1, 1); PG8_STAGE(PG8_SB(1, 0), b3, voffB); PG8_STAGE(PG8_SB(1, 1), b3 + hstep, voffB); PG8_STAGE(PG8_SA(1, 0), a3, voffA);
;             PG8_WAIT_V(8); PG8_WAIT_L(0); PG8_BAR; PG8_MMA(1, 0, At, B0); PG8_MMA(1, 1, At, B1); PG8_BAR; PG8_SCHED;
;         }
;         if (wr == 0) PG8_BAR;
	s_mov_b32 m0, s59
	v_lshl_add_u64 v[222:223], v[222:223], 0, s[52:53]
	ds_read_b128 v[174:177], v140 offset:49152
	ds_read_b128 v[178:181], v140 offset:50176
	ds_read_b128 v[182:185], v140 offset:51200
	ds_read_b128 v[186:189], v140 offset:52224
	ds_read_b128 v[190:193], v140 offset:53248
	ds_read_b128 v[194:197], v140 offset:54272
	ds_read_b128 v[198:201], v140 offset:55296
	ds_read_b128 v[202:205], v140 offset:56320
	global_load_lds_dwordx4 v[222:223], off
	v_lshl_add_u64 v[222:223], v[230:231], 0, s[52:53]
	s_mov_b32 m0, s58
	s_nop 0
	global_load_lds_dwordx4 v[222:223], off
	v_lshl_add_u64 v[222:223], s[20:21], 0, v[2:3]
	s_mov_b32 m0, s67
	s_nop 0
	global_load_lds_dwordx4 v[222:223], off
	v_lshl_add_u64 v[222:223], s[20:21], 0, v[0:1]
	s_mov_b32 m0, s66
	s_nop 0
	global_load_lds_dwordx4 v[222:223], off
	v_lshl_add_u64 v[222:223], v[232:233], 0, s[52:53]
	s_mov_b32 m0, s56
	s_nop 0
	global_load_lds_dwordx4 v[222:223], off
	v_lshl_add_u64 v[222:223], v[234:235], 0, s[52:53]
	s_mov_b32 m0, s57
	s_nop 0
	global_load_lds_dwordx4 v[222:223], off
	s_waitcnt vmcnt(8)
	s_waitcnt lgkmcnt(0)
	s_barrier
	s_waitcnt lgkmcnt(0)
	v_mfma_f32_16x16x32_bf16 v[64:67], v[142:145], v[174:177], v[64:67]
	v_mfma_f32_16x16x32_bf16 v[60:63], v[150:153], v[174:177], v[60:63]
	v_mfma_f32_16x16x32_bf16 v[56:59], v[142:145], v[182:185], v[56:59]
	v_mfma_f32_16x16x32_bf16 v[52:55], v[150:153], v[182:185], v[52:55]
	v_mfma_f32_16x16x32_bf16 v[48:51], v[142:145], v[190:193], v[48:51]
	v_mfma_f32_16x16x32_bf16 v[44:47], v[150:153], v[190:193], v[44:47]
	v_mfma_f32_16x16x32_bf16 v[40:43], v[142:145], v[198:201], v[40:43]
	v_mfma_f32_16x16x32_bf16 v[36:39], v[150:153], v[198:201], v[36:39]
	v_mfma_f32_16x16x32_bf16 v[64:67], v[146:149], v[178:181], v[64:67]
	v_mfma_f32_16x16x32_bf16 v[60:63], v[154:157], v[178:181], v[60:63]
	v_mfma_f32_16x16x32_bf16 v[56:59], v[146:149], v[186:189], v[56:59]
	v_mfma_f32_16x16x32_bf16 v[52:55], v[154:157], v[186:189], v[52:55]
	v_mfma_f32_16x16x32_bf16 v[48:51], v[146:149], v[194:197], v[48:51]
	v_mfma_f32_16x16x32_bf16 v[44:47], v[154:157], v[194:197], v[44:47]
	v_mfma_f32_16x16x32_bf16 v[40:43], v[146:149], v[202:205], v[40:43]
	v_mfma_f32_16x16x32_bf16 v[36:39], v[154:157], v[202:205], v[36:39]
	v_mfma_f32_16x16x32_bf16 v[32:35], v[158:161], v[174:177], v[32:35]
	v_mfma_f32_16x16x32_bf16 v[28:31], v[166:169], v[174:177], v[28:31]
	v_mfma_f32_16x16x32_bf16 v[24:27], v[158:161], v[182:185], v[24:27]
	v_mfma_f32_16x16x32_bf16 v[20:23], v[166:169], v[182:185], v[20:23]
	v_mfma_f32_16x16x32_bf16 v[16:19], v[158:161], v[190:193], v[16:19]
	v_mfma_f32_16x16x32_bf16 v[12:15], v[166:169], v[190:193], v[12:15]
	v_mfma_f32_16x16x32_bf16 v[8:11], v[158:161], v[198:201], v[8:11]
	v_mfma_f32_16x16x32_bf16 v[4:7], v[166:169], v[198:201], v[4:7]
	v_mfma_f32_16x16x32_bf16 v[32:35], v[162:165], v[178:181], v[32:35]
	v_mfma_f32_16x16x32_bf16 v[28:31], v[170:173], v[178:181], v[28:31]
	v_mfma_f32_16x16x32_bf16 v[24:27], v[162:165], v[186:189], v[24:27]
	v_mfma_f32_16x16x32_bf16 v[20:23], v[170:173], v[186:189], v[20:23]
	v_mfma_f32_16x16x32_bf16 v[16:19], v[162:165], v[194:197], v[16:19]
	v_mfma_f32_16x16x32_bf16 v[12:15], v[170:173], v[194:197], v[12:15]
	v_mfma_f32_16x16x32_bf16 v[8:11], v[162:165], v[202:205], v[8:11]
	v_mfma_f32_16x16x32_bf16 v[4:7], v[170:173], v[202:205], v[4:7]
	s_barrier
	s_andn2_b64 vcc, exec, s[18:19]
	s_mov_b64 s[20:21], -1
	s_mov_b64 s[18:19], 0
	s_movk_i32 s22, 0x100
	s_cbranch_vccz .LBB0_621
	s_cmpk_lt_u32 s49, 0x100
	s_cbranch_scc0 .LBB0_624
	s_barrier

; #define PG8_STAGE(bufoff, gbase, voff) do { _Pragma("unroll") for (int _i = 0; _i < 2; ++_i) \
;         __builtin_amdgcn_global_load_lds((const unsigned*)((const char*)(gbase) + (voff)[_i]), (PG8_LAS unsigned*)(lds + (bufoff) + ldsw + _i * 8192), 16, 0, 0); } while (0)
; #define PG8_LDA(dst, b, h) do { _Pragma("unroll") for (int m = 0; m < 4; ++m) _Pragma("unroll") for (int k = 0; k < 2; ++k) dst[m][k] = *(const PG8_LAS bf16x8*)(lds + PG8_SA(b, h) + aoff + m * 2048 + k * 1024); } while (0)
; #define PG8_LDB(dst, b, h) do { _Pragma("unroll") for (int n = 0; n < 2; ++n) _Pragma("unroll") for (int k = 0; k < 2; ++k) dst[n][k] = *(const PG8_LAS bf16x8*)(lds + PG8_SB(b, h) + boff + n * 2048 + k * 1024); } while (0)
; #define PG8_MMA(ai, bj, At, Bt) do { __builtin_amdgcn_s_setprio(1); _Pragma("unroll") for (int m = 0; m < 4; ++m) _Pragma("unroll") for (int n = 0; n < 2; ++n) _Pragma("unroll") for (int k = 0; k < 2; ++k) \
;         acc[ai][bj][m][n] = __builtin_amdgcn_mfma_f32_16x16x32_bf16(Bt[n][k], At[m][k], acc[ai][bj][m][n], 0, 0, 0); __builtin_amdgcn_s_setprio(0); } while (0)
; #define PG8_WAIT_V(n) asm volatile("s_waitcnt vmcnt(" #n ")" ::: "memory")
; #define PG8_WAIT_L(n) asm volatile("s_waitcnt lgkmcnt(" #n ")" ::: "memory")
; #define PG8_BAR __builtin_amdgcn_s_barrier()
; template <class Epi, class Sched, bool APERM>
; __device__ __forceinline__ void gemm_phase(PG8_LAS unsigned char* lds, const Gemm g, const Sched& S, const Epi& E) {
;     ...
;         for (int t = 0; t < nt; t += 2) {
;             const bool last = (t == nt - 2);
;             const char* a1 = cA + (size_t)(t + 1) * kstep;
;             const char* a2 = last ? nA : cA + (size_t)(t + 2) * kstep; const char* b2 = last ? nB : cB + (size_t)(t + 2) * kstep;
;             const char* a3 = a2 + kstep; const char* b3 = b2 + kstep;
;             if (last && has_next) S.a_ready(nxt);
;             PG8_LDB(B0, 0, 0); PG8_LDB(B1, 0, 1); PG8_SCHED; PG8_LDA(At, 0, 0); PG8_STAGE(PG8_SA(1, 1), a1 + hstepA, voffA);
;             PG8_WAIT_V(8); PG8_WAIT_L(0); PG8_BAR; PG8_MMA(0, 0, At, B0); PG8_MMA(0, 1, At, B1); PG8_BAR; PG8_SCHED;
;             PG8_LDA(At, 0, 1); PG8_STAGE(PG8_SB(0, 0), b2, voffB); PG8_STAGE(PG8_SB(0, 1), b2 + hstep, voffB); PG8_STAGE(PG8_SA(0, 0), a2, voffA);
;             PG8_WAIT_V(8); PG8_WAIT_L(0); PG8_BAR; PG8_MMA(1, 0, At, B0); PG8_MMA(1, 1, At, B1); PG8_BAR; PG8_SCHED;
.LBB0_634:
	s_add_i32 s21, s20, 0x100
	s_and_b64 s[18:19], s[18:19], exec
	s_cselect_b32 s19, 0, s21
	s_cselect_b32 s18, 0, 0
	s_add_u32 s22, s12, s19
	s_addc_u32 s23, s13, s18
	s_add_i32 s59, 0, 0x10000
	s_add_u32 s24, s4, s19
	s_addc_u32 s25, s5, s18
	s_add_i32 s19, 0, 0x14000
	s_add_u32 s28, s14, s20
	s_addc_u32 s29, s15, 0
	s_add_i32 s58, s59, s35
	s_add_i32 m0, s7, 0xc000
	s_add_i32 s61, s7, 0xe000
	s_add_i32 s55, s58, 0x2000
	s_add_u32 s26, s24, 0x40000
	v_add_u32_e32 v154, s59, v140
	v_add_u32_e32 v170, s19, v140
	s_addc_u32 s27, s25, 0
	s_add_i32 s57, s19, s35
	ds_read_b128 v[142:145], v154
	ds_read_b128 v[146:149], v154 offset:1024
	ds_read_b128 v[150:153], v154 offset:2048
	ds_read_b128 v[154:157], v154 offset:3072
	ds_read_b128 v[158:161], v170
	ds_read_b128 v[162:165], v170 offset:1024
	ds_read_b128 v[166:169], v170 offset:2048
	ds_read_b128 v[170:173], v170 offset:3072
	s_add_i32 s56, s57, 0x2000
	s_add_i32 s54, 0, 0x18000
	s_add_i32 s51, 0, 0x1c000
	s_add_u32 s20, s22, 0x40000
	s_addc_u32 s21, s23, 0
	s_add_i32 s50, s54, s35
	s_add_i32 s49, s50, 0x2000
	s_add_u32 s18, s24, 0x40080
	s_addc_u32 s19, s25, 0
	s_add_i32 s60, s51, s35
	s_add_i32 s59, s60, 0x2000
	v_lshl_add_u64 v[222:223], s[28:29], 0, v[134:135]
	v_lshl_add_u64 v[222:223], v[222:223], 0, s[52:53]
	ds_read_b128 v[174:177], v141
	ds_read_b128 v[178:181], v141 offset:1024
	ds_read_b128 v[182:185], v141 offset:2048
	ds_read_b128 v[186:189], v141 offset:3072
	ds_read_b128 v[190:193], v141 offset:4096
	ds_read_b128 v[194:197], v141 offset:5120
	ds_read_b128 v[198:201], v141 offset:6144
	ds_read_b128 v[202:205], v141 offset:7168
	global_load_lds_dwordx4 v[222:223], off
	v_lshl_add_u64 v[222:223], s[28:29], 0, v[132:133]
	v_lshl_add_u64 v[222:223], v[222:223], 0, s[52:53]
	s_mov_b32 m0, s61
	s_nop 0
	global_load_lds_dwordx4 v[222:223], off
	s_waitcnt vmcnt(8)
	s_waitcnt lgkmcnt(0)
	s_barrier
	s_waitcnt lgkmcnt(0)
	v_mfma_f32_16x16x32_bf16 v[128:131], v[142:145], v[174:177], v[128:131]
	v_mfma_f32_16x16x32_bf16 v[124:127], v[150:153], v[174:177], v[124:127]
	v_mfma_f32_16x16x32_bf16 v[112:115], v[142:145], v[182:185], v[112:115]
	v_mfma_f32_16x16x32_bf16 v[108:111], v[150:153], v[182:185], v[108:111]
	v_mfma_f32_16x16x32_bf16 v[96:99], v[142:145], v[190:193], v[96:99]
	v_mfma_f32_16x16x32_bf16 v[92:95], v[150:153], v[190:193], v[92:95]
	v_mfma_f32_16x16x32_bf16 v[80:83], v[142:145], v[198:201], v[80:83]
	v_mfma_f32_16x16x32_bf16 v[76:79], v[150:153], v[198:201], v[76:79]
	v_mfma_f32_16x16x32_bf16 v[128:131], v[146:149], v[178:181], v[128:131]
	v_mfma_f32_16x16x32_bf16 v[124:127], v[154:157], v[178:181], v[124:127]
	v_mfma_f32_16x16x32_bf16 v[112:115], v[146:149], v[186:189], v[112:115]
	v_mfma_f32_16x16x32_bf16 v[108:111], v[154:157], v[186:189], v[108:111]
	v_mfma_f32_16x16x32_bf16 v[96:99], v[146:149], v[194:197], v[96:99]
	v_mfma_f32_16x16x32_bf16 v[92:95], v[154:157], v[194:197], v[92:95]
	v_mfma_f32_16x16x32_bf16 v[80:83], v[146:149], v[202:205], v[80:83]
	v_mfma_f32_16x16x32_bf16 v[76:79], v[154:157], v[202:205], v[76:79]
	v_mfma_f32_16x16x32_bf16 v[120:123], v[158:161], v[174:177], v[120:123]
	v_mfma_f32_16x16x32_bf16 v[116:119], v[166:169], v[174:177], v[116:119]
	v_mfma_f32_16x16x32_bf16 v[104:107], v[158:161], v[182:185], v[104:107]
	v_mfma_f32_16x16x32_bf16 v[100:103], v[166:169], v[182:185], v[100:103]
	v_mfma_f32_16x16x32_bf16 v[88:91], v[158:161], v[190:193], v[88:91]
	v_mfma_f32_16x16x32_bf16 v[84:87], v[166:169], v[190:193], v[84:87]
	v_mfma_f32_16x16x32_bf16 v[72:75], v[158:161], v[198:201], v[72:75]
	v_mfma_f32_16x16x32_bf16 v[68:71], v[166:169], v[198:201], v[68:71]
	v_mfma_f32_16x16x32_bf16 v[120:123], v[162:165], v[178:181], v[120:123]
	v_mfma_f32_16x16x32_bf16 v[116:119], v[170:173], v[178:181], v[116:119]
	v_mfma_f32_16x16x32_bf16 v[104:107], v[162:165], v[186:189], v[104:107]
	v_mfma_f32_16x16x32_bf16 v[100:103], v[170:173], v[186:189], v[100:103]
	v_mfma_f32_16x16x32_bf16 v[88:91], v[162:165], v[194:197], v[88:91]
	v_mfma_f32_16x16x32_bf16 v[84:87], v[170:173], v[194:197], v[84:87]
	v_mfma_f32_16x16x32_bf16 v[72:75], v[162:165], v[202:205], v[72:75]
	v_mfma_f32_16x16x32_bf16 v[68:71], v[170:173], v[202:205], v[68:71]
	s_barrier
	s_mov_b32 m0, s58
	v_lshl_add_u64 v[222:223], s[24:25], 0, v[2:3]
	ds_read_b128 v[174:177], v141 offset:16384
	ds_read_b128 v[178:181], v141 offset:17408
	ds_read_b128 v[182:185], v141 offset:18432
	ds_read_b128 v[186:189], v141 offset:19456
	ds_read_b128 v[190:193], v141 offset:20480
	ds_read_b128 v[194:197], v141 offset:21504
	ds_read_b128 v[198:201], v141 offset:22528
	ds_read_b128 v[202:205], v141 offset:23552
	global_load_lds_dwordx4 v[222:223], off
	v_lshl_add_u64 v[230:231], s[24:25], 0, v[0:1]
	s_mov_b32 m0, s55
	v_lshl_add_u64 v[232:233], s[26:27], 0, v[2:3]
	global_load_lds_dwordx4 v[230:231], off
	s_mov_b32 m0, s57
	v_lshl_add_u64 v[234:235], s[22:23], 0, v[132:133]
	global_load_lds_dwordx4 v[232:233], off
	v_lshl_add_u64 v[232:233], s[26:27], 0, v[0:1]
	s_mov_b32 m0, s56
	s_nop 0
	global_load_lds_dwordx4 v[232:233], off
	v_lshl_add_u64 v[232:233], s[22:23], 0, v[134:135]
	s_mov_b32 m0, s7
	s_nop 0
	global_load_lds_dwordx4 v[232:233], off
	s_mov_b32 m0, s43
	s_nop 0
	global_load_lds_dwordx4 v[234:235], off
	s_waitcnt vmcnt(8)
	s_waitcnt lgkmcnt(0)
	s_barrier
; #define PG8_STAGE(bufoff, gbase, voff) do { _Pragma("unroll") for (int _i = 0; _i < 2; ++_i) \
;         __builtin_amdgcn_global_load_lds((const unsigned*)((const char*)(gbase) + (voff)[_i]), (PG8_LAS unsigned*)(lds + (bufoff) + ldsw + _i * 8192), 16, 0, 0); } while (0)
; #define PG8_LDA(dst, b, h) do { _Pragma("unroll") for (int m = 0; m < 4; ++m) _Pragma("unroll") for (int k = 0; k < 2; ++k) dst[m][k] = *(const PG8_LAS bf16x8*)(lds + PG8_SA(b, h) + aoff + m * 2048 + k * 1024); } while (0)
; #define PG8_LDB(dst, b, h) do { _Pragma("unroll") for (int n = 0; n < 2; ++n) _Pragma("unroll") for (int k = 0; k < 2; ++k) dst[n][k] = *(const PG8_LAS bf16x8*)(lds + PG8_SB(b, h) + boff + n * 2048 + k * 1024); } while (0)
; #define PG8_MMA(ai, bj, At, Bt) do { __builtin_amdgcn_s_setprio(1); _Pragma("unroll") for (int m = 0; m < 4; ++m) _Pragma("unroll") for (int n = 0; n < 2; ++n) _Pragma("unroll") for (int k = 0; k < 2; ++k) \
;         acc[ai][bj][m][n] = __builtin_amdgcn_mfma_f32_16x16x32_bf16(Bt[n][k], At[m][k], acc[ai][bj][m][n], 0, 0, 0); __builtin_amdgcn_s_setprio(0); } while (0)
; #define PG8_WAIT_V(n) asm volatile("s_waitcnt vmcnt(" #n ")" ::: "memory")
; #define PG8_WAIT_L(n) asm volatile("s_waitcnt lgkmcnt(" #n ")" ::: "memory")
; #define PG8_BAR __builtin_amdgcn_s_barrier()
; #define PG8_SCHED __builtin_amdgcn_sched_barrier(0)
; template <class Epi, class Sched, bool APERM>
; __device__ __forceinline__ void gemm_phase(PG8_LAS unsigned char* lds, const Gemm g, const Sched& S, const Epi& E) {
;     ...
;             PG8_WAIT_V(8); PG8_WAIT_L(0); PG8_BAR; PG8_MMA(1, 0, At, B0); PG8_MMA(1, 1, At, B1); PG8_BAR; PG8_SCHED;
;             PG8_LDB(B0, 1, 0); PG8_LDB(B1, 1, 1); PG8_SCHED; PG8_LDA(At, 1, 0); PG8_STAGE(PG8_SA(0, 1), a2 + hstepA, voffA);
;             PG8_WAIT_V(8); PG8_WAIT_L(0); PG8_BAR; PG8_MMA(0, 0, At, B0); PG8_MMA(0, 1, At, B1); PG8_BAR; PG8_SCHED;
	s_waitcnt lgkmcnt(0)
	v_mfma_f32_16x16x32_bf16 v[64:67], v[142:145], v[174:177], v[64:67]
	v_mfma_f32_16x16x32_bf16 v[60:63], v[150:153], v[174:177], v[60:63]
	v_mfma_f32_16x16x32_bf16 v[48:51], v[142:145], v[182:185], v[48:51]
	v_mfma_f32_16x16x32_bf16 v[44:47], v[150:153], v[182:185], v[44:47]
	v_mfma_f32_16x16x32_bf16 v[32:35], v[142:145], v[190:193], v[32:35]
	v_mfma_f32_16x16x32_bf16 v[28:31], v[150:153], v[190:193], v[28:31]
	v_mfma_f32_16x16x32_bf16 v[16:19], v[142:145], v[198:201], v[16:19]
	v_mfma_f32_16x16x32_bf16 v[12:15], v[150:153], v[198:201], v[12:15]
	v_mfma_f32_16x16x32_bf16 v[64:67], v[146:149], v[178:181], v[64:67]
	v_mfma_f32_16x16x32_bf16 v[60:63], v[154:157], v[178:181], v[60:63]
	v_mfma_f32_16x16x32_bf16 v[48:51], v[146:149], v[186:189], v[48:51]
	v_mfma_f32_16x16x32_bf16 v[44:47], v[154:157], v[186:189], v[44:47]
	v_mfma_f32_16x16x32_bf16 v[32:35], v[146:149], v[194:197], v[32:35]
	v_mfma_f32_16x16x32_bf16 v[28:31], v[154:157], v[194:197], v[28:31]
	v_mfma_f32_16x16x32_bf16 v[16:19], v[146:149], v[202:205], v[16:19]
	v_mfma_f32_16x16x32_bf16 v[12:15], v[154:157], v[202:205], v[12:15]
	v_mfma_f32_16x16x32_bf16 v[56:59], v[158:161], v[174:177], v[56:59]
	v_mfma_f32_16x16x32_bf16 v[52:55], v[166:169], v[174:177], v[52:55]
	v_mfma_f32_16x16x32_bf16 v[40:43], v[158:161], v[182:185], v[40:43]
	v_mfma_f32_16x16x32_bf16 v[36:39], v[166:169], v[182:185], v[36:39]
	v_mfma_f32_16x16x32_bf16 v[24:27], v[158:161], v[190:193], v[24:27]
	v_mfma_f32_16x16x32_bf16 v[20:23], v[166:169], v[190:193], v[20:23]
	v_mfma_f32_16x16x32_bf16 v[8:11], v[158:161], v[198:201], v[8:11]
	v_mfma_f32_16x16x32_bf16 v[4:7], v[166:169], v[198:201], v[4:7]
	v_mfma_f32_16x16x32_bf16 v[56:59], v[162:165], v[178:181], v[56:59]
	v_mfma_f32_16x16x32_bf16 v[52:55], v[170:173], v[178:181], v[52:55]
	v_mfma_f32_16x16x32_bf16 v[40:43], v[162:165], v[186:189], v[40:43]
	v_mfma_f32_16x16x32_bf16 v[36:39], v[170:173], v[186:189], v[36:39]
	v_mfma_f32_16x16x32_bf16 v[24:27], v[162:165], v[194:197], v[24:27]
	v_mfma_f32_16x16x32_bf16 v[20:23], v[170:173], v[194:197], v[20:23]
	v_mfma_f32_16x16x32_bf16 v[8:11], v[162:165], v[202:205], v[8:11]
	v_mfma_f32_16x16x32_bf16 v[4:7], v[170:173], v[202:205], v[4:7]
	s_barrier
	v_add_u32_e32 v154, s54, v140
	v_add_u32_e32 v170, s51, v140
	ds_read_b128 v[142:145], v154
	ds_read_b128 v[146:149], v154 offset:1024
	ds_read_b128 v[150:153], v154 offset:2048
	ds_read_b128 v[154:157], v154 offset:3072
	ds_read_b128 v[158:161], v170
	ds_read_b128 v[162:165], v170 offset:1024
	ds_read_b128 v[166:169], v170 offset:2048
	ds_read_b128 v[170:173], v170 offset:3072
	s_mov_b32 m0, s44
	v_lshl_add_u64 v[236:237], s[20:21], 0, v[134:135]
	ds_read_b128 v[174:177], v141 offset:32768
	ds_read_b128 v[178:181], v141 offset:33792
	ds_read_b128 v[182:185], v141 offset:34816
	ds_read_b128 v[186:189], v141 offset:35840
	ds_read_b128 v[190:193], v141 offset:36864
	ds_read_b128 v[194:197], v141 offset:37888
	ds_read_b128 v[198:201], v141 offset:38912
	ds_read_b128 v[202:205], v141 offset:39936
	global_load_lds_dwordx4 v[236:237], off
	v_lshl_add_u64 v[236:237], s[20:21], 0, v[132:133]
	s_mov_b32 m0, s45
	s_nop 0
	global_load_lds_dwordx4 v[236:237], off
	s_waitcnt vmcnt(8)
	s_waitcnt lgkmcnt(0)
	s_barrier
	s_waitcnt lgkmcnt(0)
	v_mfma_f32_16x16x32_bf16 v[128:131], v[142:145], v[174:177], v[128:131]
	v_mfma_f32_16x16x32_bf16 v[124:127], v[150:153], v[174:177], v[124:127]
	v_mfma_f32_16x16x32_bf16 v[112:115], v[142:145], v[182:185], v[112:115]
	v_mfma_f32_16x16x32_bf16 v[108:111], v[150:153], v[182:185], v[108:111]
	v_mfma_f32_16x16x32_bf16 v[96:99], v[142:145], v[190:193], v[96:99]
	v_mfma_f32_16x16x32_bf16 v[92:95], v[150:153], v[190:193], v[92:95]
	v_mfma_f32_16x16x32_bf16 v[80:83], v[142:145], v[198:201], v[80:83]
	v_mfma_f32_16x16x32_bf16 v[76:79], v[150:153], v[198:201], v[76:79]
	v_mfma_f32_16x16x32_bf16 v[128:131], v[146:149], v[178:181], v[128:131]
	v_mfma_f32_16x16x32_bf16 v[124:127], v[154:157], v[178:181], v[124:127]
	v_mfma_f32_16x16x32_bf16 v[112:115], v[146:149], v[186:189], v[112:115]
	v_mfma_f32_16x16x32_bf16 v[108:111], v[154:157], v[186:189], v[108:111]
	v_mfma_f32_16x16x32_bf16 v[96:99], v[146:149], v[194:197], v[96:99]
	v_mfma_f32_16x16x32_bf16 v[92:95], v[154:157], v[194:197], v[92:95]
	v_mfma_f32_16x16x32_bf16 v[80:83], v[146:149], v[202:205], v[80:83]
	v_mfma_f32_16x16x32_bf16 v[76:79], v[154:157], v[202:205], v[76:79]
	v_mfma_f32_16x16x32_bf16 v[120:123], v[158:161], v[174:177], v[120:123]
	v_mfma_f32_16x16x32_bf16 v[116:119], v[166:169], v[174:177], v[116:119]
	v_mfma_f32_16x16x32_bf16 v[104:107], v[158:161], v[182:185], v[104:107]
	v_mfma_f32_16x16x32_bf16 v[100:103], v[166:169], v[182:185], v[100:103]
	v_mfma_f32_16x16x32_bf16 v[88:91], v[158:161], v[190:193], v[88:91]
	v_mfma_f32_16x16x32_bf16 v[84:87], v[166:169], v[190:193], v[84:87]
	v_mfma_f32_16x16x32_bf16 v[72:75], v[158:161], v[198:201], v[72:75]
	v_mfma_f32_16x16x32_bf16 v[68:71], v[166:169], v[198:201], v[68:71]
	v_mfma_f32_16x16x32_bf16 v[120:123], v[162:165], v[178:181], v[120:123]
	v_mfma_f32_16x16x32_bf16 v[116:119], v[170:173], v[178:181], v[116:119]
	v_mfma_f32_16x16x32_bf16 v[104:107], v[162:165], v[186:189], v[104:107]
	v_mfma_f32_16x16x32_bf16 v[100:103], v[170:173], v[186:189], v[100:103]
	v_mfma_f32_16x16x32_bf16 v[88:91], v[162:165], v[194:197], v[88:91]
	v_mfma_f32_16x16x32_bf16 v[84:87], v[170:173], v[194:197], v[84:87]
	v_mfma_f32_16x16x32_bf16 v[72:75], v[162:165], v[202:205], v[72:75]
	v_mfma_f32_16x16x32_bf16 v[68:71], v[170:173], v[202:205], v[68:71]
	s_barrier
; #define PG8_STAGE(bufoff, gbase, voff) do { _Pragma("unroll") for (int _i = 0; _i < 2; ++_i) \
;         __builtin_amdgcn_global_load_lds((const unsigned*)((const char*)(gbase) + (voff)[_i]), (PG8_LAS unsigned*)(lds + (bufoff) + ldsw + _i * 8192), 16, 0, 0); } while (0)
; #define PG8_LDA(dst, b, h) do { _Pragma("unroll") for (int m = 0; m < 4; ++m) _Pragma("unroll") for (int k = 0; k < 2; ++k) dst[m][k] = *(const PG8_LAS bf16x8*)(lds + PG8_SA(b, h) + aoff + m * 2048 + k * 1024); } while (0)
; #define PG8_MMA(ai, bj, At, Bt) do { __builtin_amdgcn_s_setprio(1); _Pragma("unroll") for (int m = 0; m < 4; ++m) _Pragma("unroll") for (int n = 0; n < 2; ++n) _Pragma("unroll") for (int k = 0; k < 2; ++k) \
;         acc[ai][bj][m][n] = __builtin_amdgcn_mfma_f32_16x16x32_bf16(Bt[n][k], At[m][k], acc[ai][bj][m][n], 0, 0, 0); __builtin_amdgcn_s_setprio(0); } while (0)
; #define PG8_WAIT_V(n) asm volatile("s_waitcnt vmcnt(" #n ")" ::: "memory")
; #define PG8_WAIT_L(n) asm volatile("s_waitcnt lgkmcnt(" #n ")" ::: "memory")
; #define PG8_BAR __builtin_amdgcn_s_barrier()
; #define PG8_SCHED __builtin_amdgcn_sched_barrier(0)
; template <class Epi, class Sched, bool APERM>
; __device__ __forceinline__ void gemm_phase(PG8_LAS unsigned char* lds, const Gemm g, const Sched& S, const Epi& E) {
;     ...
;             PG8_LDA(At, 1, 1); PG8_STAGE(PG8_SB(1, 0), b3, voffB); PG8_STAGE(PG8_SB(1, 1), b3 + hstep, voffB); PG8_STAGE(PG8_SA(1, 0), a3, voffA);
;             PG8_WAIT_V(8); PG8_WAIT_L(0); PG8_BAR; PG8_MMA(1, 0, At, B0); PG8_MMA(1, 1, At, B1); PG8_BAR; PG8_SCHED;
;         }
;         if (wr == 0) PG8_BAR;
	s_mov_b32 m0, s50
	v_lshl_add_u64 v[222:223], v[222:223], 0, s[52:53]
	ds_read_b128 v[174:177], v141 offset:49152
	ds_read_b128 v[178:181], v141 offset:50176
	ds_read_b128 v[182:185], v141 offset:51200
	ds_read_b128 v[186:189], v141 offset:52224
	ds_read_b128 v[190:193], v141 offset:53248
	ds_read_b128 v[194:197], v141 offset:54272
	ds_read_b128 v[198:201], v141 offset:55296
	ds_read_b128 v[202:205], v141 offset:56320
	global_load_lds_dwordx4 v[222:223], off
	v_lshl_add_u64 v[222:223], v[230:231], 0, s[52:53]
	s_mov_b32 m0, s49
	s_nop 0
	global_load_lds_dwordx4 v[222:223], off
	v_lshl_add_u64 v[222:223], s[18:19], 0, v[2:3]
	s_mov_b32 m0, s60
	s_nop 0
	global_load_lds_dwordx4 v[222:223], off
	v_lshl_add_u64 v[222:223], s[18:19], 0, v[0:1]
	s_mov_b32 m0, s59
	s_nop 0
	global_load_lds_dwordx4 v[222:223], off
	v_lshl_add_u64 v[222:223], v[232:233], 0, s[52:53]
	s_mov_b32 m0, s46
	s_nop 0
	global_load_lds_dwordx4 v[222:223], off
	v_lshl_add_u64 v[222:223], v[234:235], 0, s[52:53]
	s_mov_b32 m0, s47
	s_nop 0
	global_load_lds_dwordx4 v[222:223], off
	s_waitcnt vmcnt(8)
	s_waitcnt lgkmcnt(0)
	s_barrier
	s_waitcnt lgkmcnt(0)
	v_mfma_f32_16x16x32_bf16 v[64:67], v[142:145], v[174:177], v[64:67]
	v_mfma_f32_16x16x32_bf16 v[60:63], v[150:153], v[174:177], v[60:63]
	v_mfma_f32_16x16x32_bf16 v[48:51], v[142:145], v[182:185], v[48:51]
	v_mfma_f32_16x16x32_bf16 v[44:47], v[150:153], v[182:185], v[44:47]
	v_mfma_f32_16x16x32_bf16 v[32:35], v[142:145], v[190:193], v[32:35]
	v_mfma_f32_16x16x32_bf16 v[28:31], v[150:153], v[190:193], v[28:31]
	v_mfma_f32_16x16x32_bf16 v[16:19], v[142:145], v[198:201], v[16:19]
	v_mfma_f32_16x16x32_bf16 v[12:15], v[150:153], v[198:201], v[12:15]
	v_mfma_f32_16x16x32_bf16 v[64:67], v[146:149], v[178:181], v[64:67]
	v_mfma_f32_16x16x32_bf16 v[60:63], v[154:157], v[178:181], v[60:63]
	v_mfma_f32_16x16x32_bf16 v[48:51], v[146:149], v[186:189], v[48:51]
	v_mfma_f32_16x16x32_bf16 v[44:47], v[154:157], v[186:189], v[44:47]
	v_mfma_f32_16x16x32_bf16 v[32:35], v[146:149], v[194:197], v[32:35]
	v_mfma_f32_16x16x32_bf16 v[28:31], v[154:157], v[194:197], v[28:31]
	v_mfma_f32_16x16x32_bf16 v[16:19], v[146:149], v[202:205], v[16:19]
	v_mfma_f32_16x16x32_bf16 v[12:15], v[154:157], v[202:205], v[12:15]
	v_mfma_f32_16x16x32_bf16 v[56:59], v[158:161], v[174:177], v[56:59]
	v_mfma_f32_16x16x32_bf16 v[52:55], v[166:169], v[174:177], v[52:55]
	v_mfma_f32_16x16x32_bf16 v[40:43], v[158:161], v[182:185], v[40:43]
	v_mfma_f32_16x16x32_bf16 v[36:39], v[166:169], v[182:185], v[36:39]
	v_mfma_f32_16x16x32_bf16 v[24:27], v[158:161], v[190:193], v[24:27]
	v_mfma_f32_16x16x32_bf16 v[20:23], v[166:169], v[190:193], v[20:23]
	v_mfma_f32_16x16x32_bf16 v[8:11], v[158:161], v[198:201], v[8:11]
	v_mfma_f32_16x16x32_bf16 v[4:7], v[166:169], v[198:201], v[4:7]
	v_mfma_f32_16x16x32_bf16 v[56:59], v[162:165], v[178:181], v[56:59]
	v_mfma_f32_16x16x32_bf16 v[52:55], v[170:173], v[178:181], v[52:55]
	v_mfma_f32_16x16x32_bf16 v[40:43], v[162:165], v[186:189], v[40:43]
	v_mfma_f32_16x16x32_bf16 v[36:39], v[170:173], v[186:189], v[36:39]
	v_mfma_f32_16x16x32_bf16 v[24:27], v[162:165], v[194:197], v[24:27]
	v_mfma_f32_16x16x32_bf16 v[20:23], v[170:173], v[194:197], v[20:23]
	v_mfma_f32_16x16x32_bf16 v[8:11], v[162:165], v[202:205], v[8:11]
	v_mfma_f32_16x16x32_bf16 v[4:7], v[170:173], v[202:205], v[4:7]
	s_barrier
	s_andn2_b64 vcc, exec, s[16:17]
	s_mov_b64 s[18:19], -1
	s_mov_b64 s[16:17], 0
	s_movk_i32 s20, 0x100
	s_cbranch_vccz .LBB0_634
	s_mov_b32 s2, s38
	s_cmpk_lt_u32 s34, 0x100
	s_cbranch_scc0 .LBB0_637
	s_barrier

; #define PG8_STAGE(bufoff, gbase, voff) do { _Pragma("unroll") for (int _i = 0; _i < 2; ++_i) \
;         __builtin_amdgcn_global_load_lds((const unsigned*)((const char*)(gbase) + (voff)[_i]), (PG8_LAS unsigned*)(lds + (bufoff) + ldsw + _i * 8192), 16, 0, 0); } while (0)
; #define PG8_LDA(dst, b, h) do { _Pragma("unroll") for (int m = 0; m < 4; ++m) _Pragma("unroll") for (int k = 0; k < 2; ++k) dst[m][k] = *(const PG8_LAS bf16x8*)(lds + PG8_SA(b, h) + aoff + m * 2048 + k * 1024); } while (0)
; #define PG8_LDB(dst, b, h) do { _Pragma("unroll") for (int n = 0; n < 2; ++n) _Pragma("unroll") for (int k = 0; k < 2; ++k) dst[n][k] = *(const PG8_LAS bf16x8*)(lds + PG8_SB(b, h) + boff + n * 2048 + k * 1024); } while (0)
; #define PG8_MMA(ai, bj, At, Bt) do { __builtin_amdgcn_s_setprio(1); _Pragma("unroll") for (int m = 0; m < 4; ++m) _Pragma("unroll") for (int n = 0; n < 2; ++n) _Pragma("unroll") for (int k = 0; k < 2; ++k) \
;         acc[ai][bj][m][n] = __builtin_amdgcn_mfma_f32_16x16x32_bf16(Bt[n][k], At[m][k], acc[ai][bj][m][n], 0, 0, 0); __builtin_amdgcn_s_setprio(0); } while (0)
; #define PG8_WAIT_V(n) asm volatile("s_waitcnt vmcnt(" #n ")" ::: "memory")
; #define PG8_WAIT_L(n) asm volatile("s_waitcnt lgkmcnt(" #n ")" ::: "memory")
; #define PG8_BAR __builtin_amdgcn_s_barrier()
; template <class Epi, class Sched, bool APERM>
; __device__ __forceinline__ void gemm_phase(PG8_LAS unsigned char* lds, const Gemm g, const Sched& S, const Epi& E) {
;     ...
;         for (int t = 0; t < nt; t += 2) {
;             const bool last = (t == nt - 2);
;             const char* a1 = cA + (size_t)(t + 1) * kstep;
;             const char* a2 = last ? nA : cA + (size_t)(t + 2) * kstep; const char* b2 = last ? nB : cB + (size_t)(t + 2) * kstep;
;             const char* a3 = a2 + kstep; const char* b3 = b2 + kstep;
;             if (last && has_next) S.a_ready(nxt);
;             PG8_LDB(B0, 0, 0); PG8_LDB(B1, 0, 1); PG8_SCHED; PG8_LDA(At, 0, 0); PG8_STAGE(PG8_SA(1, 1), a1 + hstepA, voffA);
;             PG8_WAIT_V(8); PG8_WAIT_L(0); PG8_BAR; PG8_MMA(0, 0, At, B0); PG8_MMA(0, 1, At, B1); PG8_BAR; PG8_SCHED;
;             PG8_LDA(At, 0, 1); PG8_STAGE(PG8_SB(0, 0), b2, voffB); PG8_STAGE(PG8_SB(0, 1), b2 + hstep, voffB); PG8_STAGE(PG8_SA(0, 0), a2, voffA);
;             PG8_WAIT_V(8); PG8_WAIT_L(0); PG8_BAR; PG8_MMA(1, 0, At, B0); PG8_MMA(1, 1, At, B1); PG8_BAR; PG8_SCHED;
.LBB0_686:
	s_add_u32 s28, s26, 0xfffc0080
	s_addc_u32 s29, s27, -1
	s_add_i32 s60, 0, 0x10000
	s_cmp_eq_u32 s59, 12
	s_cselect_b32 s35, s17, s29
	s_cselect_b32 s34, s23, s28
	s_cselect_b32 s29, s15, s58
	s_cselect_b32 s28, s56, s57
	s_add_i32 s62, 0, 0x14000
	v_add_u32_e32 v152, s60, v159
	v_add_u32_e32 v156, s62, v159
	ds_read_b128 v[132:135], v152
	ds_read_b128 v[136:139], v152 offset:1024
	ds_read_b128 v[148:151], v152 offset:2048
	ds_read_b128 v[152:155], v152 offset:3072
	ds_read_b128 v[162:165], v156
	ds_read_b128 v[166:169], v156 offset:1024
	ds_read_b128 v[170:173], v156 offset:2048
	ds_read_b128 v[174:177], v156 offset:3072
	v_lshl_add_u64 v[156:157], s[26:27], 0, v[144:145]
	s_add_i32 m0, s25, 0xc000
	ds_read_b128 v[178:181], v161
	ds_read_b128 v[182:185], v161 offset:1024
	ds_read_b128 v[186:189], v161 offset:2048
	ds_read_b128 v[190:193], v161 offset:3072
	ds_read_b128 v[194:197], v161 offset:4096
	ds_read_b128 v[198:201], v161 offset:5120
	ds_read_b128 v[202:205], v161 offset:6144
	ds_read_b128 v[230:233], v161 offset:7168
	global_load_lds_dwordx4 v[156:157], off
	v_lshl_add_u64 v[156:157], s[26:27], 0, v[146:147]
	s_add_i32 m0, s25, 0xe000
	s_nop 0
	global_load_lds_dwordx4 v[156:157], off
	s_waitcnt vmcnt(8)
	s_waitcnt lgkmcnt(0)
	s_barrier
	s_waitcnt lgkmcnt(0)
	v_mfma_f32_16x16x32_bf16 v[128:131], v[132:135], v[178:181], v[128:131]
	v_mfma_f32_16x16x32_bf16 v[124:127], v[148:151], v[178:181], v[124:127]
	v_mfma_f32_16x16x32_bf16 v[112:115], v[132:135], v[186:189], v[112:115]
	v_mfma_f32_16x16x32_bf16 v[108:111], v[148:151], v[186:189], v[108:111]
	v_mfma_f32_16x16x32_bf16 v[96:99], v[132:135], v[194:197], v[96:99]
	v_mfma_f32_16x16x32_bf16 v[92:95], v[148:151], v[194:197], v[92:95]
	v_mfma_f32_16x16x32_bf16 v[80:83], v[132:135], v[202:205], v[80:83]
	v_mfma_f32_16x16x32_bf16 v[76:79], v[148:151], v[202:205], v[76:79]
	v_mfma_f32_16x16x32_bf16 v[128:131], v[136:139], v[182:185], v[128:131]
	v_mfma_f32_16x16x32_bf16 v[124:127], v[152:155], v[182:185], v[124:127]
	v_mfma_f32_16x16x32_bf16 v[112:115], v[136:139], v[190:193], v[112:115]
	v_mfma_f32_16x16x32_bf16 v[108:111], v[152:155], v[190:193], v[108:111]
	v_mfma_f32_16x16x32_bf16 v[96:99], v[136:139], v[198:201], v[96:99]
	v_mfma_f32_16x16x32_bf16 v[92:95], v[152:155], v[198:201], v[92:95]
	v_mfma_f32_16x16x32_bf16 v[80:83], v[136:139], v[230:233], v[80:83]
	v_mfma_f32_16x16x32_bf16 v[76:79], v[152:155], v[230:233], v[76:79]
	v_mfma_f32_16x16x32_bf16 v[120:123], v[162:165], v[178:181], v[120:123]
	v_mfma_f32_16x16x32_bf16 v[116:119], v[170:173], v[178:181], v[116:119]
	v_mfma_f32_16x16x32_bf16 v[104:107], v[162:165], v[186:189], v[104:107]
	v_mfma_f32_16x16x32_bf16 v[100:103], v[170:173], v[186:189], v[100:103]
	v_mfma_f32_16x16x32_bf16 v[88:91], v[162:165], v[194:197], v[88:91]
	v_mfma_f32_16x16x32_bf16 v[84:87], v[170:173], v[194:197], v[84:87]
	v_mfma_f32_16x16x32_bf16 v[72:75], v[162:165], v[202:205], v[72:75]
	v_mfma_f32_16x16x32_bf16 v[68:71], v[170:173], v[202:205], v[68:71]
	v_mfma_f32_16x16x32_bf16 v[120:123], v[166:169], v[182:185], v[120:123]
	v_mfma_f32_16x16x32_bf16 v[116:119], v[174:177], v[182:185], v[116:119]
	v_mfma_f32_16x16x32_bf16 v[104:107], v[166:169], v[190:193], v[104:107]
	v_mfma_f32_16x16x32_bf16 v[100:103], v[174:177], v[190:193], v[100:103]
	v_mfma_f32_16x16x32_bf16 v[88:91], v[166:169], v[198:201], v[88:91]
	v_mfma_f32_16x16x32_bf16 v[84:87], v[174:177], v[198:201], v[84:87]
	v_mfma_f32_16x16x32_bf16 v[72:75], v[166:169], v[230:233], v[72:75]
	v_mfma_f32_16x16x32_bf16 v[68:71], v[174:177], v[230:233], v[68:71]
	s_barrier
	s_add_i32 s60, s60, s40
	v_lshl_add_u64 v[156:157], s[28:29], 0, v[2:3]
	s_mov_b32 m0, s60
	ds_read_b128 v[178:181], v161 offset:16384
	ds_read_b128 v[182:185], v161 offset:17408
	ds_read_b128 v[186:189], v161 offset:18432
	ds_read_b128 v[190:193], v161 offset:19456
	ds_read_b128 v[194:197], v161 offset:20480
	ds_read_b128 v[198:201], v161 offset:21504
	ds_read_b128 v[202:205], v161 offset:22528
	ds_read_b128 v[230:233], v161 offset:23552
	global_load_lds_dwordx4 v[156:157], off
	s_add_i32 m0, s60, 0x2000
	s_add_u32 s60, s28, 0x40000
	v_lshl_add_u64 v[222:223], s[28:29], 0, v[142:143]
	s_addc_u32 s61, s29, 0
	s_add_i32 s62, s62, s40
	global_load_lds_dwordx4 v[222:223], off
	v_lshl_add_u64 v[234:235], s[60:61], 0, v[2:3]
	s_mov_b32 m0, s62
	v_lshl_add_u64 v[236:237], s[34:35], 0, v[140:141]
	global_load_lds_dwordx4 v[234:235], off
	v_lshl_add_u64 v[234:235], s[60:61], 0, v[142:143]
	s_add_i32 m0, s62, 0x2000
	s_nop 0
	global_load_lds_dwordx4 v[234:235], off
	v_lshl_add_u64 v[234:235], s[34:35], 0, v[0:1]
	s_mov_b32 m0, s25
	s_nop 0
	global_load_lds_dwordx4 v[234:235], off
	s_mov_b32 m0, s41
	s_nop 0
	global_load_lds_dwordx4 v[236:237], off
	s_waitcnt vmcnt(8)
	s_waitcnt lgkmcnt(0)
	s_barrier
; #define PG8_STAGE(bufoff, gbase, voff) do { _Pragma("unroll") for (int _i = 0; _i < 2; ++_i) \
;         __builtin_amdgcn_global_load_lds((const unsigned*)((const char*)(gbase) + (voff)[_i]), (PG8_LAS unsigned*)(lds + (bufoff) + ldsw + _i * 8192), 16, 0, 0); } while (0)
; #define PG8_LDA(dst, b, h) do { _Pragma("unroll") for (int m = 0; m < 4; ++m) _Pragma("unroll") for (int k = 0; k < 2; ++k) dst[m][k] = *(const PG8_LAS bf16x8*)(lds + PG8_SA(b, h) + aoff + m * 2048 + k * 1024); } while (0)
; #define PG8_LDB(dst, b, h) do { _Pragma("unroll") for (int n = 0; n < 2; ++n) _Pragma("unroll") for (int k = 0; k < 2; ++k) dst[n][k] = *(const PG8_LAS bf16x8*)(lds + PG8_SB(b, h) + boff + n * 2048 + k * 1024); } while (0)
; #define PG8_MMA(ai, bj, At, Bt) do { __builtin_amdgcn_s_setprio(1); _Pragma("unroll") for (int m = 0; m < 4; ++m) _Pragma("unroll") for (int n = 0; n < 2; ++n) _Pragma("unroll") for (int k = 0; k < 2; ++k) \
;         acc[ai][bj][m][n] = __builtin_amdgcn_mfma_f32_16x16x32_bf16(Bt[n][k], At[m][k], acc[ai][bj][m][n], 0, 0, 0); __builtin_amdgcn_s_setprio(0); } while (0)
; #define PG8_WAIT_V(n) asm volatile("s_waitcnt vmcnt(" #n ")" ::: "memory")
; #define PG8_WAIT_L(n) asm volatile("s_waitcnt lgkmcnt(" #n ")" ::: "memory")
; #define PG8_BAR __builtin_amdgcn_s_barrier()
; #define PG8_SCHED __builtin_amdgcn_sched_barrier(0)
; template <class Epi, class Sched, bool APERM>
; __device__ __forceinline__ void gemm_phase(PG8_LAS unsigned char* lds, const Gemm g, const Sched& S, const Epi& E) {
;     ...
;             PG8_WAIT_V(8); PG8_WAIT_L(0); PG8_BAR; PG8_MMA(1, 0, At, B0); PG8_MMA(1, 1, At, B1); PG8_BAR; PG8_SCHED;
;             PG8_LDB(B0, 1, 0); PG8_LDB(B1, 1, 1); PG8_SCHED; PG8_LDA(At, 1, 0); PG8_STAGE(PG8_SA(0, 1), a2 + hstepA, voffA);
;             PG8_WAIT_V(8); PG8_WAIT_L(0); PG8_BAR; PG8_MMA(0, 0, At, B0); PG8_MMA(0, 1, At, B1); PG8_BAR; PG8_SCHED;
	s_waitcnt lgkmcnt(0)
	v_mfma_f32_16x16x32_bf16 v[64:67], v[132:135], v[178:181], v[64:67]
	v_mfma_f32_16x16x32_bf16 v[60:63], v[148:151], v[178:181], v[60:63]
	v_mfma_f32_16x16x32_bf16 v[48:51], v[132:135], v[186:189], v[48:51]
	v_mfma_f32_16x16x32_bf16 v[44:47], v[148:151], v[186:189], v[44:47]
	v_mfma_f32_16x16x32_bf16 v[32:35], v[132:135], v[194:197], v[32:35]
	v_mfma_f32_16x16x32_bf16 v[28:31], v[148:151], v[194:197], v[28:31]
	v_mfma_f32_16x16x32_bf16 v[16:19], v[132:135], v[202:205], v[16:19]
	v_mfma_f32_16x16x32_bf16 v[12:15], v[148:151], v[202:205], v[12:15]
	v_mfma_f32_16x16x32_bf16 v[64:67], v[136:139], v[182:185], v[64:67]
	v_mfma_f32_16x16x32_bf16 v[60:63], v[152:155], v[182:185], v[60:63]
	v_mfma_f32_16x16x32_bf16 v[48:51], v[136:139], v[190:193], v[48:51]
	v_mfma_f32_16x16x32_bf16 v[44:47], v[152:155], v[190:193], v[44:47]
	v_mfma_f32_16x16x32_bf16 v[32:35], v[136:139], v[198:201], v[32:35]
	v_mfma_f32_16x16x32_bf16 v[28:31], v[152:155], v[198:201], v[28:31]
	v_mfma_f32_16x16x32_bf16 v[16:19], v[136:139], v[230:233], v[16:19]
	v_mfma_f32_16x16x32_bf16 v[12:15], v[152:155], v[230:233], v[12:15]
	v_mfma_f32_16x16x32_bf16 v[56:59], v[162:165], v[178:181], v[56:59]
	v_mfma_f32_16x16x32_bf16 v[52:55], v[170:173], v[178:181], v[52:55]
	v_mfma_f32_16x16x32_bf16 v[40:43], v[162:165], v[186:189], v[40:43]
	v_mfma_f32_16x16x32_bf16 v[36:39], v[170:173], v[186:189], v[36:39]
	v_mfma_f32_16x16x32_bf16 v[24:27], v[162:165], v[194:197], v[24:27]
	v_mfma_f32_16x16x32_bf16 v[20:23], v[170:173], v[194:197], v[20:23]
	v_mfma_f32_16x16x32_bf16 v[8:11], v[162:165], v[202:205], v[8:11]
	v_mfma_f32_16x16x32_bf16 v[4:7], v[170:173], v[202:205], v[4:7]
	v_mfma_f32_16x16x32_bf16 v[56:59], v[166:169], v[182:185], v[56:59]
	v_mfma_f32_16x16x32_bf16 v[52:55], v[174:177], v[182:185], v[52:55]
	v_mfma_f32_16x16x32_bf16 v[40:43], v[166:169], v[190:193], v[40:43]
	v_mfma_f32_16x16x32_bf16 v[36:39], v[174:177], v[190:193], v[36:39]
	v_mfma_f32_16x16x32_bf16 v[24:27], v[166:169], v[198:201], v[24:27]
	v_mfma_f32_16x16x32_bf16 v[20:23], v[174:177], v[198:201], v[20:23]
	v_mfma_f32_16x16x32_bf16 v[8:11], v[166:169], v[230:233], v[8:11]
	v_mfma_f32_16x16x32_bf16 v[4:7], v[174:177], v[230:233], v[4:7]
	s_barrier
	s_add_i32 s60, 0, 0x18000
	s_add_i32 s61, 0, 0x1c000
	v_add_u32_e32 v152, s60, v159
	v_add_u32_e32 v174, s61, v159
	ds_read_b128 v[132:135], v152
	ds_read_b128 v[136:139], v152 offset:1024
	ds_read_b128 v[148:151], v152 offset:2048
	ds_read_b128 v[152:155], v152 offset:3072
	ds_read_b128 v[162:165], v174
	ds_read_b128 v[166:169], v174 offset:1024
	ds_read_b128 v[170:173], v174 offset:2048
	ds_read_b128 v[174:177], v174 offset:3072
	s_add_u32 s34, s34, 0x40000
	s_addc_u32 s35, s35, 0
	s_mov_b32 m0, s43
	v_lshl_add_u64 v[238:239], s[34:35], 0, v[0:1]
	ds_read_b128 v[178:181], v161 offset:32768
	ds_read_b128 v[182:185], v161 offset:33792
	ds_read_b128 v[186:189], v161 offset:34816
	ds_read_b128 v[190:193], v161 offset:35840
	ds_read_b128 v[194:197], v161 offset:36864
	ds_read_b128 v[198:201], v161 offset:37888
	ds_read_b128 v[202:205], v161 offset:38912
	ds_read_b128 v[230:233], v161 offset:39936
	global_load_lds_dwordx4 v[238:239], off
	v_lshl_add_u64 v[238:239], s[34:35], 0, v[140:141]
	s_mov_b32 m0, s44
	s_nop 0
	global_load_lds_dwordx4 v[238:239], off
	s_waitcnt vmcnt(8)
	s_waitcnt lgkmcnt(0)
	s_barrier
	s_waitcnt lgkmcnt(0)
	v_mfma_f32_16x16x32_bf16 v[128:131], v[132:135], v[178:181], v[128:131]
	v_mfma_f32_16x16x32_bf16 v[124:127], v[148:151], v[178:181], v[124:127]
	v_mfma_f32_16x16x32_bf16 v[112:115], v[132:135], v[186:189], v[112:115]
	v_mfma_f32_16x16x32_bf16 v[108:111], v[148:151], v[186:189], v[108:111]
	v_mfma_f32_16x16x32_bf16 v[96:99], v[132:135], v[194:197], v[96:99]
	v_mfma_f32_16x16x32_bf16 v[92:95], v[148:151], v[194:197], v[92:95]
	v_mfma_f32_16x16x32_bf16 v[80:83], v[132:135], v[202:205], v[80:83]
	v_mfma_f32_16x16x32_bf16 v[76:79], v[148:151], v[202:205], v[76:79]
	v_mfma_f32_16x16x32_bf16 v[128:131], v[136:139], v[182:185], v[128:131]
	v_mfma_f32_16x16x32_bf16 v[124:127], v[152:155], v[182:185], v[124:127]
	v_mfma_f32_16x16x32_bf16 v[112:115], v[136:139], v[190:193], v[112:115]
	v_mfma_f32_16x16x32_bf16 v[108:111], v[152:155], v[190:193], v[108:111]
	v_mfma_f32_16x16x32_bf16 v[96:99], v[136:139], v[198:201], v[96:99]
	v_mfma_f32_16x16x32_bf16 v[92:95], v[152:155], v[198:201], v[92:95]
	v_mfma_f32_16x16x32_bf16 v[80:83], v[136:139], v[230:233], v[80:83]
	v_mfma_f32_16x16x32_bf16 v[76:79], v[152:155], v[230:233], v[76:79]
	v_mfma_f32_16x16x32_bf16 v[120:123], v[162:165], v[178:181], v[120:123]
	v_mfma_f32_16x16x32_bf16 v[116:119], v[170:173], v[178:181], v[116:119]
	v_mfma_f32_16x16x32_bf16 v[104:107], v[162:165], v[186:189], v[104:107]
	v_mfma_f32_16x16x32_bf16 v[100:103], v[170:173], v[186:189], v[100:103]
	v_mfma_f32_16x16x32_bf16 v[88:91], v[162:165], v[194:197], v[88:91]
	v_mfma_f32_16x16x32_bf16 v[84:87], v[170:173], v[194:197], v[84:87]
	v_mfma_f32_16x16x32_bf16 v[72:75], v[162:165], v[202:205], v[72:75]
	v_mfma_f32_16x16x32_bf16 v[68:71], v[170:173], v[202:205], v[68:71]
	v_mfma_f32_16x16x32_bf16 v[120:123], v[166:169], v[182:185], v[120:123]
	v_mfma_f32_16x16x32_bf16 v[116:119], v[174:177], v[182:185], v[116:119]
	v_mfma_f32_16x16x32_bf16 v[104:107], v[166:169], v[190:193], v[104:107]
	v_mfma_f32_16x16x32_bf16 v[100:103], v[174:177], v[190:193], v[100:103]
	v_mfma_f32_16x16x32_bf16 v[88:91], v[166:169], v[198:201], v[88:91]
	v_mfma_f32_16x16x32_bf16 v[84:87], v[174:177], v[198:201], v[84:87]
	v_mfma_f32_16x16x32_bf16 v[72:75], v[166:169], v[230:233], v[72:75]
	v_mfma_f32_16x16x32_bf16 v[68:71], v[174:177], v[230:233], v[68:71]
	s_barrier
; #define PG8_STAGE(bufoff, gbase, voff) do { _Pragma("unroll") for (int _i = 0; _i < 2; ++_i) \
;         __builtin_amdgcn_global_load_lds((const unsigned*)((const char*)(gbase) + (voff)[_i]), (PG8_LAS unsigned*)(lds + (bufoff) + ldsw + _i * 8192), 16, 0, 0); } while (0)
; #define PG8_LDA(dst, b, h) do { _Pragma("unroll") for (int m = 0; m < 4; ++m) _Pragma("unroll") for (int k = 0; k < 2; ++k) dst[m][k] = *(const PG8_LAS bf16x8*)(lds + PG8_SA(b, h) + aoff + m * 2048 + k * 1024); } while (0)
; #define PG8_MMA(ai, bj, At, Bt) do { __builtin_amdgcn_s_setprio(1); _Pragma("unroll") for (int m = 0; m < 4; ++m) _Pragma("unroll") for (int n = 0; n < 2; ++n) _Pragma("unroll") for (int k = 0; k < 2; ++k) \
;         acc[ai][bj][m][n] = __builtin_amdgcn_mfma_f32_16x16x32_bf16(Bt[n][k], At[m][k], acc[ai][bj][m][n], 0, 0, 0); __builtin_amdgcn_s_setprio(0); } while (0)
; #define PG8_WAIT_V(n) asm volatile("s_waitcnt vmcnt(" #n ")" ::: "memory")
; #define PG8_WAIT_L(n) asm volatile("s_waitcnt lgkmcnt(" #n ")" ::: "memory")
; #define PG8_BAR __builtin_amdgcn_s_barrier()
; #define PG8_SCHED __builtin_amdgcn_sched_barrier(0)
; template <class Epi, class Sched, bool APERM>
; __device__ __forceinline__ void gemm_phase(PG8_LAS unsigned char* lds, const Gemm g, const Sched& S, const Epi& E) {
;     ...
;             PG8_LDA(At, 1, 1); PG8_STAGE(PG8_SB(1, 0), b3, voffB); PG8_STAGE(PG8_SB(1, 1), b3 + hstep, voffB); PG8_STAGE(PG8_SA(1, 0), a3, voffA);
;             PG8_WAIT_V(8); PG8_WAIT_L(0); PG8_BAR; PG8_MMA(1, 0, At, B0); PG8_MMA(1, 1, At, B1); PG8_BAR; PG8_SCHED;
;         }
;         if (wr == 0) PG8_BAR;
	s_add_i32 s34, s60, s40
	v_lshl_add_u64 v[156:157], v[156:157], 0, s[52:53]
	s_mov_b32 m0, s34
	ds_read_b128 v[178:181], v161 offset:49152
	ds_read_b128 v[182:185], v161 offset:50176
	ds_read_b128 v[186:189], v161 offset:51200
	ds_read_b128 v[190:193], v161 offset:52224
	ds_read_b128 v[194:197], v161 offset:53248
	ds_read_b128 v[198:201], v161 offset:54272
	ds_read_b128 v[202:205], v161 offset:55296
	ds_read_b128 v[230:233], v161 offset:56320
	global_load_lds_dwordx4 v[156:157], off
	s_add_i32 m0, s34, 0x2000
	s_add_u32 s28, s28, 0x40080
	v_lshl_add_u64 v[156:157], v[222:223], 0, s[52:53]
	s_addc_u32 s29, s29, 0
	s_add_i32 s34, s61, s40
	global_load_lds_dwordx4 v[156:157], off
	v_lshl_add_u64 v[156:157], s[28:29], 0, v[2:3]
	s_mov_b32 m0, s34
	s_nop 0
	global_load_lds_dwordx4 v[156:157], off
	v_lshl_add_u64 v[156:157], s[28:29], 0, v[142:143]
	s_add_i32 m0, s34, 0x2000
	s_nop 0
	global_load_lds_dwordx4 v[156:157], off
	v_lshl_add_u64 v[156:157], v[234:235], 0, s[52:53]
	s_mov_b32 m0, s45
	s_nop 0
	global_load_lds_dwordx4 v[156:157], off
	v_lshl_add_u64 v[156:157], v[236:237], 0, s[52:53]
	s_mov_b32 m0, s46
	s_nop 0
	global_load_lds_dwordx4 v[156:157], off
	s_waitcnt vmcnt(8)
	s_waitcnt lgkmcnt(0)
	s_barrier
	s_waitcnt lgkmcnt(0)
	v_mfma_f32_16x16x32_bf16 v[64:67], v[132:135], v[178:181], v[64:67]
	v_mfma_f32_16x16x32_bf16 v[60:63], v[148:151], v[178:181], v[60:63]
	v_mfma_f32_16x16x32_bf16 v[48:51], v[132:135], v[186:189], v[48:51]
	v_mfma_f32_16x16x32_bf16 v[44:47], v[148:151], v[186:189], v[44:47]
	v_mfma_f32_16x16x32_bf16 v[32:35], v[132:135], v[194:197], v[32:35]
	v_mfma_f32_16x16x32_bf16 v[28:31], v[148:151], v[194:197], v[28:31]
	v_mfma_f32_16x16x32_bf16 v[16:19], v[132:135], v[202:205], v[16:19]
	v_mfma_f32_16x16x32_bf16 v[12:15], v[148:151], v[202:205], v[12:15]
	v_mfma_f32_16x16x32_bf16 v[64:67], v[136:139], v[182:185], v[64:67]
	v_mfma_f32_16x16x32_bf16 v[60:63], v[152:155], v[182:185], v[60:63]
	v_mfma_f32_16x16x32_bf16 v[48:51], v[136:139], v[190:193], v[48:51]
	v_mfma_f32_16x16x32_bf16 v[44:47], v[152:155], v[190:193], v[44:47]
	v_mfma_f32_16x16x32_bf16 v[32:35], v[136:139], v[198:201], v[32:35]
	v_mfma_f32_16x16x32_bf16 v[28:31], v[152:155], v[198:201], v[28:31]
	v_mfma_f32_16x16x32_bf16 v[16:19], v[136:139], v[230:233], v[16:19]
	v_mfma_f32_16x16x32_bf16 v[12:15], v[152:155], v[230:233], v[12:15]
	v_mfma_f32_16x16x32_bf16 v[56:59], v[162:165], v[178:181], v[56:59]
	v_mfma_f32_16x16x32_bf16 v[52:55], v[170:173], v[178:181], v[52:55]
	v_mfma_f32_16x16x32_bf16 v[40:43], v[162:165], v[186:189], v[40:43]
	v_mfma_f32_16x16x32_bf16 v[36:39], v[170:173], v[186:189], v[36:39]
	v_mfma_f32_16x16x32_bf16 v[24:27], v[162:165], v[194:197], v[24:27]
	v_mfma_f32_16x16x32_bf16 v[20:23], v[170:173], v[194:197], v[20:23]
	v_mfma_f32_16x16x32_bf16 v[8:11], v[162:165], v[202:205], v[8:11]
	v_mfma_f32_16x16x32_bf16 v[4:7], v[170:173], v[202:205], v[4:7]
	v_mfma_f32_16x16x32_bf16 v[56:59], v[166:169], v[182:185], v[56:59]
	v_mfma_f32_16x16x32_bf16 v[52:55], v[174:177], v[182:185], v[52:55]
	v_mfma_f32_16x16x32_bf16 v[40:43], v[166:169], v[190:193], v[40:43]
	v_mfma_f32_16x16x32_bf16 v[36:39], v[174:177], v[190:193], v[36:39]
	v_mfma_f32_16x16x32_bf16 v[24:27], v[166:169], v[198:201], v[24:27]
	v_mfma_f32_16x16x32_bf16 v[20:23], v[174:177], v[198:201], v[20:23]
	v_mfma_f32_16x16x32_bf16 v[8:11], v[166:169], v[230:233], v[8:11]
	v_mfma_f32_16x16x32_bf16 v[4:7], v[174:177], v[230:233], v[4:7]
	s_barrier
	s_add_i32 s59, s59, 2
	s_add_u32 s26, s26, 0x100
	s_addc_u32 s27, s27, 0
	s_add_u32 s57, s57, 0x100
	s_addc_u32 s58, s58, 0
	s_cmp_gt_u32 s59, 13
	s_cbranch_scc0 .LBB0_686
	s_and_b64 vcc, exec, s[12:13]
	s_cbranch_vccz .LBB0_689
	s_barrier

; #define PG8_STAGE(bufoff, gbase, voff) do { _Pragma("unroll") for (int _i = 0; _i < 2; ++_i) \
;         __builtin_amdgcn_global_load_lds((const unsigned*)((const char*)(gbase) + (voff)[_i]), (PG8_LAS unsigned*)(lds + (bufoff) + ldsw + _i * 8192), 16, 0, 0); } while (0)
; #define PG8_LDA(dst, b, h) do { _Pragma("unroll") for (int m = 0; m < 4; ++m) _Pragma("unroll") for (int k = 0; k < 2; ++k) dst[m][k] = *(const PG8_LAS bf16x8*)(lds + PG8_SA(b, h) + aoff + m * 2048 + k * 1024); } while (0)
; #define PG8_LDB(dst, b, h) do { _Pragma("unroll") for (int n = 0; n < 2; ++n) _Pragma("unroll") for (int k = 0; k < 2; ++k) dst[n][k] = *(const PG8_LAS bf16x8*)(lds + PG8_SB(b, h) + boff + n * 2048 + k * 1024); } while (0)
; #define PG8_MMA(ai, bj, At, Bt) do { __builtin_amdgcn_s_setprio(1); _Pragma("unroll") for (int m = 0; m < 4; ++m) _Pragma("unroll") for (int n = 0; n < 2; ++n) _Pragma("unroll") for (int k = 0; k < 2; ++k) \
;         acc[ai][bj][m][n] = __builtin_amdgcn_mfma_f32_16x16x32_bf16(Bt[n][k], At[m][k], acc[ai][bj][m][n], 0, 0, 0); __builtin_amdgcn_s_setprio(0); } while (0)
; #define PG8_WAIT_V(n) asm volatile("s_waitcnt vmcnt(" #n ")" ::: "memory")
; #define PG8_WAIT_L(n) asm volatile("s_waitcnt lgkmcnt(" #n ")" ::: "memory")
; #define PG8_BAR __builtin_amdgcn_s_barrier()
; template <class Epi, class Sched, bool APERM>
; __device__ __forceinline__ void gemm_phase(PG8_LAS unsigned char* lds, const Gemm g, const Sched& S, const Epi& E) {
;     ...
;         for (int t = 0; t < nt; t += 2) {
;             const bool last = (t == nt - 2);
;             const char* a1 = cA + (size_t)(t + 1) * kstep;
;             const char* a2 = last ? nA : cA + (size_t)(t + 2) * kstep; const char* b2 = last ? nB : cB + (size_t)(t + 2) * kstep;
;             const char* a3 = a2 + kstep; const char* b3 = b2 + kstep;
;             if (last && has_next) S.a_ready(nxt);
;             PG8_LDB(B0, 0, 0); PG8_LDB(B1, 0, 1); PG8_SCHED; PG8_LDA(At, 0, 0); PG8_STAGE(PG8_SA(1, 1), a1 + hstepA, voffA);
;             PG8_WAIT_V(8); PG8_WAIT_L(0); PG8_BAR; PG8_MMA(0, 0, At, B0); PG8_MMA(0, 1, At, B1); PG8_BAR; PG8_SCHED;
;             PG8_LDA(At, 0, 1); PG8_STAGE(PG8_SB(0, 0), b2, voffB); PG8_STAGE(PG8_SB(0, 1), b2 + hstep, voffB); PG8_STAGE(PG8_SA(0, 0), a2, voffA);
;             PG8_WAIT_V(8); PG8_WAIT_L(0); PG8_BAR; PG8_MMA(1, 0, At, B0); PG8_MMA(1, 1, At, B1); PG8_BAR; PG8_SCHED;
.LBB0_958:
	s_add_u32 s22, s16, 0xfffc0080
	s_addc_u32 s23, s17, -1
	s_add_i32 s55, 0, 0x10000
	s_cmp_eq_u32 s54, 12
	s_cselect_b32 s25, s11, s23
	s_cselect_b32 s24, s21, s22
	v_add_u32_e32 v2, s55, v173
	s_cselect_b32 s23, s9, s51
	s_cselect_b32 s22, s49, s50
	s_add_i32 s58, 0, 0x14000
	ds_read_b128 v[144:147], v2
	ds_read_b128 v[148:151], v2 offset:1024
	ds_read_b128 v[152:155], v2 offset:2048
	ds_read_b128 v[156:159], v2 offset:3072
	v_add_u32_e32 v2, s58, v173
	ds_read_b128 v[160:163], v2
	ds_read_b128 v[164:167], v2 offset:1024
	ds_read_b128 v[168:171], v2 offset:2048
	ds_read_b128 v[178:181], v2 offset:3072
	v_lshl_add_u64 v[238:239], s[16:17], 0, v[140:141]
	s_add_i32 m0, s19, 0xc000
	ds_read_b128 v[182:185], v177
	ds_read_b128 v[186:189], v177 offset:1024
	ds_read_b128 v[190:193], v177 offset:2048
	ds_read_b128 v[194:197], v177 offset:3072
	ds_read_b128 v[198:201], v177 offset:4096
	ds_read_b128 v[202:205], v177 offset:5120
	ds_read_b128 v[230:233], v177 offset:6144
	ds_read_b128 v[234:237], v177 offset:7168
	global_load_lds_dwordx4 v[238:239], off
	v_lshl_add_u64 v[238:239], s[16:17], 0, v[142:143]
	s_add_i32 m0, s19, 0xe000
	s_nop 0
	global_load_lds_dwordx4 v[238:239], off
	s_waitcnt vmcnt(8)
	s_waitcnt lgkmcnt(0)
	s_barrier
	s_waitcnt lgkmcnt(0)
	v_mfma_f32_16x16x32_bf16 v[128:131], v[144:147], v[182:185], v[128:131]
	v_mfma_f32_16x16x32_bf16 v[124:127], v[152:155], v[182:185], v[124:127]
	v_mfma_f32_16x16x32_bf16 v[112:115], v[144:147], v[190:193], v[112:115]
	v_mfma_f32_16x16x32_bf16 v[108:111], v[152:155], v[190:193], v[108:111]
	v_mfma_f32_16x16x32_bf16 v[96:99], v[144:147], v[198:201], v[96:99]
	v_mfma_f32_16x16x32_bf16 v[92:95], v[152:155], v[198:201], v[92:95]
	v_mfma_f32_16x16x32_bf16 v[80:83], v[144:147], v[230:233], v[80:83]
	v_mfma_f32_16x16x32_bf16 v[76:79], v[152:155], v[230:233], v[76:79]
	v_mfma_f32_16x16x32_bf16 v[128:131], v[148:151], v[186:189], v[128:131]
	v_mfma_f32_16x16x32_bf16 v[124:127], v[156:159], v[186:189], v[124:127]
	v_mfma_f32_16x16x32_bf16 v[112:115], v[148:151], v[194:197], v[112:115]
	v_mfma_f32_16x16x32_bf16 v[108:111], v[156:159], v[194:197], v[108:111]
	v_mfma_f32_16x16x32_bf16 v[96:99], v[148:151], v[202:205], v[96:99]
	v_mfma_f32_16x16x32_bf16 v[92:95], v[156:159], v[202:205], v[92:95]
	v_mfma_f32_16x16x32_bf16 v[80:83], v[148:151], v[234:237], v[80:83]
	v_mfma_f32_16x16x32_bf16 v[76:79], v[156:159], v[234:237], v[76:79]
	v_mfma_f32_16x16x32_bf16 v[120:123], v[160:163], v[182:185], v[120:123]
	v_mfma_f32_16x16x32_bf16 v[116:119], v[168:171], v[182:185], v[116:119]
	v_mfma_f32_16x16x32_bf16 v[104:107], v[160:163], v[190:193], v[104:107]
	v_mfma_f32_16x16x32_bf16 v[100:103], v[168:171], v[190:193], v[100:103]
	v_mfma_f32_16x16x32_bf16 v[88:91], v[160:163], v[198:201], v[88:91]
	v_mfma_f32_16x16x32_bf16 v[84:87], v[168:171], v[198:201], v[84:87]
	v_mfma_f32_16x16x32_bf16 v[72:75], v[160:163], v[230:233], v[72:75]
	v_mfma_f32_16x16x32_bf16 v[68:71], v[168:171], v[230:233], v[68:71]
	v_mfma_f32_16x16x32_bf16 v[120:123], v[164:167], v[186:189], v[120:123]
	v_mfma_f32_16x16x32_bf16 v[116:119], v[178:181], v[186:189], v[116:119]
	v_mfma_f32_16x16x32_bf16 v[104:107], v[164:167], v[194:197], v[104:107]
	v_mfma_f32_16x16x32_bf16 v[100:103], v[178:181], v[194:197], v[100:103]
	v_mfma_f32_16x16x32_bf16 v[88:91], v[164:167], v[202:205], v[88:91]
	v_mfma_f32_16x16x32_bf16 v[84:87], v[178:181], v[202:205], v[84:87]
	v_mfma_f32_16x16x32_bf16 v[72:75], v[164:167], v[234:237], v[72:75]
	v_mfma_f32_16x16x32_bf16 v[68:71], v[178:181], v[234:237], v[68:71]
	s_barrier
	s_add_i32 s55, s55, s28
	v_lshl_add_u64 v[238:239], s[22:23], 0, v[134:135]
	s_mov_b32 m0, s55
	ds_read_b128 v[182:185], v177 offset:16384
	ds_read_b128 v[186:189], v177 offset:17408
	ds_read_b128 v[190:193], v177 offset:18432
	ds_read_b128 v[194:197], v177 offset:19456
	ds_read_b128 v[198:201], v177 offset:20480
	ds_read_b128 v[202:205], v177 offset:21504
	ds_read_b128 v[230:233], v177 offset:22528
	ds_read_b128 v[234:237], v177 offset:23552
	global_load_lds_dwordx4 v[238:239], off
	s_add_i32 m0, s55, 0x2000
	s_add_u32 s56, s22, 0x40000
	v_lshl_add_u64 v[240:241], s[22:23], 0, v[0:1]
	s_addc_u32 s57, s23, 0
	s_add_i32 s55, s58, s28
	global_load_lds_dwordx4 v[240:241], off
	v_lshl_add_u64 v[242:243], s[56:57], 0, v[134:135]
	s_mov_b32 m0, s55
	v_lshl_add_u64 v[244:245], s[24:25], 0, v[132:133]
	global_load_lds_dwordx4 v[242:243], off
	v_lshl_add_u64 v[242:243], s[56:57], 0, v[0:1]
	s_add_i32 m0, s55, 0x2000
	s_nop 0
	global_load_lds_dwordx4 v[242:243], off
	v_lshl_add_u64 v[242:243], s[24:25], 0, v[136:137]
	s_mov_b32 m0, s19
	s_nop 0
	global_load_lds_dwordx4 v[242:243], off
	s_mov_b32 m0, s36
	s_nop 0
	global_load_lds_dwordx4 v[244:245], off
	s_waitcnt vmcnt(8)
	s_waitcnt lgkmcnt(0)
	s_barrier
; #define PG8_STAGE(bufoff, gbase, voff) do { _Pragma("unroll") for (int _i = 0; _i < 2; ++_i) \
;         __builtin_amdgcn_global_load_lds((const unsigned*)((const char*)(gbase) + (voff)[_i]), (PG8_LAS unsigned*)(lds + (bufoff) + ldsw + _i * 8192), 16, 0, 0); } while (0)
; #define PG8_LDA(dst, b, h) do { _Pragma("unroll") for (int m = 0; m < 4; ++m) _Pragma("unroll") for (int k = 0; k < 2; ++k) dst[m][k] = *(const PG8_LAS bf16x8*)(lds + PG8_SA(b, h) + aoff + m * 2048 + k * 1024); } while (0)
; #define PG8_LDB(dst, b, h) do { _Pragma("unroll") for (int n = 0; n < 2; ++n) _Pragma("unroll") for (int k = 0; k < 2; ++k) dst[n][k] = *(const PG8_LAS bf16x8*)(lds + PG8_SB(b, h) + boff + n * 2048 + k * 1024); } while (0)
; #define PG8_MMA(ai, bj, At, Bt) do { __builtin_amdgcn_s_setprio(1); _Pragma("unroll") for (int m = 0; m < 4; ++m) _Pragma("unroll") for (int n = 0; n < 2; ++n) _Pragma("unroll") for (int k = 0; k < 2; ++k) \
;         acc[ai][bj][m][n] = __builtin_amdgcn_mfma_f32_16x16x32_bf16(Bt[n][k], At[m][k], acc[ai][bj][m][n], 0, 0, 0); __builtin_amdgcn_s_setprio(0); } while (0)
; #define PG8_WAIT_V(n) asm volatile("s_waitcnt vmcnt(" #n ")" ::: "memory")
; #define PG8_WAIT_L(n) asm volatile("s_waitcnt lgkmcnt(" #n ")" ::: "memory")
; #define PG8_BAR __builtin_amdgcn_s_barrier()
; #define PG8_SCHED __builtin_amdgcn_sched_barrier(0)
; template <class Epi, class Sched, bool APERM>
; __device__ __forceinline__ void gemm_phase(PG8_LAS unsigned char* lds, const Gemm g, const Sched& S, const Epi& E) {
;     ...
;             PG8_WAIT_V(8); PG8_WAIT_L(0); PG8_BAR; PG8_MMA(1, 0, At, B0); PG8_MMA(1, 1, At, B1); PG8_BAR; PG8_SCHED;
;             PG8_LDB(B0, 1, 0); PG8_LDB(B1, 1, 1); PG8_SCHED; PG8_LDA(At, 1, 0); PG8_STAGE(PG8_SA(0, 1), a2 + hstepA, voffA);
;             PG8_WAIT_V(8); PG8_WAIT_L(0); PG8_BAR; PG8_MMA(0, 0, At, B0); PG8_MMA(0, 1, At, B1); PG8_BAR; PG8_SCHED;
	s_waitcnt lgkmcnt(0)
	v_mfma_f32_16x16x32_bf16 v[64:67], v[144:147], v[182:185], v[64:67]
	v_mfma_f32_16x16x32_bf16 v[60:63], v[152:155], v[182:185], v[60:63]
	v_mfma_f32_16x16x32_bf16 v[48:51], v[144:147], v[190:193], v[48:51]
	v_mfma_f32_16x16x32_bf16 v[44:47], v[152:155], v[190:193], v[44:47]
	v_mfma_f32_16x16x32_bf16 v[32:35], v[144:147], v[198:201], v[32:35]
	v_mfma_f32_16x16x32_bf16 v[28:31], v[152:155], v[198:201], v[28:31]
	v_mfma_f32_16x16x32_bf16 v[16:19], v[144:147], v[230:233], v[16:19]
	v_mfma_f32_16x16x32_bf16 v[12:15], v[152:155], v[230:233], v[12:15]
	v_mfma_f32_16x16x32_bf16 v[64:67], v[148:151], v[186:189], v[64:67]
	v_mfma_f32_16x16x32_bf16 v[60:63], v[156:159], v[186:189], v[60:63]
	v_mfma_f32_16x16x32_bf16 v[48:51], v[148:151], v[194:197], v[48:51]
	v_mfma_f32_16x16x32_bf16 v[44:47], v[156:159], v[194:197], v[44:47]
	v_mfma_f32_16x16x32_bf16 v[32:35], v[148:151], v[202:205], v[32:35]
	v_mfma_f32_16x16x32_bf16 v[28:31], v[156:159], v[202:205], v[28:31]
	v_mfma_f32_16x16x32_bf16 v[16:19], v[148:151], v[234:237], v[16:19]
	v_mfma_f32_16x16x32_bf16 v[12:15], v[156:159], v[234:237], v[12:15]
	v_mfma_f32_16x16x32_bf16 v[56:59], v[160:163], v[182:185], v[56:59]
	v_mfma_f32_16x16x32_bf16 v[52:55], v[168:171], v[182:185], v[52:55]
	v_mfma_f32_16x16x32_bf16 v[40:43], v[160:163], v[190:193], v[40:43]
	v_mfma_f32_16x16x32_bf16 v[36:39], v[168:171], v[190:193], v[36:39]
	v_mfma_f32_16x16x32_bf16 v[24:27], v[160:163], v[198:201], v[24:27]
	v_mfma_f32_16x16x32_bf16 v[20:23], v[168:171], v[198:201], v[20:23]
	v_mfma_f32_16x16x32_bf16 v[8:11], v[160:163], v[230:233], v[8:11]
	v_mfma_f32_16x16x32_bf16 v[4:7], v[168:171], v[230:233], v[4:7]
	v_mfma_f32_16x16x32_bf16 v[56:59], v[164:167], v[186:189], v[56:59]
	v_mfma_f32_16x16x32_bf16 v[52:55], v[178:181], v[186:189], v[52:55]
	v_mfma_f32_16x16x32_bf16 v[40:43], v[164:167], v[194:197], v[40:43]
	v_mfma_f32_16x16x32_bf16 v[36:39], v[178:181], v[194:197], v[36:39]
	v_mfma_f32_16x16x32_bf16 v[24:27], v[164:167], v[202:205], v[24:27]
	v_mfma_f32_16x16x32_bf16 v[20:23], v[178:181], v[202:205], v[20:23]
	v_mfma_f32_16x16x32_bf16 v[8:11], v[164:167], v[234:237], v[8:11]
	v_mfma_f32_16x16x32_bf16 v[4:7], v[178:181], v[234:237], v[4:7]
	s_barrier
	s_add_i32 s55, 0, 0x18000
	v_add_u32_e32 v2, s55, v173
	s_add_i32 s56, 0, 0x1c000
	ds_read_b128 v[144:147], v2
	ds_read_b128 v[148:151], v2 offset:1024
	ds_read_b128 v[152:155], v2 offset:2048
	ds_read_b128 v[156:159], v2 offset:3072
	v_add_u32_e32 v2, s56, v173
	ds_read_b128 v[160:163], v2
	ds_read_b128 v[164:167], v2 offset:1024
	ds_read_b128 v[168:171], v2 offset:2048
	ds_read_b128 v[178:181], v2 offset:3072
	s_add_u32 s24, s24, 0x40000
	s_addc_u32 s25, s25, 0
	s_mov_b32 m0, s37
	v_lshl_add_u64 v[246:247], s[24:25], 0, v[136:137]
	ds_read_b128 v[182:185], v177 offset:32768
	ds_read_b128 v[186:189], v177 offset:33792
	ds_read_b128 v[190:193], v177 offset:34816
	ds_read_b128 v[194:197], v177 offset:35840
	ds_read_b128 v[198:201], v177 offset:36864
	ds_read_b128 v[202:205], v177 offset:37888
	ds_read_b128 v[230:233], v177 offset:38912
	ds_read_b128 v[234:237], v177 offset:39936
	global_load_lds_dwordx4 v[246:247], off
	v_lshl_add_u64 v[246:247], s[24:25], 0, v[132:133]
	s_mov_b32 m0, s40
	s_nop 0
	global_load_lds_dwordx4 v[246:247], off
	s_waitcnt vmcnt(8)
	s_waitcnt lgkmcnt(0)
	s_barrier
	s_waitcnt lgkmcnt(0)
	v_mfma_f32_16x16x32_bf16 v[128:131], v[144:147], v[182:185], v[128:131]
	v_mfma_f32_16x16x32_bf16 v[124:127], v[152:155], v[182:185], v[124:127]
	v_mfma_f32_16x16x32_bf16 v[112:115], v[144:147], v[190:193], v[112:115]
	v_mfma_f32_16x16x32_bf16 v[108:111], v[152:155], v[190:193], v[108:111]
	v_mfma_f32_16x16x32_bf16 v[96:99], v[144:147], v[198:201], v[96:99]
	v_mfma_f32_16x16x32_bf16 v[92:95], v[152:155], v[198:201], v[92:95]
	v_mfma_f32_16x16x32_bf16 v[80:83], v[144:147], v[230:233], v[80:83]
	v_mfma_f32_16x16x32_bf16 v[76:79], v[152:155], v[230:233], v[76:79]
	v_mfma_f32_16x16x32_bf16 v[128:131], v[148:151], v[186:189], v[128:131]
	v_mfma_f32_16x16x32_bf16 v[124:127], v[156:159], v[186:189], v[124:127]
	v_mfma_f32_16x16x32_bf16 v[112:115], v[148:151], v[194:197], v[112:115]
	v_mfma_f32_16x16x32_bf16 v[108:111], v[156:159], v[194:197], v[108:111]
	v_mfma_f32_16x16x32_bf16 v[96:99], v[148:151], v[202:205], v[96:99]
	v_mfma_f32_16x16x32_bf16 v[92:95], v[156:159], v[202:205], v[92:95]
	v_mfma_f32_16x16x32_bf16 v[80:83], v[148:151], v[234:237], v[80:83]
	v_mfma_f32_16x16x32_bf16 v[76:79], v[156:159], v[234:237], v[76:79]
	v_mfma_f32_16x16x32_bf16 v[120:123], v[160:163], v[182:185], v[120:123]
	v_mfma_f32_16x16x32_bf16 v[116:119], v[168:171], v[182:185], v[116:119]
	v_mfma_f32_16x16x32_bf16 v[104:107], v[160:163], v[190:193], v[104:107]
	v_mfma_f32_16x16x32_bf16 v[100:103], v[168:171], v[190:193], v[100:103]
	v_mfma_f32_16x16x32_bf16 v[88:91], v[160:163], v[198:201], v[88:91]
	v_mfma_f32_16x16x32_bf16 v[84:87], v[168:171], v[198:201], v[84:87]
	v_mfma_f32_16x16x32_bf16 v[72:75], v[160:163], v[230:233], v[72:75]
	v_mfma_f32_16x16x32_bf16 v[68:71], v[168:171], v[230:233], v[68:71]
	v_mfma_f32_16x16x32_bf16 v[120:123], v[164:167], v[186:189], v[120:123]
	v_mfma_f32_16x16x32_bf16 v[116:119], v[178:181], v[186:189], v[116:119]
	v_mfma_f32_16x16x32_bf16 v[104:107], v[164:167], v[194:197], v[104:107]
	v_mfma_f32_16x16x32_bf16 v[100:103], v[178:181], v[194:197], v[100:103]
	v_mfma_f32_16x16x32_bf16 v[88:91], v[164:167], v[202:205], v[88:91]
	v_mfma_f32_16x16x32_bf16 v[84:87], v[178:181], v[202:205], v[84:87]
	v_mfma_f32_16x16x32_bf16 v[72:75], v[164:167], v[234:237], v[72:75]
	v_mfma_f32_16x16x32_bf16 v[68:71], v[178:181], v[234:237], v[68:71]
	s_barrier
; #define PG8_STAGE(bufoff, gbase, voff) do { _Pragma("unroll") for (int _i = 0; _i < 2; ++_i) \
;         __builtin_amdgcn_global_load_lds((const unsigned*)((const char*)(gbase) + (voff)[_i]), (PG8_LAS unsigned*)(lds + (bufoff) + ldsw + _i * 8192), 16, 0, 0); } while (0)
; #define PG8_LDA(dst, b, h) do { _Pragma("unroll") for (int m = 0; m < 4; ++m) _Pragma("unroll") for (int k = 0; k < 2; ++k) dst[m][k] = *(const PG8_LAS bf16x8*)(lds + PG8_SA(b, h) + aoff + m * 2048 + k * 1024); } while (0)
; #define PG8_MMA(ai, bj, At, Bt) do { __builtin_amdgcn_s_setprio(1); _Pragma("unroll") for (int m = 0; m < 4; ++m) _Pragma("unroll") for (int n = 0; n < 2; ++n) _Pragma("unroll") for (int k = 0; k < 2; ++k) \
;         acc[ai][bj][m][n] = __builtin_amdgcn_mfma_f32_16x16x32_bf16(Bt[n][k], At[m][k], acc[ai][bj][m][n], 0, 0, 0); __builtin_amdgcn_s_setprio(0); } while (0)
; #define PG8_WAIT_V(n) asm volatile("s_waitcnt vmcnt(" #n ")" ::: "memory")
; #define PG8_WAIT_L(n) asm volatile("s_waitcnt lgkmcnt(" #n ")" ::: "memory")
; #define PG8_BAR __builtin_amdgcn_s_barrier()
; #define PG8_SCHED __builtin_amdgcn_sched_barrier(0)
; template <class Epi, class Sched, bool APERM>
; __device__ __forceinline__ void gemm_phase(PG8_LAS unsigned char* lds, const Gemm g, const Sched& S, const Epi& E) {
;     ...
;             PG8_LDA(At, 1, 1); PG8_STAGE(PG8_SB(1, 0), b3, voffB); PG8_STAGE(PG8_SB(1, 1), b3 + hstep, voffB); PG8_STAGE(PG8_SA(1, 0), a3, voffA);
;             PG8_WAIT_V(8); PG8_WAIT_L(0); PG8_BAR; PG8_MMA(1, 0, At, B0); PG8_MMA(1, 1, At, B1); PG8_BAR; PG8_SCHED;
;         }
;         if (wr == 0) PG8_BAR;
	s_add_i32 s24, s55, s28
	v_lshl_add_u64 v[238:239], v[238:239], 0, s[52:53]
	s_mov_b32 m0, s24
	ds_read_b128 v[182:185], v177 offset:49152
	ds_read_b128 v[186:189], v177 offset:50176
	ds_read_b128 v[190:193], v177 offset:51200
	ds_read_b128 v[194:197], v177 offset:52224
	ds_read_b128 v[198:201], v177 offset:53248
	ds_read_b128 v[202:205], v177 offset:54272
	ds_read_b128 v[230:233], v177 offset:55296
	ds_read_b128 v[234:237], v177 offset:56320
	global_load_lds_dwordx4 v[238:239], off
	s_add_i32 m0, s24, 0x2000
	s_add_u32 s22, s22, 0x40080
	v_lshl_add_u64 v[238:239], v[240:241], 0, s[52:53]
	s_addc_u32 s23, s23, 0
	s_add_i32 s24, s56, s28
	global_load_lds_dwordx4 v[238:239], off
	v_lshl_add_u64 v[238:239], s[22:23], 0, v[134:135]
	s_mov_b32 m0, s24
	s_nop 0
	global_load_lds_dwordx4 v[238:239], off
	v_lshl_add_u64 v[238:239], s[22:23], 0, v[0:1]
	s_add_i32 m0, s24, 0x2000
	s_nop 0
	global_load_lds_dwordx4 v[238:239], off
	v_lshl_add_u64 v[238:239], v[242:243], 0, s[52:53]
	s_mov_b32 m0, s44
	s_nop 0
	global_load_lds_dwordx4 v[238:239], off
	v_lshl_add_u64 v[238:239], v[244:245], 0, s[52:53]
	s_mov_b32 m0, s45
	s_nop 0
	global_load_lds_dwordx4 v[238:239], off
	s_waitcnt vmcnt(8)
	s_waitcnt lgkmcnt(0)
	s_barrier
	s_waitcnt lgkmcnt(0)
	v_mfma_f32_16x16x32_bf16 v[64:67], v[144:147], v[182:185], v[64:67]
	v_mfma_f32_16x16x32_bf16 v[60:63], v[152:155], v[182:185], v[60:63]
	v_mfma_f32_16x16x32_bf16 v[48:51], v[144:147], v[190:193], v[48:51]
	v_mfma_f32_16x16x32_bf16 v[44:47], v[152:155], v[190:193], v[44:47]
	v_mfma_f32_16x16x32_bf16 v[32:35], v[144:147], v[198:201], v[32:35]
	v_mfma_f32_16x16x32_bf16 v[28:31], v[152:155], v[198:201], v[28:31]
	v_mfma_f32_16x16x32_bf16 v[16:19], v[144:147], v[230:233], v[16:19]
	v_mfma_f32_16x16x32_bf16 v[12:15], v[152:155], v[230:233], v[12:15]
	v_mfma_f32_16x16x32_bf16 v[64:67], v[148:151], v[186:189], v[64:67]
	v_mfma_f32_16x16x32_bf16 v[60:63], v[156:159], v[186:189], v[60:63]
	v_mfma_f32_16x16x32_bf16 v[48:51], v[148:151], v[194:197], v[48:51]
	v_mfma_f32_16x16x32_bf16 v[44:47], v[156:159], v[194:197], v[44:47]
	v_mfma_f32_16x16x32_bf16 v[32:35], v[148:151], v[202:205], v[32:35]
	v_mfma_f32_16x16x32_bf16 v[28:31], v[156:159], v[202:205], v[28:31]
	v_mfma_f32_16x16x32_bf16 v[16:19], v[148:151], v[234:237], v[16:19]
	v_mfma_f32_16x16x32_bf16 v[12:15], v[156:159], v[234:237], v[12:15]
	v_mfma_f32_16x16x32_bf16 v[56:59], v[160:163], v[182:185], v[56:59]
	v_mfma_f32_16x16x32_bf16 v[52:55], v[168:171], v[182:185], v[52:55]
	v_mfma_f32_16x16x32_bf16 v[40:43], v[160:163], v[190:193], v[40:43]
	v_mfma_f32_16x16x32_bf16 v[36:39], v[168:171], v[190:193], v[36:39]
	v_mfma_f32_16x16x32_bf16 v[24:27], v[160:163], v[198:201], v[24:27]
	v_mfma_f32_16x16x32_bf16 v[20:23], v[168:171], v[198:201], v[20:23]
	v_mfma_f32_16x16x32_bf16 v[8:11], v[160:163], v[230:233], v[8:11]
	v_mfma_f32_16x16x32_bf16 v[4:7], v[168:171], v[230:233], v[4:7]
	v_mfma_f32_16x16x32_bf16 v[56:59], v[164:167], v[186:189], v[56:59]
	v_mfma_f32_16x16x32_bf16 v[52:55], v[178:181], v[186:189], v[52:55]
	v_mfma_f32_16x16x32_bf16 v[40:43], v[164:167], v[194:197], v[40:43]
	v_mfma_f32_16x16x32_bf16 v[36:39], v[178:181], v[194:197], v[36:39]
	v_mfma_f32_16x16x32_bf16 v[24:27], v[164:167], v[202:205], v[24:27]
	v_mfma_f32_16x16x32_bf16 v[20:23], v[178:181], v[202:205], v[20:23]
	v_mfma_f32_16x16x32_bf16 v[8:11], v[164:167], v[234:237], v[8:11]
	v_mfma_f32_16x16x32_bf16 v[4:7], v[178:181], v[234:237], v[4:7]
	s_barrier
	s_add_i32 s54, s54, 2
	s_add_u32 s16, s16, 0x100
	s_addc_u32 s17, s17, 0
	s_add_u32 s50, s50, 0x100
	s_addc_u32 s51, s51, 0
	s_cmp_gt_u32 s54, 13
	s_cbranch_scc0 .LBB0_958
	s_and_b64 vcc, exec, s[6:7]
	s_cbranch_vccz .LBB0_961
	s_barrier

; #define PG8_STAGE(bufoff, gbase, voff) do { _Pragma("unroll") for (int _i = 0; _i < 2; ++_i) \
;         __builtin_amdgcn_global_load_lds((const unsigned*)((const char*)(gbase) + (voff)[_i]), (PG8_LAS unsigned*)(lds + (bufoff) + ldsw + _i * 8192), 16, 0, 0); } while (0)
; #define PG8_LDA(dst, b, h) do { _Pragma("unroll") for (int m = 0; m < 4; ++m) _Pragma("unroll") for (int k = 0; k < 2; ++k) dst[m][k] = *(const PG8_LAS bf16x8*)(lds + PG8_SA(b, h) + aoff + m * 2048 + k * 1024); } while (0)
; #define PG8_LDB(dst, b, h) do { _Pragma("unroll") for (int n = 0; n < 2; ++n) _Pragma("unroll") for (int k = 0; k < 2; ++k) dst[n][k] = *(const PG8_LAS bf16x8*)(lds + PG8_SB(b, h) + boff + n * 2048 + k * 1024); } while (0)
; #define PG8_MMA(ai, bj, At, Bt) do { __builtin_amdgcn_s_setprio(1); _Pragma("unroll") for (int m = 0; m < 4; ++m) _Pragma("unroll") for (int n = 0; n < 2; ++n) _Pragma("unroll") for (int k = 0; k < 2; ++k) \
;         acc[ai][bj][m][n] = __builtin_amdgcn_mfma_f32_16x16x32_bf16(Bt[n][k], At[m][k], acc[ai][bj][m][n], 0, 0, 0); __builtin_amdgcn_s_setprio(0); } while (0)
; #define PG8_WAIT_V(n) asm volatile("s_waitcnt vmcnt(" #n ")" ::: "memory")
; #define PG8_WAIT_L(n) asm volatile("s_waitcnt lgkmcnt(" #n ")" ::: "memory")
; #define PG8_BAR __builtin_amdgcn_s_barrier()
; template <class Epi, class Sched, bool APERM>
; __device__ __forceinline__ void gemm_phase(PG8_LAS unsigned char* lds, const Gemm g, const Sched& S, const Epi& E) {
;     ...
;         for (int t = 0; t < nt; t += 2) {
;             const bool last = (t == nt - 2);
;             const char* a1 = cA + (size_t)(t + 1) * kstep;
;             const char* a2 = last ? nA : cA + (size_t)(t + 2) * kstep; const char* b2 = last ? nB : cB + (size_t)(t + 2) * kstep;
;             const char* a3 = a2 + kstep; const char* b3 = b2 + kstep;
;             if (last && has_next) S.a_ready(nxt);
;             PG8_LDB(B0, 0, 0); PG8_LDB(B1, 0, 1); PG8_SCHED; PG8_LDA(At, 0, 0); PG8_STAGE(PG8_SA(1, 1), a1 + hstepA, voffA);
;             PG8_WAIT_V(8); PG8_WAIT_L(0); PG8_BAR; PG8_MMA(0, 0, At, B0); PG8_MMA(0, 1, At, B1); PG8_BAR; PG8_SCHED;
;             PG8_LDA(At, 0, 1); PG8_STAGE(PG8_SB(0, 0), b2, voffB); PG8_STAGE(PG8_SB(0, 1), b2 + hstep, voffB); PG8_STAGE(PG8_SA(0, 0), a2, voffA);
;             PG8_WAIT_V(8); PG8_WAIT_L(0); PG8_BAR; PG8_MMA(1, 0, At, B0); PG8_MMA(1, 1, At, B1); PG8_BAR; PG8_SCHED;
.LBB0_979:
	s_add_u32 s18, s16, 0x100
	s_addc_u32 s19, s17, 0
	s_cmp_lg_u32 s45, 4
	s_cselect_b32 s20, s18, 0
	s_cselect_b32 s21, s19, 0
	s_add_u32 s22, s14, s20
	s_addc_u32 s23, s15, s21
	s_add_i32 s46, 0, 0x10000
	s_add_u32 s20, s12, s20
	v_add_u32_e32 v145, s46, v143
	s_addc_u32 s21, s13, s21
	s_add_i32 s47, 0, 0x14000
	ds_read_b128 v[146:149], v145
	ds_read_b128 v[150:153], v145 offset:1024
	ds_read_b128 v[154:157], v145 offset:2048
	ds_read_b128 v[158:161], v145 offset:3072
	v_add_u32_e32 v145, s47, v143
	ds_read_b128 v[162:165], v145
	ds_read_b128 v[166:169], v145 offset:1024
	ds_read_b128 v[170:173], v145 offset:2048
	ds_read_b128 v[174:177], v145 offset:3072
	v_lshl_add_u64 v[222:223], v[136:137], 0, s[16:17]
	s_add_i32 m0, s1, 0xc000
	ds_read_b128 v[178:181], v144
	ds_read_b128 v[182:185], v144 offset:1024
	ds_read_b128 v[186:189], v144 offset:2048
	ds_read_b128 v[190:193], v144 offset:3072
	ds_read_b128 v[194:197], v144 offset:4096
	ds_read_b128 v[198:201], v144 offset:5120
	ds_read_b128 v[202:205], v144 offset:6144
	ds_read_b128 v[230:233], v144 offset:7168
	global_load_lds_dwordx4 v[222:223], off
	v_lshl_add_u64 v[222:223], v[138:139], 0, s[16:17]
	s_add_i32 m0, s1, 0xe000
	s_nop 0
	global_load_lds_dwordx4 v[222:223], off
	s_waitcnt vmcnt(8)
	s_waitcnt lgkmcnt(0)
	s_barrier
	s_waitcnt lgkmcnt(0)
	v_mfma_f32_16x16x32_bf16 v[128:131], v[146:149], v[178:181], v[128:131]
	v_mfma_f32_16x16x32_bf16 v[124:127], v[154:157], v[178:181], v[124:127]
	v_mfma_f32_16x16x32_bf16 v[120:123], v[146:149], v[186:189], v[120:123]
	v_mfma_f32_16x16x32_bf16 v[116:119], v[154:157], v[186:189], v[116:119]
	v_mfma_f32_16x16x32_bf16 v[112:115], v[146:149], v[194:197], v[112:115]
	v_mfma_f32_16x16x32_bf16 v[108:111], v[154:157], v[194:197], v[108:111]
	v_mfma_f32_16x16x32_bf16 v[104:107], v[146:149], v[202:205], v[104:107]
	v_mfma_f32_16x16x32_bf16 v[100:103], v[154:157], v[202:205], v[100:103]
	v_mfma_f32_16x16x32_bf16 v[128:131], v[150:153], v[182:185], v[128:131]
	v_mfma_f32_16x16x32_bf16 v[124:127], v[158:161], v[182:185], v[124:127]
	v_mfma_f32_16x16x32_bf16 v[120:123], v[150:153], v[190:193], v[120:123]
	v_mfma_f32_16x16x32_bf16 v[116:119], v[158:161], v[190:193], v[116:119]
	v_mfma_f32_16x16x32_bf16 v[112:115], v[150:153], v[198:201], v[112:115]
	v_mfma_f32_16x16x32_bf16 v[108:111], v[158:161], v[198:201], v[108:111]
	v_mfma_f32_16x16x32_bf16 v[104:107], v[150:153], v[230:233], v[104:107]
	v_mfma_f32_16x16x32_bf16 v[100:103], v[158:161], v[230:233], v[100:103]
	v_mfma_f32_16x16x32_bf16 v[96:99], v[162:165], v[178:181], v[96:99]
	v_mfma_f32_16x16x32_bf16 v[92:95], v[170:173], v[178:181], v[92:95]
	v_mfma_f32_16x16x32_bf16 v[88:91], v[162:165], v[186:189], v[88:91]
	v_mfma_f32_16x16x32_bf16 v[84:87], v[170:173], v[186:189], v[84:87]
	v_mfma_f32_16x16x32_bf16 v[80:83], v[162:165], v[194:197], v[80:83]
	v_mfma_f32_16x16x32_bf16 v[76:79], v[170:173], v[194:197], v[76:79]
	v_mfma_f32_16x16x32_bf16 v[72:75], v[162:165], v[202:205], v[72:75]
	v_mfma_f32_16x16x32_bf16 v[68:71], v[170:173], v[202:205], v[68:71]
	v_mfma_f32_16x16x32_bf16 v[96:99], v[166:169], v[182:185], v[96:99]
	v_mfma_f32_16x16x32_bf16 v[92:95], v[174:177], v[182:185], v[92:95]
	v_mfma_f32_16x16x32_bf16 v[88:91], v[166:169], v[190:193], v[88:91]
	v_mfma_f32_16x16x32_bf16 v[84:87], v[174:177], v[190:193], v[84:87]
	v_mfma_f32_16x16x32_bf16 v[80:83], v[166:169], v[198:201], v[80:83]
	v_mfma_f32_16x16x32_bf16 v[76:79], v[174:177], v[198:201], v[76:79]
	v_mfma_f32_16x16x32_bf16 v[72:75], v[166:169], v[230:233], v[72:75]
	v_mfma_f32_16x16x32_bf16 v[68:71], v[174:177], v[230:233], v[68:71]
	s_barrier
	s_add_i32 s16, s46, s35
	v_lshl_add_u64 v[222:223], s[20:21], 0, v[2:3]
	s_mov_b32 m0, s16
	ds_read_b128 v[178:181], v144 offset:16384
	ds_read_b128 v[182:185], v144 offset:17408
	ds_read_b128 v[186:189], v144 offset:18432
	ds_read_b128 v[190:193], v144 offset:19456
	ds_read_b128 v[194:197], v144 offset:20480
	ds_read_b128 v[198:201], v144 offset:21504
	ds_read_b128 v[202:205], v144 offset:22528
	ds_read_b128 v[230:233], v144 offset:23552
	global_load_lds_dwordx4 v[222:223], off
	s_add_i32 m0, s16, 0x2000
	s_add_u32 s16, s20, 0x40000
	v_lshl_add_u64 v[234:235], s[20:21], 0, v[0:1]
	s_addc_u32 s17, s21, 0
	s_add_i32 s46, s47, s35
	global_load_lds_dwordx4 v[234:235], off
	v_lshl_add_u64 v[236:237], s[16:17], 0, v[2:3]
	s_mov_b32 m0, s46
	v_lshl_add_u64 v[238:239], s[22:23], 0, v[132:133]
	global_load_lds_dwordx4 v[236:237], off
	v_lshl_add_u64 v[236:237], s[16:17], 0, v[0:1]
	s_add_i32 m0, s46, 0x2000
	s_nop 0
	global_load_lds_dwordx4 v[236:237], off
	v_lshl_add_u64 v[236:237], s[22:23], 0, v[134:135]
	s_mov_b32 m0, s1
	s_nop 0
	global_load_lds_dwordx4 v[236:237], off
	s_mov_b32 m0, s7
	s_nop 0
	global_load_lds_dwordx4 v[238:239], off
	s_waitcnt vmcnt(8)
	s_waitcnt lgkmcnt(0)
	s_barrier
; #define PG8_STAGE(bufoff, gbase, voff) do { _Pragma("unroll") for (int _i = 0; _i < 2; ++_i) \
;         __builtin_amdgcn_global_load_lds((const unsigned*)((const char*)(gbase) + (voff)[_i]), (PG8_LAS unsigned*)(lds + (bufoff) + ldsw + _i * 8192), 16, 0, 0); } while (0)
; #define PG8_LDA(dst, b, h) do { _Pragma("unroll") for (int m = 0; m < 4; ++m) _Pragma("unroll") for (int k = 0; k < 2; ++k) dst[m][k] = *(const PG8_LAS bf16x8*)(lds + PG8_SA(b, h) + aoff + m * 2048 + k * 1024); } while (0)
; #define PG8_LDB(dst, b, h) do { _Pragma("unroll") for (int n = 0; n < 2; ++n) _Pragma("unroll") for (int k = 0; k < 2; ++k) dst[n][k] = *(const PG8_LAS bf16x8*)(lds + PG8_SB(b, h) + boff + n * 2048 + k * 1024); } while (0)
; #define PG8_MMA(ai, bj, At, Bt) do { __builtin_amdgcn_s_setprio(1); _Pragma("unroll") for (int m = 0; m < 4; ++m) _Pragma("unroll") for (int n = 0; n < 2; ++n) _Pragma("unroll") for (int k = 0; k < 2; ++k) \
;         acc[ai][bj][m][n] = __builtin_amdgcn_mfma_f32_16x16x32_bf16(Bt[n][k], At[m][k], acc[ai][bj][m][n], 0, 0, 0); __builtin_amdgcn_s_setprio(0); } while (0)
; #define PG8_WAIT_V(n) asm volatile("s_waitcnt vmcnt(" #n ")" ::: "memory")
; #define PG8_WAIT_L(n) asm volatile("s_waitcnt lgkmcnt(" #n ")" ::: "memory")
; #define PG8_BAR __builtin_amdgcn_s_barrier()
; #define PG8_SCHED __builtin_amdgcn_sched_barrier(0)
; template <class Epi, class Sched, bool APERM>
; __device__ __forceinline__ void gemm_phase(PG8_LAS unsigned char* lds, const Gemm g, const Sched& S, const Epi& E) {
;     ...
;             PG8_WAIT_V(8); PG8_WAIT_L(0); PG8_BAR; PG8_MMA(1, 0, At, B0); PG8_MMA(1, 1, At, B1); PG8_BAR; PG8_SCHED;
;             PG8_LDB(B0, 1, 0); PG8_LDB(B1, 1, 1); PG8_SCHED; PG8_LDA(At, 1, 0); PG8_STAGE(PG8_SA(0, 1), a2 + hstepA, voffA);
;             PG8_WAIT_V(8); PG8_WAIT_L(0); PG8_BAR; PG8_MMA(0, 0, At, B0); PG8_MMA(0, 1, At, B1); PG8_BAR; PG8_SCHED;
	s_waitcnt lgkmcnt(0)
	v_mfma_f32_16x16x32_bf16 v[64:67], v[146:149], v[178:181], v[64:67]
	v_mfma_f32_16x16x32_bf16 v[60:63], v[154:157], v[178:181], v[60:63]
	v_mfma_f32_16x16x32_bf16 v[56:59], v[146:149], v[186:189], v[56:59]
	v_mfma_f32_16x16x32_bf16 v[52:55], v[154:157], v[186:189], v[52:55]
	v_mfma_f32_16x16x32_bf16 v[48:51], v[146:149], v[194:197], v[48:51]
	v_mfma_f32_16x16x32_bf16 v[44:47], v[154:157], v[194:197], v[44:47]
	v_mfma_f32_16x16x32_bf16 v[40:43], v[146:149], v[202:205], v[40:43]
	v_mfma_f32_16x16x32_bf16 v[36:39], v[154:157], v[202:205], v[36:39]
	v_mfma_f32_16x16x32_bf16 v[64:67], v[150:153], v[182:185], v[64:67]
	v_mfma_f32_16x16x32_bf16 v[60:63], v[158:161], v[182:185], v[60:63]
	v_mfma_f32_16x16x32_bf16 v[56:59], v[150:153], v[190:193], v[56:59]
	v_mfma_f32_16x16x32_bf16 v[52:55], v[158:161], v[190:193], v[52:55]
	v_mfma_f32_16x16x32_bf16 v[48:51], v[150:153], v[198:201], v[48:51]
	v_mfma_f32_16x16x32_bf16 v[44:47], v[158:161], v[198:201], v[44:47]
	v_mfma_f32_16x16x32_bf16 v[40:43], v[150:153], v[230:233], v[40:43]
	v_mfma_f32_16x16x32_bf16 v[36:39], v[158:161], v[230:233], v[36:39]
	v_mfma_f32_16x16x32_bf16 v[32:35], v[162:165], v[178:181], v[32:35]
	v_mfma_f32_16x16x32_bf16 v[28:31], v[170:173], v[178:181], v[28:31]
	v_mfma_f32_16x16x32_bf16 v[24:27], v[162:165], v[186:189], v[24:27]
	v_mfma_f32_16x16x32_bf16 v[20:23], v[170:173], v[186:189], v[20:23]
	v_mfma_f32_16x16x32_bf16 v[16:19], v[162:165], v[194:197], v[16:19]
	v_mfma_f32_16x16x32_bf16 v[12:15], v[170:173], v[194:197], v[12:15]
	v_mfma_f32_16x16x32_bf16 v[8:11], v[162:165], v[202:205], v[8:11]
	v_mfma_f32_16x16x32_bf16 v[4:7], v[170:173], v[202:205], v[4:7]
	v_mfma_f32_16x16x32_bf16 v[32:35], v[166:169], v[182:185], v[32:35]
	v_mfma_f32_16x16x32_bf16 v[28:31], v[174:177], v[182:185], v[28:31]
	v_mfma_f32_16x16x32_bf16 v[24:27], v[166:169], v[190:193], v[24:27]
	v_mfma_f32_16x16x32_bf16 v[20:23], v[174:177], v[190:193], v[20:23]
	v_mfma_f32_16x16x32_bf16 v[16:19], v[166:169], v[198:201], v[16:19]
	v_mfma_f32_16x16x32_bf16 v[12:15], v[174:177], v[198:201], v[12:15]
	v_mfma_f32_16x16x32_bf16 v[8:11], v[166:169], v[230:233], v[8:11]
	v_mfma_f32_16x16x32_bf16 v[4:7], v[174:177], v[230:233], v[4:7]
	s_barrier
	s_add_i32 s46, 0, 0x18000
	v_add_u32_e32 v145, s46, v143
	s_add_i32 s47, 0, 0x1c000
	ds_read_b128 v[146:149], v145
	ds_read_b128 v[150:153], v145 offset:1024
	ds_read_b128 v[154:157], v145 offset:2048
	ds_read_b128 v[158:161], v145 offset:3072
	v_add_u32_e32 v145, s47, v143
	ds_read_b128 v[162:165], v145
	ds_read_b128 v[166:169], v145 offset:1024
	ds_read_b128 v[170:173], v145 offset:2048
	ds_read_b128 v[174:177], v145 offset:3072
	s_add_u32 s16, s22, 0x40000
	s_addc_u32 s17, s23, 0
	s_mov_b32 m0, s36
	v_lshl_add_u64 v[240:241], s[16:17], 0, v[134:135]
	ds_read_b128 v[178:181], v144 offset:32768
	ds_read_b128 v[182:185], v144 offset:33792
	ds_read_b128 v[186:189], v144 offset:34816
	ds_read_b128 v[190:193], v144 offset:35840
	ds_read_b128 v[194:197], v144 offset:36864
	ds_read_b128 v[198:201], v144 offset:37888
	ds_read_b128 v[202:205], v144 offset:38912
	ds_read_b128 v[230:233], v144 offset:39936
	global_load_lds_dwordx4 v[240:241], off
	v_lshl_add_u64 v[240:241], s[16:17], 0, v[132:133]
	s_mov_b32 m0, s37
	s_nop 0
	global_load_lds_dwordx4 v[240:241], off
	s_waitcnt vmcnt(8)
	s_waitcnt lgkmcnt(0)
	s_barrier
	s_waitcnt lgkmcnt(0)
	v_mfma_f32_16x16x32_bf16 v[128:131], v[146:149], v[178:181], v[128:131]
	v_mfma_f32_16x16x32_bf16 v[124:127], v[154:157], v[178:181], v[124:127]
	v_mfma_f32_16x16x32_bf16 v[120:123], v[146:149], v[186:189], v[120:123]
	v_mfma_f32_16x16x32_bf16 v[116:119], v[154:157], v[186:189], v[116:119]
	v_mfma_f32_16x16x32_bf16 v[112:115], v[146:149], v[194:197], v[112:115]
	v_mfma_f32_16x16x32_bf16 v[108:111], v[154:157], v[194:197], v[108:111]
	v_mfma_f32_16x16x32_bf16 v[104:107], v[146:149], v[202:205], v[104:107]
	v_mfma_f32_16x16x32_bf16 v[100:103], v[154:157], v[202:205], v[100:103]
	v_mfma_f32_16x16x32_bf16 v[128:131], v[150:153], v[182:185], v[128:131]
	v_mfma_f32_16x16x32_bf16 v[124:127], v[158:161], v[182:185], v[124:127]
	v_mfma_f32_16x16x32_bf16 v[120:123], v[150:153], v[190:193], v[120:123]
	v_mfma_f32_16x16x32_bf16 v[116:119], v[158:161], v[190:193], v[116:119]
	v_mfma_f32_16x16x32_bf16 v[112:115], v[150:153], v[198:201], v[112:115]
	v_mfma_f32_16x16x32_bf16 v[108:111], v[158:161], v[198:201], v[108:111]
	v_mfma_f32_16x16x32_bf16 v[104:107], v[150:153], v[230:233], v[104:107]
	v_mfma_f32_16x16x32_bf16 v[100:103], v[158:161], v[230:233], v[100:103]
	v_mfma_f32_16x16x32_bf16 v[96:99], v[162:165], v[178:181], v[96:99]
	v_mfma_f32_16x16x32_bf16 v[92:95], v[170:173], v[178:181], v[92:95]
	v_mfma_f32_16x16x32_bf16 v[88:91], v[162:165], v[186:189], v[88:91]
	v_mfma_f32_16x16x32_bf16 v[84:87], v[170:173], v[186:189], v[84:87]
	v_mfma_f32_16x16x32_bf16 v[80:83], v[162:165], v[194:197], v[80:83]
	v_mfma_f32_16x16x32_bf16 v[76:79], v[170:173], v[194:197], v[76:79]
	v_mfma_f32_16x16x32_bf16 v[72:75], v[162:165], v[202:205], v[72:75]
	v_mfma_f32_16x16x32_bf16 v[68:71], v[170:173], v[202:205], v[68:71]
	v_mfma_f32_16x16x32_bf16 v[96:99], v[166:169], v[182:185], v[96:99]
	v_mfma_f32_16x16x32_bf16 v[92:95], v[174:177], v[182:185], v[92:95]
	v_mfma_f32_16x16x32_bf16 v[88:91], v[166:169], v[190:193], v[88:91]
	v_mfma_f32_16x16x32_bf16 v[84:87], v[174:177], v[190:193], v[84:87]
	v_mfma_f32_16x16x32_bf16 v[80:83], v[166:169], v[198:201], v[80:83]
	v_mfma_f32_16x16x32_bf16 v[76:79], v[174:177], v[198:201], v[76:79]
	v_mfma_f32_16x16x32_bf16 v[72:75], v[166:169], v[230:233], v[72:75]
	v_mfma_f32_16x16x32_bf16 v[68:71], v[174:177], v[230:233], v[68:71]
	s_barrier
; #define PG8_STAGE(bufoff, gbase, voff) do { _Pragma("unroll") for (int _i = 0; _i < 2; ++_i) \
;         __builtin_amdgcn_global_load_lds((const unsigned*)((const char*)(gbase) + (voff)[_i]), (PG8_LAS unsigned*)(lds + (bufoff) + ldsw + _i * 8192), 16, 0, 0); } while (0)
; #define PG8_LDA(dst, b, h) do { _Pragma("unroll") for (int m = 0; m < 4; ++m) _Pragma("unroll") for (int k = 0; k < 2; ++k) dst[m][k] = *(const PG8_LAS bf16x8*)(lds + PG8_SA(b, h) + aoff + m * 2048 + k * 1024); } while (0)
; #define PG8_MMA(ai, bj, At, Bt) do { __builtin_amdgcn_s_setprio(1); _Pragma("unroll") for (int m = 0; m < 4; ++m) _Pragma("unroll") for (int n = 0; n < 2; ++n) _Pragma("unroll") for (int k = 0; k < 2; ++k) \
;         acc[ai][bj][m][n] = __builtin_amdgcn_mfma_f32_16x16x32_bf16(Bt[n][k], At[m][k], acc[ai][bj][m][n], 0, 0, 0); __builtin_amdgcn_s_setprio(0); } while (0)
; #define PG8_WAIT_V(n) asm volatile("s_waitcnt vmcnt(" #n ")" ::: "memory")
; #define PG8_WAIT_L(n) asm volatile("s_waitcnt lgkmcnt(" #n ")" ::: "memory")
; #define PG8_BAR __builtin_amdgcn_s_barrier()
; #define PG8_SCHED __builtin_amdgcn_sched_barrier(0)
; template <class Epi, class Sched, bool APERM>
; __device__ __forceinline__ void gemm_phase(PG8_LAS unsigned char* lds, const Gemm g, const Sched& S, const Epi& E) {
;     ...
;             PG8_LDA(At, 1, 1); PG8_STAGE(PG8_SB(1, 0), b3, voffB); PG8_STAGE(PG8_SB(1, 1), b3 + hstep, voffB); PG8_STAGE(PG8_SA(1, 0), a3, voffA);
;             PG8_WAIT_V(8); PG8_WAIT_L(0); PG8_BAR; PG8_MMA(1, 0, At, B0); PG8_MMA(1, 1, At, B1); PG8_BAR; PG8_SCHED;
;         }
;         if (wr == 0) PG8_BAR;
	s_add_i32 s16, s46, s35
	v_lshl_add_u64 v[222:223], v[222:223], 0, s[52:53]
	s_mov_b32 m0, s16
	ds_read_b128 v[178:181], v144 offset:49152
	ds_read_b128 v[182:185], v144 offset:50176
	ds_read_b128 v[186:189], v144 offset:51200
	ds_read_b128 v[190:193], v144 offset:52224
	ds_read_b128 v[194:197], v144 offset:53248
	ds_read_b128 v[198:201], v144 offset:54272
	ds_read_b128 v[202:205], v144 offset:55296
	ds_read_b128 v[230:233], v144 offset:56320
	global_load_lds_dwordx4 v[222:223], off
	s_add_i32 m0, s16, 0x2000
	s_add_u32 s16, s20, 0x40080
	v_lshl_add_u64 v[222:223], v[234:235], 0, s[52:53]
	s_addc_u32 s17, s21, 0
	s_add_i32 s20, s47, s35
	global_load_lds_dwordx4 v[222:223], off
	v_lshl_add_u64 v[222:223], s[16:17], 0, v[2:3]
	s_mov_b32 m0, s20
	s_nop 0
	global_load_lds_dwordx4 v[222:223], off
	v_lshl_add_u64 v[222:223], s[16:17], 0, v[0:1]
	s_add_i32 m0, s20, 0x2000
	s_nop 0
	global_load_lds_dwordx4 v[222:223], off
	v_lshl_add_u64 v[222:223], v[236:237], 0, s[52:53]
	s_mov_b32 m0, s41
	s_nop 0
	global_load_lds_dwordx4 v[222:223], off
	v_lshl_add_u64 v[222:223], v[238:239], 0, s[52:53]
	s_mov_b32 m0, s44
	s_nop 0
	global_load_lds_dwordx4 v[222:223], off
	s_waitcnt vmcnt(8)
	s_waitcnt lgkmcnt(0)
	s_barrier
	s_waitcnt lgkmcnt(0)
	v_mfma_f32_16x16x32_bf16 v[64:67], v[146:149], v[178:181], v[64:67]
	v_mfma_f32_16x16x32_bf16 v[60:63], v[154:157], v[178:181], v[60:63]
	v_mfma_f32_16x16x32_bf16 v[56:59], v[146:149], v[186:189], v[56:59]
	v_mfma_f32_16x16x32_bf16 v[52:55], v[154:157], v[186:189], v[52:55]
	v_mfma_f32_16x16x32_bf16 v[48:51], v[146:149], v[194:197], v[48:51]
	v_mfma_f32_16x16x32_bf16 v[44:47], v[154:157], v[194:197], v[44:47]
	v_mfma_f32_16x16x32_bf16 v[40:43], v[146:149], v[202:205], v[40:43]
	v_mfma_f32_16x16x32_bf16 v[36:39], v[154:157], v[202:205], v[36:39]
	v_mfma_f32_16x16x32_bf16 v[64:67], v[150:153], v[182:185], v[64:67]
	v_mfma_f32_16x16x32_bf16 v[60:63], v[158:161], v[182:185], v[60:63]
	v_mfma_f32_16x16x32_bf16 v[56:59], v[150:153], v[190:193], v[56:59]
	v_mfma_f32_16x16x32_bf16 v[52:55], v[158:161], v[190:193], v[52:55]
	v_mfma_f32_16x16x32_bf16 v[48:51], v[150:153], v[198:201], v[48:51]
	v_mfma_f32_16x16x32_bf16 v[44:47], v[158:161], v[198:201], v[44:47]
	v_mfma_f32_16x16x32_bf16 v[40:43], v[150:153], v[230:233], v[40:43]
	v_mfma_f32_16x16x32_bf16 v[36:39], v[158:161], v[230:233], v[36:39]
	v_mfma_f32_16x16x32_bf16 v[32:35], v[162:165], v[178:181], v[32:35]
	v_mfma_f32_16x16x32_bf16 v[28:31], v[170:173], v[178:181], v[28:31]
	v_mfma_f32_16x16x32_bf16 v[24:27], v[162:165], v[186:189], v[24:27]
	v_mfma_f32_16x16x32_bf16 v[20:23], v[170:173], v[186:189], v[20:23]
	v_mfma_f32_16x16x32_bf16 v[16:19], v[162:165], v[194:197], v[16:19]
	v_mfma_f32_16x16x32_bf16 v[12:15], v[170:173], v[194:197], v[12:15]
	v_mfma_f32_16x16x32_bf16 v[8:11], v[162:165], v[202:205], v[8:11]
	v_mfma_f32_16x16x32_bf16 v[4:7], v[170:173], v[202:205], v[4:7]
	v_mfma_f32_16x16x32_bf16 v[32:35], v[166:169], v[182:185], v[32:35]
	v_mfma_f32_16x16x32_bf16 v[28:31], v[174:177], v[182:185], v[28:31]
	v_mfma_f32_16x16x32_bf16 v[24:27], v[166:169], v[190:193], v[24:27]
	v_mfma_f32_16x16x32_bf16 v[20:23], v[174:177], v[190:193], v[20:23]
	v_mfma_f32_16x16x32_bf16 v[16:19], v[166:169], v[198:201], v[16:19]
	v_mfma_f32_16x16x32_bf16 v[12:15], v[174:177], v[198:201], v[12:15]
	v_mfma_f32_16x16x32_bf16 v[8:11], v[166:169], v[230:233], v[8:11]
	v_mfma_f32_16x16x32_bf16 v[4:7], v[174:177], v[230:233], v[4:7]
	s_barrier
	s_add_i32 s45, s45, 2
	s_cmp_gt_u32 s45, 5
	s_mov_b64 s[16:17], s[18:19]
	s_cbranch_scc0 .LBB0_979
	s_cmpk_lt_u32 s34, 0x100
	s_cbranch_scc0 .LBB0_982
	s_barrier

; #define PG8_STAGE(bufoff, gbase, voff) do { _Pragma("unroll") for (int _i = 0; _i < 2; ++_i) \
;         __builtin_amdgcn_global_load_lds((const unsigned*)((const char*)(gbase) + (voff)[_i]), (PG8_LAS unsigned*)(lds + (bufoff) + ldsw + _i * 8192), 16, 0, 0); } while (0)
; #define PG8_LDA(dst, b, h) do { _Pragma("unroll") for (int m = 0; m < 4; ++m) _Pragma("unroll") for (int k = 0; k < 2; ++k) dst[m][k] = *(const PG8_LAS bf16x8*)(lds + PG8_SA(b, h) + aoff + m * 2048 + k * 1024); } while (0)
; #define PG8_LDB(dst, b, h) do { _Pragma("unroll") for (int n = 0; n < 2; ++n) _Pragma("unroll") for (int k = 0; k < 2; ++k) dst[n][k] = *(const PG8_LAS bf16x8*)(lds + PG8_SB(b, h) + boff + n * 2048 + k * 1024); } while (0)
; #define PG8_MMA(ai, bj, At, Bt) do { __builtin_amdgcn_s_setprio(1); _Pragma("unroll") for (int m = 0; m < 4; ++m) _Pragma("unroll") for (int n = 0; n < 2; ++n) _Pragma("unroll") for (int k = 0; k < 2; ++k) \
;         acc[ai][bj][m][n] = __builtin_amdgcn_mfma_f32_16x16x32_bf16(Bt[n][k], At[m][k], acc[ai][bj][m][n], 0, 0, 0); __builtin_amdgcn_s_setprio(0); } while (0)
; #define PG8_WAIT_V(n) asm volatile("s_waitcnt vmcnt(" #n ")" ::: "memory")
; #define PG8_WAIT_L(n) asm volatile("s_waitcnt lgkmcnt(" #n ")" ::: "memory")
; #define PG8_BAR __builtin_amdgcn_s_barrier()
; template <class Epi, class Sched, bool APERM>
; __device__ __forceinline__ void gemm_phase(PG8_LAS unsigned char* lds, const Gemm g, const Sched& S, const Epi& E) {
;     ...
;         for (int t = 0; t < nt; t += 2) {
;             const bool last = (t == nt - 2);
;             const char* a1 = cA + (size_t)(t + 1) * kstep;
;             const char* a2 = last ? nA : cA + (size_t)(t + 2) * kstep; const char* b2 = last ? nB : cB + (size_t)(t + 2) * kstep;
;             const char* a3 = a2 + kstep; const char* b3 = b2 + kstep;
;             if (last && has_next) S.a_ready(nxt);
;             PG8_LDB(B0, 0, 0); PG8_LDB(B1, 0, 1); PG8_SCHED; PG8_LDA(At, 0, 0); PG8_STAGE(PG8_SA(1, 1), a1 + hstepA, voffA);
;             PG8_WAIT_V(8); PG8_WAIT_L(0); PG8_BAR; PG8_MMA(0, 0, At, B0); PG8_MMA(0, 1, At, B1); PG8_BAR; PG8_SCHED;
;             PG8_LDA(At, 0, 1); PG8_STAGE(PG8_SB(0, 0), b2, voffB); PG8_STAGE(PG8_SB(0, 1), b2 + hstep, voffB); PG8_STAGE(PG8_SA(0, 0), a2, voffA);
;             PG8_WAIT_V(8); PG8_WAIT_L(0); PG8_BAR; PG8_MMA(1, 0, At, B0); PG8_MMA(1, 1, At, B1); PG8_BAR; PG8_SCHED;
.LBB0_992:
	s_add_u32 s14, s28, s10
	s_addc_u32 s15, s29, s11
	s_add_u32 s14, s14, 0xf200100
	s_addc_u32 s15, s15, 0
	s_add_u32 s36, s27, s10
	s_addc_u32 s37, s34, s11
	s_add_i32 s40, 0, 0x10000
	s_cmpk_eq_i32 s10, 0x300
	s_cselect_b32 s17, s13, s15
	s_cselect_b32 s16, s12, s14
	s_cselect_b32 s15, s5, s37
	s_cselect_b32 s14, s4, s36
	s_add_i32 s41, 0, 0x14000
	v_add_u32_e32 v156, s40, v142
	v_add_u32_e32 v172, s41, v142
	ds_read_b128 v[144:147], v156
	ds_read_b128 v[148:151], v156 offset:1024
	ds_read_b128 v[152:155], v156 offset:2048
	ds_read_b128 v[156:159], v156 offset:3072
	ds_read_b128 v[160:163], v172
	ds_read_b128 v[164:167], v172 offset:1024
	ds_read_b128 v[168:171], v172 offset:2048
	ds_read_b128 v[172:175], v172 offset:3072
	v_lshl_add_u64 v[184:185], v[136:137], 0, s[10:11]
	s_add_i32 m0, s20, 0xc000
	ds_read_b128 v[176:179], v143
	ds_read_b128 v[180:183], v143 offset:1024
	ds_read_b128 v[188:191], v143 offset:2048
	ds_read_b128 v[192:195], v143 offset:3072
	ds_read_b128 v[196:199], v143 offset:4096
	ds_read_b128 v[200:203], v143 offset:5120
	ds_read_b128 v[230:233], v143 offset:6144
	ds_read_b128 v[234:237], v143 offset:7168
	global_load_lds_dwordx4 v[184:185], off
	v_lshl_add_u64 v[184:185], v[138:139], 0, s[10:11]
	s_add_i32 m0, s20, 0xe000
	s_nop 0
	global_load_lds_dwordx4 v[184:185], off
	s_waitcnt vmcnt(8)
	s_waitcnt lgkmcnt(0)
	s_barrier
	s_waitcnt lgkmcnt(0)
	v_mfma_f32_16x16x32_bf16 v[128:131], v[144:147], v[176:179], v[128:131]
	v_mfma_f32_16x16x32_bf16 v[124:127], v[152:155], v[176:179], v[124:127]
	v_mfma_f32_16x16x32_bf16 v[120:123], v[144:147], v[188:191], v[120:123]
	v_mfma_f32_16x16x32_bf16 v[116:119], v[152:155], v[188:191], v[116:119]
	v_mfma_f32_16x16x32_bf16 v[112:115], v[144:147], v[196:199], v[112:115]
	v_mfma_f32_16x16x32_bf16 v[108:111], v[152:155], v[196:199], v[108:111]
	v_mfma_f32_16x16x32_bf16 v[104:107], v[144:147], v[230:233], v[104:107]
	v_mfma_f32_16x16x32_bf16 v[100:103], v[152:155], v[230:233], v[100:103]
	v_mfma_f32_16x16x32_bf16 v[128:131], v[148:151], v[180:183], v[128:131]
	v_mfma_f32_16x16x32_bf16 v[124:127], v[156:159], v[180:183], v[124:127]
	v_mfma_f32_16x16x32_bf16 v[120:123], v[148:151], v[192:195], v[120:123]
	v_mfma_f32_16x16x32_bf16 v[116:119], v[156:159], v[192:195], v[116:119]
	v_mfma_f32_16x16x32_bf16 v[112:115], v[148:151], v[200:203], v[112:115]
	v_mfma_f32_16x16x32_bf16 v[108:111], v[156:159], v[200:203], v[108:111]
	v_mfma_f32_16x16x32_bf16 v[104:107], v[148:151], v[234:237], v[104:107]
	v_mfma_f32_16x16x32_bf16 v[100:103], v[156:159], v[234:237], v[100:103]
	v_mfma_f32_16x16x32_bf16 v[96:99], v[160:163], v[176:179], v[96:99]
	v_mfma_f32_16x16x32_bf16 v[92:95], v[168:171], v[176:179], v[92:95]
	v_mfma_f32_16x16x32_bf16 v[88:91], v[160:163], v[188:191], v[88:91]
	v_mfma_f32_16x16x32_bf16 v[84:87], v[168:171], v[188:191], v[84:87]
	v_mfma_f32_16x16x32_bf16 v[80:83], v[160:163], v[196:199], v[80:83]
	v_mfma_f32_16x16x32_bf16 v[76:79], v[168:171], v[196:199], v[76:79]
	v_mfma_f32_16x16x32_bf16 v[72:75], v[160:163], v[230:233], v[72:75]
	v_mfma_f32_16x16x32_bf16 v[68:71], v[168:171], v[230:233], v[68:71]
	v_mfma_f32_16x16x32_bf16 v[96:99], v[164:167], v[180:183], v[96:99]
	v_mfma_f32_16x16x32_bf16 v[92:95], v[172:175], v[180:183], v[92:95]
	v_mfma_f32_16x16x32_bf16 v[88:91], v[164:167], v[192:195], v[88:91]
	v_mfma_f32_16x16x32_bf16 v[84:87], v[172:175], v[192:195], v[84:87]
	v_mfma_f32_16x16x32_bf16 v[80:83], v[164:167], v[200:203], v[80:83]
	v_mfma_f32_16x16x32_bf16 v[76:79], v[172:175], v[200:203], v[76:79]
	v_mfma_f32_16x16x32_bf16 v[72:75], v[164:167], v[234:237], v[72:75]
	v_mfma_f32_16x16x32_bf16 v[68:71], v[172:175], v[234:237], v[68:71]
	s_barrier
	s_add_i32 s36, s40, s19
	v_lshl_add_u64 v[184:185], s[14:15], 0, v[2:3]
	s_mov_b32 m0, s36
	ds_read_b128 v[176:179], v143 offset:16384
	ds_read_b128 v[180:183], v143 offset:17408
	ds_read_b128 v[188:191], v143 offset:18432
	ds_read_b128 v[192:195], v143 offset:19456
	ds_read_b128 v[196:199], v143 offset:20480
	ds_read_b128 v[200:203], v143 offset:21504
	ds_read_b128 v[230:233], v143 offset:22528
	ds_read_b128 v[234:237], v143 offset:23552
	global_load_lds_dwordx4 v[184:185], off
	s_add_i32 m0, s36, 0x2000
	s_add_u32 s36, s14, 0x40000
	v_lshl_add_u64 v[204:205], s[14:15], 0, v[0:1]
	s_addc_u32 s37, s15, 0
	s_add_i32 s40, s41, s19
	global_load_lds_dwordx4 v[204:205], off
	v_lshl_add_u64 v[222:223], s[36:37], 0, v[2:3]
	s_mov_b32 m0, s40
	v_lshl_add_u64 v[238:239], s[16:17], 0, v[132:133]
	global_load_lds_dwordx4 v[222:223], off
	v_lshl_add_u64 v[222:223], s[36:37], 0, v[0:1]
	s_add_i32 m0, s40, 0x2000
	s_nop 0
	global_load_lds_dwordx4 v[222:223], off
	v_lshl_add_u64 v[222:223], s[16:17], 0, v[134:135]
	s_mov_b32 m0, s20
	s_nop 0
	global_load_lds_dwordx4 v[222:223], off
	s_mov_b32 m0, s21
	s_nop 0
	global_load_lds_dwordx4 v[238:239], off
	s_waitcnt vmcnt(8)
	s_waitcnt lgkmcnt(0)
	s_barrier
; #define PG8_STAGE(bufoff, gbase, voff) do { _Pragma("unroll") for (int _i = 0; _i < 2; ++_i) \
;         __builtin_amdgcn_global_load_lds((const unsigned*)((const char*)(gbase) + (voff)[_i]), (PG8_LAS unsigned*)(lds + (bufoff) + ldsw + _i * 8192), 16, 0, 0); } while (0)
; #define PG8_LDA(dst, b, h) do { _Pragma("unroll") for (int m = 0; m < 4; ++m) _Pragma("unroll") for (int k = 0; k < 2; ++k) dst[m][k] = *(const PG8_LAS bf16x8*)(lds + PG8_SA(b, h) + aoff + m * 2048 + k * 1024); } while (0)
; #define PG8_LDB(dst, b, h) do { _Pragma("unroll") for (int n = 0; n < 2; ++n) _Pragma("unroll") for (int k = 0; k < 2; ++k) dst[n][k] = *(const PG8_LAS bf16x8*)(lds + PG8_SB(b, h) + boff + n * 2048 + k * 1024); } while (0)
; #define PG8_MMA(ai, bj, At, Bt) do { __builtin_amdgcn_s_setprio(1); _Pragma("unroll") for (int m = 0; m < 4; ++m) _Pragma("unroll") for (int n = 0; n < 2; ++n) _Pragma("unroll") for (int k = 0; k < 2; ++k) \
;         acc[ai][bj][m][n] = __builtin_amdgcn_mfma_f32_16x16x32_bf16(Bt[n][k], At[m][k], acc[ai][bj][m][n], 0, 0, 0); __builtin_amdgcn_s_setprio(0); } while (0)
; #define PG8_WAIT_V(n) asm volatile("s_waitcnt vmcnt(" #n ")" ::: "memory")
; #define PG8_WAIT_L(n) asm volatile("s_waitcnt lgkmcnt(" #n ")" ::: "memory")
; #define PG8_BAR __builtin_amdgcn_s_barrier()
; #define PG8_SCHED __builtin_amdgcn_sched_barrier(0)
; template <class Epi, class Sched, bool APERM>
; __device__ __forceinline__ void gemm_phase(PG8_LAS unsigned char* lds, const Gemm g, const Sched& S, const Epi& E) {
;     ...
;             PG8_WAIT_V(8); PG8_WAIT_L(0); PG8_BAR; PG8_MMA(1, 0, At, B0); PG8_MMA(1, 1, At, B1); PG8_BAR; PG8_SCHED;
;             PG8_LDB(B0, 1, 0); PG8_LDB(B1, 1, 1); PG8_SCHED; PG8_LDA(At, 1, 0); PG8_STAGE(PG8_SA(0, 1), a2 + hstepA, voffA);
;             PG8_WAIT_V(8); PG8_WAIT_L(0); PG8_BAR; PG8_MMA(0, 0, At, B0); PG8_MMA(0, 1, At, B1); PG8_BAR; PG8_SCHED;
	s_waitcnt lgkmcnt(0)
	v_mfma_f32_16x16x32_bf16 v[64:67], v[144:147], v[176:179], v[64:67]
	v_mfma_f32_16x16x32_bf16 v[60:63], v[152:155], v[176:179], v[60:63]
	v_mfma_f32_16x16x32_bf16 v[56:59], v[144:147], v[188:191], v[56:59]
	v_mfma_f32_16x16x32_bf16 v[52:55], v[152:155], v[188:191], v[52:55]
	v_mfma_f32_16x16x32_bf16 v[48:51], v[144:147], v[196:199], v[48:51]
	v_mfma_f32_16x16x32_bf16 v[44:47], v[152:155], v[196:199], v[44:47]
	v_mfma_f32_16x16x32_bf16 v[40:43], v[144:147], v[230:233], v[40:43]
	v_mfma_f32_16x16x32_bf16 v[36:39], v[152:155], v[230:233], v[36:39]
	v_mfma_f32_16x16x32_bf16 v[64:67], v[148:151], v[180:183], v[64:67]
	v_mfma_f32_16x16x32_bf16 v[60:63], v[156:159], v[180:183], v[60:63]
	v_mfma_f32_16x16x32_bf16 v[56:59], v[148:151], v[192:195], v[56:59]
	v_mfma_f32_16x16x32_bf16 v[52:55], v[156:159], v[192:195], v[52:55]
	v_mfma_f32_16x16x32_bf16 v[48:51], v[148:151], v[200:203], v[48:51]
	v_mfma_f32_16x16x32_bf16 v[44:47], v[156:159], v[200:203], v[44:47]
	v_mfma_f32_16x16x32_bf16 v[40:43], v[148:151], v[234:237], v[40:43]
	v_mfma_f32_16x16x32_bf16 v[36:39], v[156:159], v[234:237], v[36:39]
	v_mfma_f32_16x16x32_bf16 v[32:35], v[160:163], v[176:179], v[32:35]
	v_mfma_f32_16x16x32_bf16 v[28:31], v[168:171], v[176:179], v[28:31]
	v_mfma_f32_16x16x32_bf16 v[24:27], v[160:163], v[188:191], v[24:27]
	v_mfma_f32_16x16x32_bf16 v[20:23], v[168:171], v[188:191], v[20:23]
	v_mfma_f32_16x16x32_bf16 v[16:19], v[160:163], v[196:199], v[16:19]
	v_mfma_f32_16x16x32_bf16 v[12:15], v[168:171], v[196:199], v[12:15]
	v_mfma_f32_16x16x32_bf16 v[8:11], v[160:163], v[230:233], v[8:11]
	v_mfma_f32_16x16x32_bf16 v[4:7], v[168:171], v[230:233], v[4:7]
	v_mfma_f32_16x16x32_bf16 v[32:35], v[164:167], v[180:183], v[32:35]
	v_mfma_f32_16x16x32_bf16 v[28:31], v[172:175], v[180:183], v[28:31]
	v_mfma_f32_16x16x32_bf16 v[24:27], v[164:167], v[192:195], v[24:27]
	v_mfma_f32_16x16x32_bf16 v[20:23], v[172:175], v[192:195], v[20:23]
	v_mfma_f32_16x16x32_bf16 v[16:19], v[164:167], v[200:203], v[16:19]
	v_mfma_f32_16x16x32_bf16 v[12:15], v[172:175], v[200:203], v[12:15]
	v_mfma_f32_16x16x32_bf16 v[8:11], v[164:167], v[234:237], v[8:11]
	v_mfma_f32_16x16x32_bf16 v[4:7], v[172:175], v[234:237], v[4:7]
	s_barrier
	s_add_i32 s36, 0, 0x18000
	s_add_i32 s37, 0, 0x1c000
	v_add_u32_e32 v156, s36, v142
	v_add_u32_e32 v172, s37, v142
	ds_read_b128 v[144:147], v156
	ds_read_b128 v[148:151], v156 offset:1024
	ds_read_b128 v[152:155], v156 offset:2048
	ds_read_b128 v[156:159], v156 offset:3072
	ds_read_b128 v[160:163], v172
	ds_read_b128 v[164:167], v172 offset:1024
	ds_read_b128 v[168:171], v172 offset:2048
	ds_read_b128 v[172:175], v172 offset:3072
	s_add_u32 s16, s16, 0x40000
	s_addc_u32 s17, s17, 0
	s_mov_b32 m0, s22
	v_lshl_add_u64 v[240:241], s[16:17], 0, v[134:135]
	ds_read_b128 v[176:179], v143 offset:32768
	ds_read_b128 v[180:183], v143 offset:33792
	ds_read_b128 v[188:191], v143 offset:34816
	ds_read_b128 v[192:195], v143 offset:35840
	ds_read_b128 v[196:199], v143 offset:36864
	ds_read_b128 v[200:203], v143 offset:37888
	ds_read_b128 v[230:233], v143 offset:38912
	ds_read_b128 v[234:237], v143 offset:39936
	global_load_lds_dwordx4 v[240:241], off
	v_lshl_add_u64 v[240:241], s[16:17], 0, v[132:133]
	s_mov_b32 m0, s23
	s_nop 0
	global_load_lds_dwordx4 v[240:241], off
	s_waitcnt vmcnt(8)
	s_waitcnt lgkmcnt(0)
	s_barrier
	s_waitcnt lgkmcnt(0)
	v_mfma_f32_16x16x32_bf16 v[128:131], v[144:147], v[176:179], v[128:131]
	v_mfma_f32_16x16x32_bf16 v[124:127], v[152:155], v[176:179], v[124:127]
	v_mfma_f32_16x16x32_bf16 v[120:123], v[144:147], v[188:191], v[120:123]
	v_mfma_f32_16x16x32_bf16 v[116:119], v[152:155], v[188:191], v[116:119]
	v_mfma_f32_16x16x32_bf16 v[112:115], v[144:147], v[196:199], v[112:115]
	v_mfma_f32_16x16x32_bf16 v[108:111], v[152:155], v[196:199], v[108:111]
	v_mfma_f32_16x16x32_bf16 v[104:107], v[144:147], v[230:233], v[104:107]
	v_mfma_f32_16x16x32_bf16 v[100:103], v[152:155], v[230:233], v[100:103]
	v_mfma_f32_16x16x32_bf16 v[128:131], v[148:151], v[180:183], v[128:131]
	v_mfma_f32_16x16x32_bf16 v[124:127], v[156:159], v[180:183], v[124:127]
	v_mfma_f32_16x16x32_bf16 v[120:123], v[148:151], v[192:195], v[120:123]
	v_mfma_f32_16x16x32_bf16 v[116:119], v[156:159], v[192:195], v[116:119]
	v_mfma_f32_16x16x32_bf16 v[112:115], v[148:151], v[200:203], v[112:115]
	v_mfma_f32_16x16x32_bf16 v[108:111], v[156:159], v[200:203], v[108:111]
	v_mfma_f32_16x16x32_bf16 v[104:107], v[148:151], v[234:237], v[104:107]
	v_mfma_f32_16x16x32_bf16 v[100:103], v[156:159], v[234:237], v[100:103]
	v_mfma_f32_16x16x32_bf16 v[96:99], v[160:163], v[176:179], v[96:99]
	v_mfma_f32_16x16x32_bf16 v[92:95], v[168:171], v[176:179], v[92:95]
	v_mfma_f32_16x16x32_bf16 v[88:91], v[160:163], v[188:191], v[88:91]
	v_mfma_f32_16x16x32_bf16 v[84:87], v[168:171], v[188:191], v[84:87]
	v_mfma_f32_16x16x32_bf16 v[80:83], v[160:163], v[196:199], v[80:83]
	v_mfma_f32_16x16x32_bf16 v[76:79], v[168:171], v[196:199], v[76:79]
	v_mfma_f32_16x16x32_bf16 v[72:75], v[160:163], v[230:233], v[72:75]
	v_mfma_f32_16x16x32_bf16 v[68:71], v[168:171], v[230:233], v[68:71]
	v_mfma_f32_16x16x32_bf16 v[96:99], v[164:167], v[180:183], v[96:99]
	v_mfma_f32_16x16x32_bf16 v[92:95], v[172:175], v[180:183], v[92:95]
	v_mfma_f32_16x16x32_bf16 v[88:91], v[164:167], v[192:195], v[88:91]
	v_mfma_f32_16x16x32_bf16 v[84:87], v[172:175], v[192:195], v[84:87]
	v_mfma_f32_16x16x32_bf16 v[80:83], v[164:167], v[200:203], v[80:83]
	v_mfma_f32_16x16x32_bf16 v[76:79], v[172:175], v[200:203], v[76:79]
	v_mfma_f32_16x16x32_bf16 v[72:75], v[164:167], v[234:237], v[72:75]
	v_mfma_f32_16x16x32_bf16 v[68:71], v[172:175], v[234:237], v[68:71]
	s_barrier
; #define PG8_STAGE(bufoff, gbase, voff) do { _Pragma("unroll") for (int _i = 0; _i < 2; ++_i) \
;         __builtin_amdgcn_global_load_lds((const unsigned*)((const char*)(gbase) + (voff)[_i]), (PG8_LAS unsigned*)(lds + (bufoff) + ldsw + _i * 8192), 16, 0, 0); } while (0)
; #define PG8_LDA(dst, b, h) do { _Pragma("unroll") for (int m = 0; m < 4; ++m) _Pragma("unroll") for (int k = 0; k < 2; ++k) dst[m][k] = *(const PG8_LAS bf16x8*)(lds + PG8_SA(b, h) + aoff + m * 2048 + k * 1024); } while (0)
; #define PG8_MMA(ai, bj, At, Bt) do { __builtin_amdgcn_s_setprio(1); _Pragma("unroll") for (int m = 0; m < 4; ++m) _Pragma("unroll") for (int n = 0; n < 2; ++n) _Pragma("unroll") for (int k = 0; k < 2; ++k) \
;         acc[ai][bj][m][n] = __builtin_amdgcn_mfma_f32_16x16x32_bf16(Bt[n][k], At[m][k], acc[ai][bj][m][n], 0, 0, 0); __builtin_amdgcn_s_setprio(0); } while (0)
; #define PG8_WAIT_V(n) asm volatile("s_waitcnt vmcnt(" #n ")" ::: "memory")
; #define PG8_WAIT_L(n) asm volatile("s_waitcnt lgkmcnt(" #n ")" ::: "memory")
; #define PG8_BAR __builtin_amdgcn_s_barrier()
; #define PG8_SCHED __builtin_amdgcn_sched_barrier(0)
; template <class Epi, class Sched, bool APERM>
; __device__ __forceinline__ void gemm_phase(PG8_LAS unsigned char* lds, const Gemm g, const Sched& S, const Epi& E) {
;     ...
;             PG8_LDA(At, 1, 1); PG8_STAGE(PG8_SB(1, 0), b3, voffB); PG8_STAGE(PG8_SB(1, 1), b3 + hstep, voffB); PG8_STAGE(PG8_SA(1, 0), a3, voffA);
;             PG8_WAIT_V(8); PG8_WAIT_L(0); PG8_BAR; PG8_MMA(1, 0, At, B0); PG8_MMA(1, 1, At, B1); PG8_BAR; PG8_SCHED;
;         }
;         if (wr == 0) PG8_BAR;
	s_add_i32 s16, s36, s19
	v_lshl_add_u64 v[184:185], v[184:185], 0, s[52:53]
	s_mov_b32 m0, s16
	ds_read_b128 v[176:179], v143 offset:49152
	ds_read_b128 v[180:183], v143 offset:50176
	ds_read_b128 v[188:191], v143 offset:51200
	ds_read_b128 v[192:195], v143 offset:52224
	ds_read_b128 v[196:199], v143 offset:53248
	ds_read_b128 v[200:203], v143 offset:54272
	ds_read_b128 v[230:233], v143 offset:55296
	ds_read_b128 v[234:237], v143 offset:56320
	global_load_lds_dwordx4 v[184:185], off
	s_add_i32 m0, s16, 0x2000
	s_add_u32 s14, s14, 0x40080
	v_lshl_add_u64 v[184:185], v[204:205], 0, s[52:53]
	s_addc_u32 s15, s15, 0
	s_add_i32 s16, s37, s19
	global_load_lds_dwordx4 v[184:185], off
	v_lshl_add_u64 v[184:185], s[14:15], 0, v[2:3]
	s_mov_b32 m0, s16
	s_nop 0
	global_load_lds_dwordx4 v[184:185], off
	v_lshl_add_u64 v[184:185], s[14:15], 0, v[0:1]
	s_add_i32 m0, s16, 0x2000
	s_nop 0
	global_load_lds_dwordx4 v[184:185], off
	v_lshl_add_u64 v[184:185], v[222:223], 0, s[52:53]
	s_mov_b32 m0, s25
	s_nop 0
	global_load_lds_dwordx4 v[184:185], off
	v_lshl_add_u64 v[184:185], v[238:239], 0, s[52:53]
	s_mov_b32 m0, s26
	s_nop 0
	global_load_lds_dwordx4 v[184:185], off
	s_waitcnt vmcnt(8)
	s_waitcnt lgkmcnt(0)
	s_barrier
	s_waitcnt lgkmcnt(0)
	v_mfma_f32_16x16x32_bf16 v[64:67], v[144:147], v[176:179], v[64:67]
	v_mfma_f32_16x16x32_bf16 v[60:63], v[152:155], v[176:179], v[60:63]
	v_mfma_f32_16x16x32_bf16 v[56:59], v[144:147], v[188:191], v[56:59]
	v_mfma_f32_16x16x32_bf16 v[52:55], v[152:155], v[188:191], v[52:55]
	v_mfma_f32_16x16x32_bf16 v[48:51], v[144:147], v[196:199], v[48:51]
	v_mfma_f32_16x16x32_bf16 v[44:47], v[152:155], v[196:199], v[44:47]
	v_mfma_f32_16x16x32_bf16 v[40:43], v[144:147], v[230:233], v[40:43]
	v_mfma_f32_16x16x32_bf16 v[36:39], v[152:155], v[230:233], v[36:39]
	v_mfma_f32_16x16x32_bf16 v[64:67], v[148:151], v[180:183], v[64:67]
	v_mfma_f32_16x16x32_bf16 v[60:63], v[156:159], v[180:183], v[60:63]
	v_mfma_f32_16x16x32_bf16 v[56:59], v[148:151], v[192:195], v[56:59]
	v_mfma_f32_16x16x32_bf16 v[52:55], v[156:159], v[192:195], v[52:55]
	v_mfma_f32_16x16x32_bf16 v[48:51], v[148:151], v[200:203], v[48:51]
	v_mfma_f32_16x16x32_bf16 v[44:47], v[156:159], v[200:203], v[44:47]
	v_mfma_f32_16x16x32_bf16 v[40:43], v[148:151], v[234:237], v[40:43]
	v_mfma_f32_16x16x32_bf16 v[36:39], v[156:159], v[234:237], v[36:39]
	v_mfma_f32_16x16x32_bf16 v[32:35], v[160:163], v[176:179], v[32:35]
	v_mfma_f32_16x16x32_bf16 v[28:31], v[168:171], v[176:179], v[28:31]
	v_mfma_f32_16x16x32_bf16 v[24:27], v[160:163], v[188:191], v[24:27]
	v_mfma_f32_16x16x32_bf16 v[20:23], v[168:171], v[188:191], v[20:23]
	v_mfma_f32_16x16x32_bf16 v[16:19], v[160:163], v[196:199], v[16:19]
	v_mfma_f32_16x16x32_bf16 v[12:15], v[168:171], v[196:199], v[12:15]
	v_mfma_f32_16x16x32_bf16 v[8:11], v[160:163], v[230:233], v[8:11]
	v_mfma_f32_16x16x32_bf16 v[4:7], v[168:171], v[230:233], v[4:7]
	v_mfma_f32_16x16x32_bf16 v[32:35], v[164:167], v[180:183], v[32:35]
	v_mfma_f32_16x16x32_bf16 v[28:31], v[172:175], v[180:183], v[28:31]
	v_mfma_f32_16x16x32_bf16 v[24:27], v[164:167], v[192:195], v[24:27]
	v_mfma_f32_16x16x32_bf16 v[20:23], v[172:175], v[192:195], v[20:23]
	v_mfma_f32_16x16x32_bf16 v[16:19], v[164:167], v[200:203], v[16:19]
	v_mfma_f32_16x16x32_bf16 v[12:15], v[172:175], v[200:203], v[12:15]
	v_mfma_f32_16x16x32_bf16 v[8:11], v[164:167], v[234:237], v[8:11]
	v_mfma_f32_16x16x32_bf16 v[4:7], v[172:175], v[234:237], v[4:7]
	s_barrier
	s_add_i32 s35, s35, 2
	s_add_u32 s10, s10, 0x100
	s_addc_u32 s11, s11, 0
	s_cmp_gt_u32 s35, 5
	s_cbranch_scc0 .LBB0_992
	s_cmpk_lt_u32 s18, 0x100
	s_cbranch_scc0 .LBB0_995
	s_barrier

; #define PG8_STAGE(bufoff, gbase, voff) do { _Pragma("unroll") for (int _i = 0; _i < 2; ++_i) \
;         __builtin_amdgcn_global_load_lds((const unsigned*)((const char*)(gbase) + (voff)[_i]), (PG8_LAS unsigned*)(lds + (bufoff) + ldsw + _i * 8192), 16, 0, 0); } while (0)
; #define PG8_LDA(dst, b, h) do { _Pragma("unroll") for (int m = 0; m < 4; ++m) _Pragma("unroll") for (int k = 0; k < 2; ++k) dst[m][k] = *(const PG8_LAS bf16x8*)(lds + PG8_SA(b, h) + aoff + m * 2048 + k * 1024); } while (0)
; #define PG8_LDB(dst, b, h) do { _Pragma("unroll") for (int n = 0; n < 2; ++n) _Pragma("unroll") for (int k = 0; k < 2; ++k) dst[n][k] = *(const PG8_LAS bf16x8*)(lds + PG8_SB(b, h) + boff + n * 2048 + k * 1024); } while (0)
; #define PG8_MMA(ai, bj, At, Bt) do { __builtin_amdgcn_s_setprio(1); _Pragma("unroll") for (int m = 0; m < 4; ++m) _Pragma("unroll") for (int n = 0; n < 2; ++n) _Pragma("unroll") for (int k = 0; k < 2; ++k) \
;         acc[ai][bj][m][n] = __builtin_amdgcn_mfma_f32_16x16x32_bf16(Bt[n][k], At[m][k], acc[ai][bj][m][n], 0, 0, 0); __builtin_amdgcn_s_setprio(0); } while (0)
; #define PG8_WAIT_V(n) asm volatile("s_waitcnt vmcnt(" #n ")" ::: "memory")
; #define PG8_WAIT_L(n) asm volatile("s_waitcnt lgkmcnt(" #n ")" ::: "memory")
; #define PG8_BAR __builtin_amdgcn_s_barrier()
; template <class Epi, class Sched, bool APERM>
; __device__ __forceinline__ void gemm_phase(PG8_LAS unsigned char* lds, const Gemm g, const Sched& S, const Epi& E) {
;     ...
;         for (int t = 0; t < nt; t += 2) {
;             const bool last = (t == nt - 2);
;             const char* a1 = cA + (size_t)(t + 1) * kstep;
;             const char* a2 = last ? nA : cA + (size_t)(t + 2) * kstep; const char* b2 = last ? nB : cB + (size_t)(t + 2) * kstep;
;             const char* a3 = a2 + kstep; const char* b3 = b2 + kstep;
;             if (last && has_next) S.a_ready(nxt);
;             PG8_LDB(B0, 0, 0); PG8_LDB(B1, 0, 1); PG8_SCHED; PG8_LDA(At, 0, 0); PG8_STAGE(PG8_SA(1, 1), a1 + hstepA, voffA);
;             PG8_WAIT_V(8); PG8_WAIT_L(0); PG8_BAR; PG8_MMA(0, 0, At, B0); PG8_MMA(0, 1, At, B1); PG8_BAR; PG8_SCHED;
;             PG8_LDA(At, 0, 1); PG8_STAGE(PG8_SB(0, 0), b2, voffB); PG8_STAGE(PG8_SB(0, 1), b2 + hstep, voffB); PG8_STAGE(PG8_SA(0, 0), a2, voffA);
;             PG8_WAIT_V(8); PG8_WAIT_L(0); PG8_BAR; PG8_MMA(1, 0, At, B0); PG8_MMA(1, 1, At, B1); PG8_BAR; PG8_SCHED;
.LBB0_1312:
	s_add_u32 s36, s34, 0xfffc0080
	s_addc_u32 s37, s35, -1
	s_add_i32 s57, 0, 0x10000
	s_cmp_eq_u32 s56, 12
	s_cselect_b32 s41, s17, s37
	s_cselect_b32 s40, s25, s36
	v_add_u32_e32 v2, s57, v167
	s_cselect_b32 s37, s23, s49
	s_cselect_b32 s36, s44, s45
	s_add_i32 s60, 0, 0x14000
	ds_read_b128 v[142:145], v2
	ds_read_b128 v[146:149], v2 offset:1024
	ds_read_b128 v[150:153], v2 offset:2048
	ds_read_b128 v[154:157], v2 offset:3072
	v_add_u32_e32 v2, s60, v167
	ds_read_b128 v[158:161], v2
	ds_read_b128 v[162:165], v2 offset:1024
	ds_read_b128 v[170:173], v2 offset:2048
	ds_read_b128 v[174:177], v2 offset:3072
	v_lshl_add_u64 v[222:223], s[34:35], 0, v[138:139]
	s_add_i32 m0, s21, 0xc000
	ds_read_b128 v[178:181], v169
	ds_read_b128 v[182:185], v169 offset:1024
	ds_read_b128 v[186:189], v169 offset:2048
	ds_read_b128 v[190:193], v169 offset:3072
	ds_read_b128 v[194:197], v169 offset:4096
	ds_read_b128 v[198:201], v169 offset:5120
	ds_read_b128 v[202:205], v169 offset:6144
	ds_read_b128 v[230:233], v169 offset:7168
	global_load_lds_dwordx4 v[222:223], off
	v_lshl_add_u64 v[222:223], s[34:35], 0, v[140:141]
	s_add_i32 m0, s21, 0xe000
	s_nop 0
	global_load_lds_dwordx4 v[222:223], off
	s_waitcnt vmcnt(8)
	s_waitcnt lgkmcnt(0)
	s_barrier
	s_waitcnt lgkmcnt(0)
	v_mfma_f32_16x16x32_bf16 v[128:131], v[142:145], v[178:181], v[128:131]
	v_mfma_f32_16x16x32_bf16 v[124:127], v[150:153], v[178:181], v[124:127]
	v_mfma_f32_16x16x32_bf16 v[112:115], v[142:145], v[186:189], v[112:115]
	v_mfma_f32_16x16x32_bf16 v[108:111], v[150:153], v[186:189], v[108:111]
	v_mfma_f32_16x16x32_bf16 v[96:99], v[142:145], v[194:197], v[96:99]
	v_mfma_f32_16x16x32_bf16 v[92:95], v[150:153], v[194:197], v[92:95]
	v_mfma_f32_16x16x32_bf16 v[80:83], v[142:145], v[202:205], v[80:83]
	v_mfma_f32_16x16x32_bf16 v[76:79], v[150:153], v[202:205], v[76:79]
	v_mfma_f32_16x16x32_bf16 v[128:131], v[146:149], v[182:185], v[128:131]
	v_mfma_f32_16x16x32_bf16 v[124:127], v[154:157], v[182:185], v[124:127]
	v_mfma_f32_16x16x32_bf16 v[112:115], v[146:149], v[190:193], v[112:115]
	v_mfma_f32_16x16x32_bf16 v[108:111], v[154:157], v[190:193], v[108:111]
	v_mfma_f32_16x16x32_bf16 v[96:99], v[146:149], v[198:201], v[96:99]
	v_mfma_f32_16x16x32_bf16 v[92:95], v[154:157], v[198:201], v[92:95]
	v_mfma_f32_16x16x32_bf16 v[80:83], v[146:149], v[230:233], v[80:83]
	v_mfma_f32_16x16x32_bf16 v[76:79], v[154:157], v[230:233], v[76:79]
	v_mfma_f32_16x16x32_bf16 v[120:123], v[158:161], v[178:181], v[120:123]
	v_mfma_f32_16x16x32_bf16 v[116:119], v[170:173], v[178:181], v[116:119]
	v_mfma_f32_16x16x32_bf16 v[104:107], v[158:161], v[186:189], v[104:107]
	v_mfma_f32_16x16x32_bf16 v[100:103], v[170:173], v[186:189], v[100:103]
	v_mfma_f32_16x16x32_bf16 v[88:91], v[158:161], v[194:197], v[88:91]
	v_mfma_f32_16x16x32_bf16 v[84:87], v[170:173], v[194:197], v[84:87]
	v_mfma_f32_16x16x32_bf16 v[72:75], v[158:161], v[202:205], v[72:75]
	v_mfma_f32_16x16x32_bf16 v[68:71], v[170:173], v[202:205], v[68:71]
	v_mfma_f32_16x16x32_bf16 v[120:123], v[162:165], v[182:185], v[120:123]
	v_mfma_f32_16x16x32_bf16 v[116:119], v[174:177], v[182:185], v[116:119]
	v_mfma_f32_16x16x32_bf16 v[104:107], v[162:165], v[190:193], v[104:107]
	v_mfma_f32_16x16x32_bf16 v[100:103], v[174:177], v[190:193], v[100:103]
	v_mfma_f32_16x16x32_bf16 v[88:91], v[162:165], v[198:201], v[88:91]
	v_mfma_f32_16x16x32_bf16 v[84:87], v[174:177], v[198:201], v[84:87]
	v_mfma_f32_16x16x32_bf16 v[72:75], v[162:165], v[230:233], v[72:75]
	v_mfma_f32_16x16x32_bf16 v[68:71], v[174:177], v[230:233], v[68:71]
	s_barrier
	s_add_i32 s57, s57, s46
	v_lshl_add_u64 v[222:223], s[36:37], 0, v[132:133]
	s_mov_b32 m0, s57
	ds_read_b128 v[178:181], v169 offset:16384
	ds_read_b128 v[182:185], v169 offset:17408
	ds_read_b128 v[186:189], v169 offset:18432
	ds_read_b128 v[190:193], v169 offset:19456
	ds_read_b128 v[194:197], v169 offset:20480
	ds_read_b128 v[198:201], v169 offset:21504
	ds_read_b128 v[202:205], v169 offset:22528
	ds_read_b128 v[230:233], v169 offset:23552
	global_load_lds_dwordx4 v[222:223], off
	s_add_i32 m0, s57, 0x2000
	s_add_u32 s58, s36, 0x40000
	v_lshl_add_u64 v[234:235], s[36:37], 0, v[136:137]
	s_addc_u32 s59, s37, 0
	s_add_i32 s57, s60, s46
	global_load_lds_dwordx4 v[234:235], off
	v_lshl_add_u64 v[236:237], s[58:59], 0, v[132:133]
	s_mov_b32 m0, s57
	v_lshl_add_u64 v[238:239], s[40:41], 0, v[134:135]
	global_load_lds_dwordx4 v[236:237], off
	v_lshl_add_u64 v[236:237], s[58:59], 0, v[136:137]
	s_add_i32 m0, s57, 0x2000
	s_nop 0
	global_load_lds_dwordx4 v[236:237], off
	v_lshl_add_u64 v[236:237], s[40:41], 0, v[0:1]
	s_mov_b32 m0, s21
	s_nop 0
	global_load_lds_dwordx4 v[236:237], off
	s_mov_b32 m0, s47
	s_nop 0
	global_load_lds_dwordx4 v[238:239], off
	s_waitcnt vmcnt(8)
	s_waitcnt lgkmcnt(0)
	s_barrier
; #define PG8_STAGE(bufoff, gbase, voff) do { _Pragma("unroll") for (int _i = 0; _i < 2; ++_i) \
;         __builtin_amdgcn_global_load_lds((const unsigned*)((const char*)(gbase) + (voff)[_i]), (PG8_LAS unsigned*)(lds + (bufoff) + ldsw + _i * 8192), 16, 0, 0); } while (0)
; #define PG8_LDA(dst, b, h) do { _Pragma("unroll") for (int m = 0; m < 4; ++m) _Pragma("unroll") for (int k = 0; k < 2; ++k) dst[m][k] = *(const PG8_LAS bf16x8*)(lds + PG8_SA(b, h) + aoff + m * 2048 + k * 1024); } while (0)
; #define PG8_LDB(dst, b, h) do { _Pragma("unroll") for (int n = 0; n < 2; ++n) _Pragma("unroll") for (int k = 0; k < 2; ++k) dst[n][k] = *(const PG8_LAS bf16x8*)(lds + PG8_SB(b, h) + boff + n * 2048 + k * 1024); } while (0)
; #define PG8_MMA(ai, bj, At, Bt) do { __builtin_amdgcn_s_setprio(1); _Pragma("unroll") for (int m = 0; m < 4; ++m) _Pragma("unroll") for (int n = 0; n < 2; ++n) _Pragma("unroll") for (int k = 0; k < 2; ++k) \
;         acc[ai][bj][m][n] = __builtin_amdgcn_mfma_f32_16x16x32_bf16(Bt[n][k], At[m][k], acc[ai][bj][m][n], 0, 0, 0); __builtin_amdgcn_s_setprio(0); } while (0)
; #define PG8_WAIT_V(n) asm volatile("s_waitcnt vmcnt(" #n ")" ::: "memory")
; #define PG8_WAIT_L(n) asm volatile("s_waitcnt lgkmcnt(" #n ")" ::: "memory")
; #define PG8_BAR __builtin_amdgcn_s_barrier()
; #define PG8_SCHED __builtin_amdgcn_sched_barrier(0)
; template <class Epi, class Sched, bool APERM>
; __device__ __forceinline__ void gemm_phase(PG8_LAS unsigned char* lds, const Gemm g, const Sched& S, const Epi& E) {
;     ...
;             PG8_WAIT_V(8); PG8_WAIT_L(0); PG8_BAR; PG8_MMA(1, 0, At, B0); PG8_MMA(1, 1, At, B1); PG8_BAR; PG8_SCHED;
;             PG8_LDB(B0, 1, 0); PG8_LDB(B1, 1, 1); PG8_SCHED; PG8_LDA(At, 1, 0); PG8_STAGE(PG8_SA(0, 1), a2 + hstepA, voffA);
;             PG8_WAIT_V(8); PG8_WAIT_L(0); PG8_BAR; PG8_MMA(0, 0, At, B0); PG8_MMA(0, 1, At, B1); PG8_BAR; PG8_SCHED;
	s_waitcnt lgkmcnt(0)
	v_mfma_f32_16x16x32_bf16 v[64:67], v[142:145], v[178:181], v[64:67]
	v_mfma_f32_16x16x32_bf16 v[60:63], v[150:153], v[178:181], v[60:63]
	v_mfma_f32_16x16x32_bf16 v[48:51], v[142:145], v[186:189], v[48:51]
	v_mfma_f32_16x16x32_bf16 v[44:47], v[150:153], v[186:189], v[44:47]
	v_mfma_f32_16x16x32_bf16 v[32:35], v[142:145], v[194:197], v[32:35]
	v_mfma_f32_16x16x32_bf16 v[28:31], v[150:153], v[194:197], v[28:31]
	v_mfma_f32_16x16x32_bf16 v[16:19], v[142:145], v[202:205], v[16:19]
	v_mfma_f32_16x16x32_bf16 v[12:15], v[150:153], v[202:205], v[12:15]
	v_mfma_f32_16x16x32_bf16 v[64:67], v[146:149], v[182:185], v[64:67]
	v_mfma_f32_16x16x32_bf16 v[60:63], v[154:157], v[182:185], v[60:63]
	v_mfma_f32_16x16x32_bf16 v[48:51], v[146:149], v[190:193], v[48:51]
	v_mfma_f32_16x16x32_bf16 v[44:47], v[154:157], v[190:193], v[44:47]
	v_mfma_f32_16x16x32_bf16 v[32:35], v[146:149], v[198:201], v[32:35]
	v_mfma_f32_16x16x32_bf16 v[28:31], v[154:157], v[198:201], v[28:31]
	v_mfma_f32_16x16x32_bf16 v[16:19], v[146:149], v[230:233], v[16:19]
	v_mfma_f32_16x16x32_bf16 v[12:15], v[154:157], v[230:233], v[12:15]
	v_mfma_f32_16x16x32_bf16 v[56:59], v[158:161], v[178:181], v[56:59]
	v_mfma_f32_16x16x32_bf16 v[52:55], v[170:173], v[178:181], v[52:55]
	v_mfma_f32_16x16x32_bf16 v[40:43], v[158:161], v[186:189], v[40:43]
	v_mfma_f32_16x16x32_bf16 v[36:39], v[170:173], v[186:189], v[36:39]
	v_mfma_f32_16x16x32_bf16 v[24:27], v[158:161], v[194:197], v[24:27]
	v_mfma_f32_16x16x32_bf16 v[20:23], v[170:173], v[194:197], v[20:23]
	v_mfma_f32_16x16x32_bf16 v[8:11], v[158:161], v[202:205], v[8:11]
	v_mfma_f32_16x16x32_bf16 v[4:7], v[170:173], v[202:205], v[4:7]
	v_mfma_f32_16x16x32_bf16 v[56:59], v[162:165], v[182:185], v[56:59]
	v_mfma_f32_16x16x32_bf16 v[52:55], v[174:177], v[182:185], v[52:55]
	v_mfma_f32_16x16x32_bf16 v[40:43], v[162:165], v[190:193], v[40:43]
	v_mfma_f32_16x16x32_bf16 v[36:39], v[174:177], v[190:193], v[36:39]
	v_mfma_f32_16x16x32_bf16 v[24:27], v[162:165], v[198:201], v[24:27]
	v_mfma_f32_16x16x32_bf16 v[20:23], v[174:177], v[198:201], v[20:23]
	v_mfma_f32_16x16x32_bf16 v[8:11], v[162:165], v[230:233], v[8:11]
	v_mfma_f32_16x16x32_bf16 v[4:7], v[174:177], v[230:233], v[4:7]
	s_barrier
	s_add_i32 s57, 0, 0x18000
	v_add_u32_e32 v2, s57, v167
	s_add_i32 s58, 0, 0x1c000
	ds_read_b128 v[142:145], v2
	ds_read_b128 v[146:149], v2 offset:1024
	ds_read_b128 v[150:153], v2 offset:2048
	ds_read_b128 v[154:157], v2 offset:3072
	v_add_u32_e32 v2, s58, v167
	ds_read_b128 v[158:161], v2
	ds_read_b128 v[162:165], v2 offset:1024
	ds_read_b128 v[170:173], v2 offset:2048
	ds_read_b128 v[174:177], v2 offset:3072
	s_add_u32 s40, s40, 0x40000
	s_addc_u32 s41, s41, 0
	s_mov_b32 m0, s50
	v_lshl_add_u64 v[240:241], s[40:41], 0, v[0:1]
	ds_read_b128 v[178:181], v169 offset:32768
	ds_read_b128 v[182:185], v169 offset:33792
	ds_read_b128 v[186:189], v169 offset:34816
	ds_read_b128 v[190:193], v169 offset:35840
	ds_read_b128 v[194:197], v169 offset:36864
	ds_read_b128 v[198:201], v169 offset:37888
	ds_read_b128 v[202:205], v169 offset:38912
	ds_read_b128 v[230:233], v169 offset:39936
	global_load_lds_dwordx4 v[240:241], off
	v_lshl_add_u64 v[240:241], s[40:41], 0, v[134:135]
	s_mov_b32 m0, s51
	s_nop 0
	global_load_lds_dwordx4 v[240:241], off
	s_waitcnt vmcnt(8)
	s_waitcnt lgkmcnt(0)
	s_barrier
	s_waitcnt lgkmcnt(0)
	v_mfma_f32_16x16x32_bf16 v[128:131], v[142:145], v[178:181], v[128:131]
	v_mfma_f32_16x16x32_bf16 v[124:127], v[150:153], v[178:181], v[124:127]
	v_mfma_f32_16x16x32_bf16 v[112:115], v[142:145], v[186:189], v[112:115]
	v_mfma_f32_16x16x32_bf16 v[108:111], v[150:153], v[186:189], v[108:111]
	v_mfma_f32_16x16x32_bf16 v[96:99], v[142:145], v[194:197], v[96:99]
	v_mfma_f32_16x16x32_bf16 v[92:95], v[150:153], v[194:197], v[92:95]
	v_mfma_f32_16x16x32_bf16 v[80:83], v[142:145], v[202:205], v[80:83]
	v_mfma_f32_16x16x32_bf16 v[76:79], v[150:153], v[202:205], v[76:79]
	v_mfma_f32_16x16x32_bf16 v[128:131], v[146:149], v[182:185], v[128:131]
	v_mfma_f32_16x16x32_bf16 v[124:127], v[154:157], v[182:185], v[124:127]
	v_mfma_f32_16x16x32_bf16 v[112:115], v[146:149], v[190:193], v[112:115]
	v_mfma_f32_16x16x32_bf16 v[108:111], v[154:157], v[190:193], v[108:111]
	v_mfma_f32_16x16x32_bf16 v[96:99], v[146:149], v[198:201], v[96:99]
	v_mfma_f32_16x16x32_bf16 v[92:95], v[154:157], v[198:201], v[92:95]
	v_mfma_f32_16x16x32_bf16 v[80:83], v[146:149], v[230:233], v[80:83]
	v_mfma_f32_16x16x32_bf16 v[76:79], v[154:157], v[230:233], v[76:79]
	v_mfma_f32_16x16x32_bf16 v[120:123], v[158:161], v[178:181], v[120:123]
	v_mfma_f32_16x16x32_bf16 v[116:119], v[170:173], v[178:181], v[116:119]
	v_mfma_f32_16x16x32_bf16 v[104:107], v[158:161], v[186:189], v[104:107]
	v_mfma_f32_16x16x32_bf16 v[100:103], v[170:173], v[186:189], v[100:103]
	v_mfma_f32_16x16x32_bf16 v[88:91], v[158:161], v[194:197], v[88:91]
	v_mfma_f32_16x16x32_bf16 v[84:87], v[170:173], v[194:197], v[84:87]
	v_mfma_f32_16x16x32_bf16 v[72:75], v[158:161], v[202:205], v[72:75]
	v_mfma_f32_16x16x32_bf16 v[68:71], v[170:173], v[202:205], v[68:71]
	v_mfma_f32_16x16x32_bf16 v[120:123], v[162:165], v[182:185], v[120:123]
	v_mfma_f32_16x16x32_bf16 v[116:119], v[174:177], v[182:185], v[116:119]
	v_mfma_f32_16x16x32_bf16 v[104:107], v[162:165], v[190:193], v[104:107]
	v_mfma_f32_16x16x32_bf16 v[100:103], v[174:177], v[190:193], v[100:103]
	v_mfma_f32_16x16x32_bf16 v[88:91], v[162:165], v[198:201], v[88:91]
	v_mfma_f32_16x16x32_bf16 v[84:87], v[174:177], v[198:201], v[84:87]
	v_mfma_f32_16x16x32_bf16 v[72:75], v[162:165], v[230:233], v[72:75]
	v_mfma_f32_16x16x32_bf16 v[68:71], v[174:177], v[230:233], v[68:71]
	s_barrier
; #define PG8_STAGE(bufoff, gbase, voff) do { _Pragma("unroll") for (int _i = 0; _i < 2; ++_i) \
;         __builtin_amdgcn_global_load_lds((const unsigned*)((const char*)(gbase) + (voff)[_i]), (PG8_LAS unsigned*)(lds + (bufoff) + ldsw + _i * 8192), 16, 0, 0); } while (0)
; #define PG8_LDA(dst, b, h) do { _Pragma("unroll") for (int m = 0; m < 4; ++m) _Pragma("unroll") for (int k = 0; k < 2; ++k) dst[m][k] = *(const PG8_LAS bf16x8*)(lds + PG8_SA(b, h) + aoff + m * 2048 + k * 1024); } while (0)
; #define PG8_MMA(ai, bj, At, Bt) do { __builtin_amdgcn_s_setprio(1); _Pragma("unroll") for (int m = 0; m < 4; ++m) _Pragma("unroll") for (int n = 0; n < 2; ++n) _Pragma("unroll") for (int k = 0; k < 2; ++k) \
;         acc[ai][bj][m][n] = __builtin_amdgcn_mfma_f32_16x16x32_bf16(Bt[n][k], At[m][k], acc[ai][bj][m][n], 0, 0, 0); __builtin_amdgcn_s_setprio(0); } while (0)
; #define PG8_WAIT_V(n) asm volatile("s_waitcnt vmcnt(" #n ")" ::: "memory")
; #define PG8_WAIT_L(n) asm volatile("s_waitcnt lgkmcnt(" #n ")" ::: "memory")
; #define PG8_BAR __builtin_amdgcn_s_barrier()
; #define PG8_SCHED __builtin_amdgcn_sched_barrier(0)
; template <class Epi, class Sched, bool APERM>
; __device__ __forceinline__ void gemm_phase(PG8_LAS unsigned char* lds, const Gemm g, const Sched& S, const Epi& E) {
;     ...
;             PG8_LDA(At, 1, 1); PG8_STAGE(PG8_SB(1, 0), b3, voffB); PG8_STAGE(PG8_SB(1, 1), b3 + hstep, voffB); PG8_STAGE(PG8_SA(1, 0), a3, voffA);
;             PG8_WAIT_V(8); PG8_WAIT_L(0); PG8_BAR; PG8_MMA(1, 0, At, B0); PG8_MMA(1, 1, At, B1); PG8_BAR; PG8_SCHED;
;         }
;         if (wr == 0) PG8_BAR;
	s_add_i32 s40, s57, s46
	v_lshl_add_u64 v[222:223], v[222:223], 0, s[52:53]
	s_mov_b32 m0, s40
	ds_read_b128 v[178:181], v169 offset:49152
	ds_read_b128 v[182:185], v169 offset:50176
	ds_read_b128 v[186:189], v169 offset:51200
	ds_read_b128 v[190:193], v169 offset:52224
	ds_read_b128 v[194:197], v169 offset:53248
	ds_read_b128 v[198:201], v169 offset:54272
	ds_read_b128 v[202:205], v169 offset:55296
	ds_read_b128 v[230:233], v169 offset:56320
	global_load_lds_dwordx4 v[222:223], off
	s_add_i32 m0, s40, 0x2000
	s_add_u32 s36, s36, 0x40080
	v_lshl_add_u64 v[222:223], v[234:235], 0, s[52:53]
	s_addc_u32 s37, s37, 0
	s_add_i32 s40, s58, s46
	global_load_lds_dwordx4 v[222:223], off
	v_lshl_add_u64 v[222:223], s[36:37], 0, v[132:133]
	s_mov_b32 m0, s40
	s_nop 0
	global_load_lds_dwordx4 v[222:223], off
	v_lshl_add_u64 v[222:223], s[36:37], 0, v[136:137]
	s_add_i32 m0, s40, 0x2000
	s_nop 0
	global_load_lds_dwordx4 v[222:223], off
	v_lshl_add_u64 v[222:223], v[236:237], 0, s[52:53]
	s_mov_b32 m0, s55
	s_nop 0
	global_load_lds_dwordx4 v[222:223], off
	v_lshl_add_u64 v[222:223], v[238:239], 0, s[52:53]
	s_mov_b32 m0, s72
	s_nop 0
	global_load_lds_dwordx4 v[222:223], off
	s_waitcnt vmcnt(8)
	s_waitcnt lgkmcnt(0)
	s_barrier
	s_waitcnt lgkmcnt(0)
	v_mfma_f32_16x16x32_bf16 v[64:67], v[142:145], v[178:181], v[64:67]
	v_mfma_f32_16x16x32_bf16 v[60:63], v[150:153], v[178:181], v[60:63]
	v_mfma_f32_16x16x32_bf16 v[48:51], v[142:145], v[186:189], v[48:51]
	v_mfma_f32_16x16x32_bf16 v[44:47], v[150:153], v[186:189], v[44:47]
	v_mfma_f32_16x16x32_bf16 v[32:35], v[142:145], v[194:197], v[32:35]
	v_mfma_f32_16x16x32_bf16 v[28:31], v[150:153], v[194:197], v[28:31]
	v_mfma_f32_16x16x32_bf16 v[16:19], v[142:145], v[202:205], v[16:19]
	v_mfma_f32_16x16x32_bf16 v[12:15], v[150:153], v[202:205], v[12:15]
	v_mfma_f32_16x16x32_bf16 v[64:67], v[146:149], v[182:185], v[64:67]
	v_mfma_f32_16x16x32_bf16 v[60:63], v[154:157], v[182:185], v[60:63]
	v_mfma_f32_16x16x32_bf16 v[48:51], v[146:149], v[190:193], v[48:51]
	v_mfma_f32_16x16x32_bf16 v[44:47], v[154:157], v[190:193], v[44:47]
	v_mfma_f32_16x16x32_bf16 v[32:35], v[146:149], v[198:201], v[32:35]
	v_mfma_f32_16x16x32_bf16 v[28:31], v[154:157], v[198:201], v[28:31]
	v_mfma_f32_16x16x32_bf16 v[16:19], v[146:149], v[230:233], v[16:19]
	v_mfma_f32_16x16x32_bf16 v[12:15], v[154:157], v[230:233], v[12:15]
	v_mfma_f32_16x16x32_bf16 v[56:59], v[158:161], v[178:181], v[56:59]
	v_mfma_f32_16x16x32_bf16 v[52:55], v[170:173], v[178:181], v[52:55]
	v_mfma_f32_16x16x32_bf16 v[40:43], v[158:161], v[186:189], v[40:43]
	v_mfma_f32_16x16x32_bf16 v[36:39], v[170:173], v[186:189], v[36:39]
	v_mfma_f32_16x16x32_bf16 v[24:27], v[158:161], v[194:197], v[24:27]
	v_mfma_f32_16x16x32_bf16 v[20:23], v[170:173], v[194:197], v[20:23]
	v_mfma_f32_16x16x32_bf16 v[8:11], v[158:161], v[202:205], v[8:11]
	v_mfma_f32_16x16x32_bf16 v[4:7], v[170:173], v[202:205], v[4:7]
	v_mfma_f32_16x16x32_bf16 v[56:59], v[162:165], v[182:185], v[56:59]
	v_mfma_f32_16x16x32_bf16 v[52:55], v[174:177], v[182:185], v[52:55]
	v_mfma_f32_16x16x32_bf16 v[40:43], v[162:165], v[190:193], v[40:43]
	v_mfma_f32_16x16x32_bf16 v[36:39], v[174:177], v[190:193], v[36:39]
	v_mfma_f32_16x16x32_bf16 v[24:27], v[162:165], v[198:201], v[24:27]
	v_mfma_f32_16x16x32_bf16 v[20:23], v[174:177], v[198:201], v[20:23]
	v_mfma_f32_16x16x32_bf16 v[8:11], v[162:165], v[230:233], v[8:11]
	v_mfma_f32_16x16x32_bf16 v[4:7], v[174:177], v[230:233], v[4:7]
	s_barrier
	s_add_i32 s56, s56, 2
	s_add_u32 s34, s34, 0x100
	s_addc_u32 s35, s35, 0
	s_add_u32 s45, s45, 0x100
	s_addc_u32 s49, s49, 0
	s_cmp_gt_u32 s56, 13
	s_cbranch_scc0 .LBB0_1312
	s_and_b64 vcc, exec, s[18:19]
	s_cbranch_vccz .LBB0_1315
	s_barrier
